# GEMM K loops: s_setprio 1 from the k-tile barrier to the 14th MFMA, 0 for the last two MFMAs and LDS stores
# baseline (speedup 1.0000x reference)
; template <class Epi, class ColV>
; DI void gemm_tile(const bf16_t* __restrict__ A, int lda, const bf16_t* __restrict__ Bt, int ldb, int K, int m0, int n0, unsigned char* smem, Epi epi, ColV colv, const bf16_t* __restrict__ HYT = nullptr) {
;     ...
;     auto step = [&](int kt, u32x4 (&ldset)[8], const u32x4 (&stset)[8]) {
;         const int buf = kt & 1;
;         if (kt + 2 < nk) gload(ldset, kt + 2);
;         const bf16_t* Ab = As + (buf * 128 + 64 * wr + li) * LS + 8 * lh;
;         const bf16_t* Bb = Bs + (buf * 128 + 64 * wc + li) * LS + 8 * lh;
;         bf16x8 fa[2][2], fb[2][2], ga[2][2], gb[2][2];
; #pragma unroll
;         for (int k2 = 0; k2 < 2; ++k2) { fa[k2][0] = ld8(Ab + 16 * k2); fa[k2][1] = ld8(Ab + 32 * LS + 16 * k2); fb[k2][0] = ld8(Bb + 16 * k2); fb[k2][1] = ld8(Bb + 32 * LS + 16 * k2); }
;         __builtin_amdgcn_sched_barrier(0);
; #pragma unroll
;         for (int k2 = 0; k2 < 2; ++k2) {
;             acc[0][0] = MFMA(fa[k2][0], fb[k2][0], acc[0][0]); acc[0][1] = MFMA(fa[k2][0], fb[k2][1], acc[0][1]);
;             acc[1][0] = MFMA(fa[k2][1], fb[k2][0], acc[1][0]); acc[1][1] = MFMA(fa[k2][1], fb[k2][1], acc[1][1]);
;         }
; #pragma unroll
;         for (int k2 = 0; k2 < 2; ++k2) { const int ks = 2 + k2; ga[k2][0] = ld8(Ab + 16 * ks); ga[k2][1] = ld8(Ab + 32 * LS + 16 * ks); gb[k2][0] = ld8(Bb + 16 * ks); gb[k2][1] = ld8(Bb + 32 * LS + 16 * ks); }
; #pragma unroll
;         for (int k2 = 0; k2 < 2; ++k2) {
;             acc[0][0] = MFMA(ga[k2][0], gb[k2][0], acc[0][0]); acc[0][1] = MFMA(ga[k2][0], gb[k2][1], acc[0][1]);
;             acc[1][0] = MFMA(ga[k2][1], gb[k2][0], acc[1][0]); acc[1][1] = MFMA(ga[k2][1], gb[k2][1], acc[1][1]);
;         }
;         if (kt + 1 < nk) sstore(stset, buf ^ 1, kt + 1);
; #pragma unroll
;         for (int i = 0; i < 8; ++i) { __builtin_amdgcn_sched_group_barrier(0x008, 1, 0); __builtin_amdgcn_sched_group_barrier(0x100, 1, 0); }
; #pragma unroll
;         for (int i = 0; i < 8; ++i) { __builtin_amdgcn_sched_group_barrier(0x008, 1, 0); __builtin_amdgcn_sched_group_barrier(0x200, 1, 0); }
;         __builtin_amdgcn_sched_barrier(0);
;         __syncthreads();
;     };
;     ...
;     case 11: {
;         float* out = p.out; float* XC = (float*)(p.ws + WS_XC);
;         auto gate = [&](int m0_, int c) { return MOD[(m0_ < NL ? (m0_ >> 12) : 4) * 6144 + 5120 + c]; };
.Lg3_phase11:
	ds_read_b128 v[174:177], v194
	ds_read_b128 v[210:213], v195 offset:36864
	ds_read_b128 v[218:221], v195 offset:41472
	ds_read_b128 v[202:205], v194 offset:4608
	ds_read_b128 v[178:181], v194 offset:32
	ds_read_b128 v[222:225], v195 offset:41504
	ds_read_b128 v[206:209], v194 offset:4640
	ds_read_b128 v[214:217], v195 offset:36896
	s_waitcnt lgkmcnt(6)
	v_mfma_f32_32x32x16_bf16 v[52:67], v[174:177], v[210:213], v[52:67]
	global_load_dwordx4 v[68:71], v[164:165], off offset:384
	s_waitcnt lgkmcnt(5)
	v_mfma_f32_32x32x16_bf16 v[36:51], v[174:177], v[218:221], v[36:51]
	global_load_dwordx4 v[72:75], v[162:163], off offset:384
	s_waitcnt lgkmcnt(4)
	v_mfma_f32_32x32x16_bf16 v[4:19], v[202:205], v[218:221], v[4:19]
	global_load_dwordx4 v[76:79], v[160:161], off offset:384
	s_waitcnt lgkmcnt(2)
	v_mfma_f32_32x32x16_bf16 v[36:51], v[178:181], v[222:225], v[36:51]
	global_load_dwordx4 v[80:83], v[158:159], off offset:384
	s_waitcnt lgkmcnt(1)
	v_mfma_f32_32x32x16_bf16 v[4:19], v[206:209], v[222:225], v[4:19]
	global_load_dwordx4 v[84:87], v[156:157], off offset:384
	ds_read_b128 v[222:225], v195 offset:41568
	ds_read_b128 v[174:177], v194 offset:4672
	v_mfma_f32_32x32x16_bf16 v[20:35], v[202:205], v[210:213], v[20:35]
	global_load_dwordx4 v[92:95], v[154:155], off offset:384
	ds_read_b128 v[210:213], v194 offset:4704
	ds_read_b128 v[202:205], v194 offset:64
	s_waitcnt lgkmcnt(4)
	v_mfma_f32_32x32x16_bf16 v[52:67], v[178:181], v[214:217], v[52:67]
	global_load_dwordx4 v[104:107], v[152:153], off offset:384
	ds_read_b128 v[218:221], v195 offset:36960
	ds_read_b128 v[178:181], v195 offset:41536
	v_mfma_f32_32x32x16_bf16 v[20:35], v[206:209], v[214:217], v[20:35]
	global_load_dwordx4 v[112:115], v[146:147], off offset:384
	ds_read_b128 v[214:217], v195 offset:36928
	ds_read_b128 v[206:209], v194 offset:96
	s_waitcnt lgkmcnt(1)
	v_mfma_f32_32x32x16_bf16 v[52:67], v[202:205], v[214:217], v[52:67]
	s_waitcnt vmcnt(23)
	ds_write_b128 v190, v[88:91] offset:18432
	v_mfma_f32_32x32x16_bf16 v[36:51], v[202:205], v[178:181], v[36:51]
	s_waitcnt vmcnt(22)
	ds_write_b128 v190, v[96:99] offset:55296
	v_mfma_f32_32x32x16_bf16 v[20:35], v[174:177], v[214:217], v[20:35]
	s_waitcnt vmcnt(21)
	ds_write_b128 v191, v[100:103] offset:18432
	v_mfma_f32_32x32x16_bf16 v[4:19], v[174:177], v[178:181], v[4:19]
	s_waitcnt vmcnt(20)
	ds_write_b128 v191, v[108:111] offset:55296
	s_waitcnt lgkmcnt(4)
	v_mfma_f32_32x32x16_bf16 v[52:67], v[206:209], v[218:221], v[52:67]
	s_waitcnt vmcnt(19)
	ds_write_b128 v192, v[116:119] offset:18432
	v_mfma_f32_32x32x16_bf16 v[36:51], v[206:209], v[222:225], v[36:51]
	s_setprio 0
	s_waitcnt vmcnt(18)
	ds_write_b128 v192, v[120:123] offset:55296
	v_mfma_f32_32x32x16_bf16 v[20:35], v[210:213], v[218:221], v[20:35]
	s_waitcnt vmcnt(17)
	ds_write_b128 v193, v[124:127] offset:18432
	v_mfma_f32_32x32x16_bf16 v[4:19], v[210:213], v[222:225], v[4:19]
	s_waitcnt vmcnt(16)
	ds_write_b128 v193, v[128:131] offset:55296
	s_waitcnt lgkmcnt(0)
	s_barrier
	s_setprio 1
	ds_read_b128 v[174:177], v196
	ds_read_b128 v[210:213], v197 offset:36864
	ds_read_b128 v[218:221], v197 offset:41472
	ds_read_b128 v[202:205], v196 offset:4608
	ds_read_b128 v[178:181], v196 offset:32
	ds_read_b128 v[222:225], v197 offset:41504
	ds_read_b128 v[206:209], v196 offset:4640
	ds_read_b128 v[214:217], v197 offset:36896
	s_waitcnt lgkmcnt(6)
	v_mfma_f32_32x32x16_bf16 v[52:67], v[174:177], v[210:213], v[52:67]
	global_load_dwordx4 v[88:91], v[164:165], off offset:512
	s_waitcnt lgkmcnt(5)
	v_mfma_f32_32x32x16_bf16 v[36:51], v[174:177], v[218:221], v[36:51]
	global_load_dwordx4 v[96:99], v[162:163], off offset:512
	s_waitcnt lgkmcnt(4)
	v_mfma_f32_32x32x16_bf16 v[4:19], v[202:205], v[218:221], v[4:19]
	global_load_dwordx4 v[100:103], v[160:161], off offset:512
	s_waitcnt lgkmcnt(2)
	v_mfma_f32_32x32x16_bf16 v[36:51], v[178:181], v[222:225], v[36:51]
	global_load_dwordx4 v[108:111], v[158:159], off offset:512
	s_waitcnt lgkmcnt(1)
	v_mfma_f32_32x32x16_bf16 v[4:19], v[206:209], v[222:225], v[4:19]
	global_load_dwordx4 v[116:119], v[156:157], off offset:512
	ds_read_b128 v[222:225], v197 offset:41568
	ds_read_b128 v[174:177], v196 offset:4672
	v_mfma_f32_32x32x16_bf16 v[20:35], v[202:205], v[210:213], v[20:35]
	global_load_dwordx4 v[120:123], v[154:155], off offset:512
	ds_read_b128 v[210:213], v196 offset:4704
	ds_read_b128 v[202:205], v196 offset:64
	s_waitcnt lgkmcnt(4)
	v_mfma_f32_32x32x16_bf16 v[52:67], v[178:181], v[214:217], v[52:67]
	global_load_dwordx4 v[124:127], v[152:153], off offset:512
	ds_read_b128 v[218:221], v197 offset:36960
	ds_read_b128 v[178:181], v197 offset:41536
	v_mfma_f32_32x32x16_bf16 v[20:35], v[206:209], v[214:217], v[20:35]
	global_load_dwordx4 v[128:131], v[146:147], off offset:512
	ds_read_b128 v[214:217], v197 offset:36928
	ds_read_b128 v[206:209], v196 offset:96
	s_waitcnt lgkmcnt(1)
	v_mfma_f32_32x32x16_bf16 v[52:67], v[202:205], v[214:217], v[52:67]
	s_waitcnt vmcnt(23)
	ds_write_b128 v190, v[132:135]
	v_mfma_f32_32x32x16_bf16 v[36:51], v[202:205], v[178:181], v[36:51]
	s_waitcnt vmcnt(22)
	ds_write_b128 v190, v[136:139] offset:36864
	v_mfma_f32_32x32x16_bf16 v[20:35], v[174:177], v[214:217], v[20:35]
	s_waitcnt vmcnt(21)
	ds_write_b128 v191, v[140:143]
	v_mfma_f32_32x32x16_bf16 v[4:19], v[174:177], v[178:181], v[4:19]
	s_waitcnt vmcnt(20)
	ds_write_b128 v191, v[198:201] offset:36864
	s_waitcnt lgkmcnt(4)
	v_mfma_f32_32x32x16_bf16 v[52:67], v[206:209], v[218:221], v[52:67]
	s_waitcnt vmcnt(19)
	ds_write_b128 v192, v[226:229]
	v_mfma_f32_32x32x16_bf16 v[36:51], v[206:209], v[222:225], v[36:51]
	s_setprio 0
	s_waitcnt vmcnt(18)
	ds_write_b128 v192, v[230:233] offset:36864
	v_mfma_f32_32x32x16_bf16 v[20:35], v[210:213], v[218:221], v[20:35]
	s_waitcnt vmcnt(17)
	ds_write_b128 v193, v[242:245]
	v_mfma_f32_32x32x16_bf16 v[4:19], v[210:213], v[222:225], v[4:19]
	s_waitcnt vmcnt(16)
	ds_write_b128 v193, v[246:249] offset:36864
	s_waitcnt lgkmcnt(0)
	s_barrier
; template <class Epi, class ColV>
; DI void gemm_tile(const bf16_t* __restrict__ A, int lda, const bf16_t* __restrict__ Bt, int ldb, int K, int m0, int n0, unsigned char* smem, Epi epi, ColV colv, const bf16_t* __restrict__ HYT = nullptr) {
;     ...
;     auto step = [&](int kt, u32x4 (&ldset)[8], const u32x4 (&stset)[8]) {
;         const int buf = kt & 1;
;         if (kt + 2 < nk) gload(ldset, kt + 2);
;         const bf16_t* Ab = As + (buf * 128 + 64 * wr + li) * LS + 8 * lh;
;         const bf16_t* Bb = Bs + (buf * 128 + 64 * wc + li) * LS + 8 * lh;
;         bf16x8 fa[2][2], fb[2][2], ga[2][2], gb[2][2];
; #pragma unroll
;         for (int k2 = 0; k2 < 2; ++k2) { fa[k2][0] = ld8(Ab + 16 * k2); fa[k2][1] = ld8(Ab + 32 * LS + 16 * k2); fb[k2][0] = ld8(Bb + 16 * k2); fb[k2][1] = ld8(Bb + 32 * LS + 16 * k2); }
;         __builtin_amdgcn_sched_barrier(0);
; #pragma unroll
;         for (int k2 = 0; k2 < 2; ++k2) {
;             acc[0][0] = MFMA(fa[k2][0], fb[k2][0], acc[0][0]); acc[0][1] = MFMA(fa[k2][0], fb[k2][1], acc[0][1]);
;             acc[1][0] = MFMA(fa[k2][1], fb[k2][0], acc[1][0]); acc[1][1] = MFMA(fa[k2][1], fb[k2][1], acc[1][1]);
;         }
; #pragma unroll
;         for (int k2 = 0; k2 < 2; ++k2) { const int ks = 2 + k2; ga[k2][0] = ld8(Ab + 16 * ks); ga[k2][1] = ld8(Ab + 32 * LS + 16 * ks); gb[k2][0] = ld8(Bb + 16 * ks); gb[k2][1] = ld8(Bb + 32 * LS + 16 * ks); }
; #pragma unroll
;         for (int k2 = 0; k2 < 2; ++k2) {
;             acc[0][0] = MFMA(ga[k2][0], gb[k2][0], acc[0][0]); acc[0][1] = MFMA(ga[k2][0], gb[k2][1], acc[0][1]);
;             acc[1][0] = MFMA(ga[k2][1], gb[k2][0], acc[1][0]); acc[1][1] = MFMA(ga[k2][1], gb[k2][1], acc[1][1]);
;         }
;         if (kt + 1 < nk) sstore(stset, buf ^ 1, kt + 1);
; #pragma unroll
;         for (int i = 0; i < 8; ++i) { __builtin_amdgcn_sched_group_barrier(0x008, 1, 0); __builtin_amdgcn_sched_group_barrier(0x100, 1, 0); }
; #pragma unroll
;         for (int i = 0; i < 8; ++i) { __builtin_amdgcn_sched_group_barrier(0x008, 1, 0); __builtin_amdgcn_sched_group_barrier(0x200, 1, 0); }
;         __builtin_amdgcn_sched_barrier(0);
;         __syncthreads();
;     };
;     ...
;         XCD_TILE_LOOP(NL / 128, 8, tm, tn) gemm_tile((const bf16_t*)(p.ws + WS_HID), 4096, (const bf16_t*)(p.ws + wbase(layer) + W_FF2), 4096, 4096, tm * 128, tn * 128, smem, epi, gate);
	s_setprio 1
	ds_read_b128 v[174:177], v194
	ds_read_b128 v[210:213], v195 offset:36864
	ds_read_b128 v[218:221], v195 offset:41472
	ds_read_b128 v[202:205], v194 offset:4608
	ds_read_b128 v[178:181], v194 offset:32
	ds_read_b128 v[222:225], v195 offset:41504
	ds_read_b128 v[206:209], v194 offset:4640
	ds_read_b128 v[214:217], v195 offset:36896
	s_waitcnt lgkmcnt(6)
	v_mfma_f32_32x32x16_bf16 v[52:67], v[174:177], v[210:213], v[52:67]
	global_load_dwordx4 v[132:135], v[164:165], off offset:640
	s_waitcnt lgkmcnt(5)
	v_mfma_f32_32x32x16_bf16 v[36:51], v[174:177], v[218:221], v[36:51]
	global_load_dwordx4 v[136:139], v[162:163], off offset:640
	s_waitcnt lgkmcnt(4)
	v_mfma_f32_32x32x16_bf16 v[4:19], v[202:205], v[218:221], v[4:19]
	global_load_dwordx4 v[140:143], v[160:161], off offset:640
	s_waitcnt lgkmcnt(2)
	v_mfma_f32_32x32x16_bf16 v[36:51], v[178:181], v[222:225], v[36:51]
	global_load_dwordx4 v[198:201], v[158:159], off offset:640
	s_waitcnt lgkmcnt(1)
	v_mfma_f32_32x32x16_bf16 v[4:19], v[206:209], v[222:225], v[4:19]
	global_load_dwordx4 v[226:229], v[156:157], off offset:640
	ds_read_b128 v[222:225], v195 offset:41568
	ds_read_b128 v[174:177], v194 offset:4672
	v_mfma_f32_32x32x16_bf16 v[20:35], v[202:205], v[210:213], v[20:35]
	global_load_dwordx4 v[230:233], v[154:155], off offset:640
	ds_read_b128 v[210:213], v194 offset:4704
	ds_read_b128 v[202:205], v194 offset:64
	s_waitcnt lgkmcnt(4)
	v_mfma_f32_32x32x16_bf16 v[52:67], v[178:181], v[214:217], v[52:67]
	global_load_dwordx4 v[242:245], v[152:153], off offset:640
	ds_read_b128 v[218:221], v195 offset:36960
	ds_read_b128 v[178:181], v195 offset:41536
	v_mfma_f32_32x32x16_bf16 v[20:35], v[206:209], v[214:217], v[20:35]
	global_load_dwordx4 v[246:249], v[146:147], off offset:640
	ds_read_b128 v[214:217], v195 offset:36928
	ds_read_b128 v[206:209], v194 offset:96
	s_waitcnt lgkmcnt(1)
	v_mfma_f32_32x32x16_bf16 v[52:67], v[202:205], v[214:217], v[52:67]
	s_waitcnt vmcnt(23)
	ds_write_b128 v190, v[68:71] offset:18432
	v_mfma_f32_32x32x16_bf16 v[36:51], v[202:205], v[178:181], v[36:51]
	s_waitcnt vmcnt(22)
	ds_write_b128 v190, v[72:75] offset:55296
	v_mfma_f32_32x32x16_bf16 v[20:35], v[174:177], v[214:217], v[20:35]
	s_waitcnt vmcnt(21)
	ds_write_b128 v191, v[76:79] offset:18432
	v_mfma_f32_32x32x16_bf16 v[4:19], v[174:177], v[178:181], v[4:19]
	s_waitcnt vmcnt(20)
	ds_write_b128 v191, v[80:83] offset:55296
	s_waitcnt lgkmcnt(4)
	v_mfma_f32_32x32x16_bf16 v[52:67], v[206:209], v[218:221], v[52:67]
	s_waitcnt vmcnt(19)
	ds_write_b128 v192, v[84:87] offset:18432
	v_mfma_f32_32x32x16_bf16 v[36:51], v[206:209], v[222:225], v[36:51]
	s_setprio 0
	s_waitcnt vmcnt(18)
	ds_write_b128 v192, v[92:95] offset:55296
	v_mfma_f32_32x32x16_bf16 v[20:35], v[210:213], v[218:221], v[20:35]
	s_waitcnt vmcnt(17)
	ds_write_b128 v193, v[104:107] offset:18432
	v_mfma_f32_32x32x16_bf16 v[4:19], v[210:213], v[222:225], v[4:19]
	s_waitcnt vmcnt(16)
	ds_write_b128 v193, v[112:115] offset:55296
	s_waitcnt lgkmcnt(0)
	s_barrier
	s_setprio 1
	ds_read_b128 v[174:177], v196
	ds_read_b128 v[210:213], v197 offset:36864
	ds_read_b128 v[218:221], v197 offset:41472
	ds_read_b128 v[202:205], v196 offset:4608
	ds_read_b128 v[178:181], v196 offset:32
	ds_read_b128 v[222:225], v197 offset:41504
	ds_read_b128 v[206:209], v196 offset:4640
	ds_read_b128 v[214:217], v197 offset:36896
	s_waitcnt lgkmcnt(6)
	v_mfma_f32_32x32x16_bf16 v[52:67], v[174:177], v[210:213], v[52:67]
	global_load_dwordx4 v[68:71], v[164:165], off offset:768
	s_waitcnt lgkmcnt(5)
	v_mfma_f32_32x32x16_bf16 v[36:51], v[174:177], v[218:221], v[36:51]
	global_load_dwordx4 v[72:75], v[162:163], off offset:768
	s_waitcnt lgkmcnt(4)
	v_mfma_f32_32x32x16_bf16 v[4:19], v[202:205], v[218:221], v[4:19]
	global_load_dwordx4 v[76:79], v[160:161], off offset:768
	s_waitcnt lgkmcnt(2)
	v_mfma_f32_32x32x16_bf16 v[36:51], v[178:181], v[222:225], v[36:51]
	global_load_dwordx4 v[80:83], v[158:159], off offset:768
	s_waitcnt lgkmcnt(1)
	v_mfma_f32_32x32x16_bf16 v[4:19], v[206:209], v[222:225], v[4:19]
	global_load_dwordx4 v[84:87], v[156:157], off offset:768
	ds_read_b128 v[222:225], v197 offset:41568
	ds_read_b128 v[174:177], v196 offset:4672
	v_mfma_f32_32x32x16_bf16 v[20:35], v[202:205], v[210:213], v[20:35]
	global_load_dwordx4 v[92:95], v[154:155], off offset:768
	ds_read_b128 v[210:213], v196 offset:4704
	ds_read_b128 v[202:205], v196 offset:64
	s_waitcnt lgkmcnt(4)
	v_mfma_f32_32x32x16_bf16 v[52:67], v[178:181], v[214:217], v[52:67]
	global_load_dwordx4 v[104:107], v[152:153], off offset:768
	ds_read_b128 v[218:221], v197 offset:36960
	ds_read_b128 v[178:181], v197 offset:41536
	v_mfma_f32_32x32x16_bf16 v[20:35], v[206:209], v[214:217], v[20:35]
	global_load_dwordx4 v[112:115], v[146:147], off offset:768
	ds_read_b128 v[214:217], v197 offset:36928
	ds_read_b128 v[206:209], v196 offset:96
	s_waitcnt lgkmcnt(1)
	v_mfma_f32_32x32x16_bf16 v[52:67], v[202:205], v[214:217], v[52:67]
	s_waitcnt vmcnt(23)
	ds_write_b128 v190, v[88:91]
	v_mfma_f32_32x32x16_bf16 v[36:51], v[202:205], v[178:181], v[36:51]
	s_waitcnt vmcnt(22)
	ds_write_b128 v190, v[96:99] offset:36864
	v_mfma_f32_32x32x16_bf16 v[20:35], v[174:177], v[214:217], v[20:35]
	s_waitcnt vmcnt(21)
	ds_write_b128 v191, v[100:103]
	v_mfma_f32_32x32x16_bf16 v[4:19], v[174:177], v[178:181], v[4:19]
	s_waitcnt vmcnt(20)
	ds_write_b128 v191, v[108:111] offset:36864
	s_waitcnt lgkmcnt(4)
	v_mfma_f32_32x32x16_bf16 v[52:67], v[206:209], v[218:221], v[52:67]
	s_waitcnt vmcnt(19)
	ds_write_b128 v192, v[116:119]
	v_mfma_f32_32x32x16_bf16 v[36:51], v[206:209], v[222:225], v[36:51]
	s_setprio 0
	s_waitcnt vmcnt(18)
	ds_write_b128 v192, v[120:123] offset:36864
	v_mfma_f32_32x32x16_bf16 v[20:35], v[210:213], v[218:221], v[20:35]
	s_waitcnt vmcnt(17)
	ds_write_b128 v193, v[124:127]
	v_mfma_f32_32x32x16_bf16 v[4:19], v[210:213], v[222:225], v[4:19]
	s_waitcnt vmcnt(16)
	ds_write_b128 v193, v[128:131] offset:36864
	s_waitcnt lgkmcnt(0)
	s_barrier
; template <class Epi, class ColV>
; DI void gemm_tile(const bf16_t* __restrict__ A, int lda, const bf16_t* __restrict__ Bt, int ldb, int K, int m0, int n0, unsigned char* smem, Epi epi, ColV colv, const bf16_t* __restrict__ HYT = nullptr) {
;     ...
;     auto step = [&](int kt, u32x4 (&ldset)[8], const u32x4 (&stset)[8]) {
;         const int buf = kt & 1;
;         if (kt + 2 < nk) gload(ldset, kt + 2);
;         const bf16_t* Ab = As + (buf * 128 + 64 * wr + li) * LS + 8 * lh;
;         const bf16_t* Bb = Bs + (buf * 128 + 64 * wc + li) * LS + 8 * lh;
;         bf16x8 fa[2][2], fb[2][2], ga[2][2], gb[2][2];
; #pragma unroll
;         for (int k2 = 0; k2 < 2; ++k2) { fa[k2][0] = ld8(Ab + 16 * k2); fa[k2][1] = ld8(Ab + 32 * LS + 16 * k2); fb[k2][0] = ld8(Bb + 16 * k2); fb[k2][1] = ld8(Bb + 32 * LS + 16 * k2); }
;         __builtin_amdgcn_sched_barrier(0);
; #pragma unroll
;         for (int k2 = 0; k2 < 2; ++k2) {
;             acc[0][0] = MFMA(fa[k2][0], fb[k2][0], acc[0][0]); acc[0][1] = MFMA(fa[k2][0], fb[k2][1], acc[0][1]);
;             acc[1][0] = MFMA(fa[k2][1], fb[k2][0], acc[1][0]); acc[1][1] = MFMA(fa[k2][1], fb[k2][1], acc[1][1]);
;         }
; #pragma unroll
;         for (int k2 = 0; k2 < 2; ++k2) { const int ks = 2 + k2; ga[k2][0] = ld8(Ab + 16 * ks); ga[k2][1] = ld8(Ab + 32 * LS + 16 * ks); gb[k2][0] = ld8(Bb + 16 * ks); gb[k2][1] = ld8(Bb + 32 * LS + 16 * ks); }
; #pragma unroll
;         for (int k2 = 0; k2 < 2; ++k2) {
;             acc[0][0] = MFMA(ga[k2][0], gb[k2][0], acc[0][0]); acc[0][1] = MFMA(ga[k2][0], gb[k2][1], acc[0][1]);
;             acc[1][0] = MFMA(ga[k2][1], gb[k2][0], acc[1][0]); acc[1][1] = MFMA(ga[k2][1], gb[k2][1], acc[1][1]);
;         }
;         if (kt + 1 < nk) sstore(stset, buf ^ 1, kt + 1);
; #pragma unroll
;         for (int i = 0; i < 8; ++i) { __builtin_amdgcn_sched_group_barrier(0x008, 1, 0); __builtin_amdgcn_sched_group_barrier(0x100, 1, 0); }
; #pragma unroll
;         for (int i = 0; i < 8; ++i) { __builtin_amdgcn_sched_group_barrier(0x008, 1, 0); __builtin_amdgcn_sched_group_barrier(0x200, 1, 0); }
;         __builtin_amdgcn_sched_barrier(0);
;         __syncthreads();
;     };
;     ...
;         XCD_TILE_LOOP(NL / 128, 8, tm, tn) gemm_tile((const bf16_t*)(p.ws + WS_HID), 4096, (const bf16_t*)(p.ws + wbase(layer) + W_FF2), 4096, 4096, tm * 128, tn * 128, smem, epi, gate);
	s_setprio 1
	ds_read_b128 v[174:177], v194
	ds_read_b128 v[210:213], v195 offset:36864
	ds_read_b128 v[218:221], v195 offset:41472
	ds_read_b128 v[202:205], v194 offset:4608
	ds_read_b128 v[178:181], v194 offset:32
	ds_read_b128 v[222:225], v195 offset:41504
	ds_read_b128 v[206:209], v194 offset:4640
	ds_read_b128 v[214:217], v195 offset:36896
	s_waitcnt lgkmcnt(6)
	v_mfma_f32_32x32x16_bf16 v[52:67], v[174:177], v[210:213], v[52:67]
	global_load_dwordx4 v[88:91], v[164:165], off offset:896
	s_waitcnt lgkmcnt(5)
	v_mfma_f32_32x32x16_bf16 v[36:51], v[174:177], v[218:221], v[36:51]
	global_load_dwordx4 v[96:99], v[162:163], off offset:896
	s_waitcnt lgkmcnt(4)
	v_mfma_f32_32x32x16_bf16 v[4:19], v[202:205], v[218:221], v[4:19]
	global_load_dwordx4 v[100:103], v[160:161], off offset:896
	s_waitcnt lgkmcnt(2)
	v_mfma_f32_32x32x16_bf16 v[36:51], v[178:181], v[222:225], v[36:51]
	global_load_dwordx4 v[108:111], v[158:159], off offset:896
	s_waitcnt lgkmcnt(1)
	v_mfma_f32_32x32x16_bf16 v[4:19], v[206:209], v[222:225], v[4:19]
	global_load_dwordx4 v[116:119], v[156:157], off offset:896
	ds_read_b128 v[222:225], v195 offset:41568
	ds_read_b128 v[174:177], v194 offset:4672
	v_mfma_f32_32x32x16_bf16 v[20:35], v[202:205], v[210:213], v[20:35]
	global_load_dwordx4 v[120:123], v[154:155], off offset:896
	ds_read_b128 v[210:213], v194 offset:4704
	ds_read_b128 v[202:205], v194 offset:64
	s_waitcnt lgkmcnt(4)
	v_mfma_f32_32x32x16_bf16 v[52:67], v[178:181], v[214:217], v[52:67]
	global_load_dwordx4 v[124:127], v[152:153], off offset:896
	ds_read_b128 v[218:221], v195 offset:36960
	ds_read_b128 v[178:181], v195 offset:41536
	v_mfma_f32_32x32x16_bf16 v[20:35], v[206:209], v[214:217], v[20:35]
	global_load_dwordx4 v[128:131], v[146:147], off offset:896
	ds_read_b128 v[214:217], v195 offset:36928
	ds_read_b128 v[206:209], v194 offset:96
	s_waitcnt lgkmcnt(1)
	v_mfma_f32_32x32x16_bf16 v[52:67], v[202:205], v[214:217], v[52:67]
	s_waitcnt vmcnt(23)
	ds_write_b128 v190, v[132:135] offset:18432
	v_mfma_f32_32x32x16_bf16 v[36:51], v[202:205], v[178:181], v[36:51]
	s_waitcnt vmcnt(22)
	ds_write_b128 v190, v[136:139] offset:55296
	v_mfma_f32_32x32x16_bf16 v[20:35], v[174:177], v[214:217], v[20:35]
	s_waitcnt vmcnt(21)
	ds_write_b128 v191, v[140:143] offset:18432
	v_mfma_f32_32x32x16_bf16 v[4:19], v[174:177], v[178:181], v[4:19]
	s_waitcnt vmcnt(20)
	ds_write_b128 v191, v[198:201] offset:55296
	s_waitcnt lgkmcnt(4)
	v_mfma_f32_32x32x16_bf16 v[52:67], v[206:209], v[218:221], v[52:67]
	s_waitcnt vmcnt(19)
	ds_write_b128 v192, v[226:229] offset:18432
	v_mfma_f32_32x32x16_bf16 v[36:51], v[206:209], v[222:225], v[36:51]
	s_setprio 0
	s_waitcnt vmcnt(18)
	ds_write_b128 v192, v[230:233] offset:55296
	v_mfma_f32_32x32x16_bf16 v[20:35], v[210:213], v[218:221], v[20:35]
	s_waitcnt vmcnt(17)
	ds_write_b128 v193, v[242:245] offset:18432
	v_mfma_f32_32x32x16_bf16 v[4:19], v[210:213], v[222:225], v[4:19]
	s_waitcnt vmcnt(16)
	ds_write_b128 v193, v[246:249] offset:55296
	s_waitcnt lgkmcnt(0)
	s_barrier
	s_setprio 1
	ds_read_b128 v[174:177], v196
	ds_read_b128 v[210:213], v197 offset:36864
	ds_read_b128 v[218:221], v197 offset:41472
	ds_read_b128 v[202:205], v196 offset:4608
	ds_read_b128 v[178:181], v196 offset:32
	ds_read_b128 v[222:225], v197 offset:41504
	ds_read_b128 v[206:209], v196 offset:4640
	ds_read_b128 v[214:217], v197 offset:36896
	s_waitcnt lgkmcnt(6)
	v_mfma_f32_32x32x16_bf16 v[52:67], v[174:177], v[210:213], v[52:67]
	global_load_dwordx4 v[132:135], v[164:165], off offset:1024
	s_waitcnt lgkmcnt(5)
	v_mfma_f32_32x32x16_bf16 v[36:51], v[174:177], v[218:221], v[36:51]
	global_load_dwordx4 v[136:139], v[162:163], off offset:1024
	s_waitcnt lgkmcnt(4)
	v_mfma_f32_32x32x16_bf16 v[4:19], v[202:205], v[218:221], v[4:19]
	global_load_dwordx4 v[140:143], v[160:161], off offset:1024
	s_waitcnt lgkmcnt(2)
	v_mfma_f32_32x32x16_bf16 v[36:51], v[178:181], v[222:225], v[36:51]
	global_load_dwordx4 v[198:201], v[158:159], off offset:1024
	s_waitcnt lgkmcnt(1)
	v_mfma_f32_32x32x16_bf16 v[4:19], v[206:209], v[222:225], v[4:19]
	global_load_dwordx4 v[226:229], v[156:157], off offset:1024
	ds_read_b128 v[222:225], v197 offset:41568
	ds_read_b128 v[174:177], v196 offset:4672
	v_mfma_f32_32x32x16_bf16 v[20:35], v[202:205], v[210:213], v[20:35]
	global_load_dwordx4 v[230:233], v[154:155], off offset:1024
	ds_read_b128 v[210:213], v196 offset:4704
	ds_read_b128 v[202:205], v196 offset:64
	s_waitcnt lgkmcnt(4)
	v_mfma_f32_32x32x16_bf16 v[52:67], v[178:181], v[214:217], v[52:67]
	global_load_dwordx4 v[242:245], v[152:153], off offset:1024
	ds_read_b128 v[218:221], v197 offset:36960
	ds_read_b128 v[178:181], v197 offset:41536
	v_mfma_f32_32x32x16_bf16 v[20:35], v[206:209], v[214:217], v[20:35]
	global_load_dwordx4 v[246:249], v[146:147], off offset:1024
	ds_read_b128 v[214:217], v197 offset:36928
	ds_read_b128 v[206:209], v196 offset:96
	s_waitcnt lgkmcnt(1)
	v_mfma_f32_32x32x16_bf16 v[52:67], v[202:205], v[214:217], v[52:67]
	s_waitcnt vmcnt(23)
	ds_write_b128 v190, v[68:71]
	v_mfma_f32_32x32x16_bf16 v[36:51], v[202:205], v[178:181], v[36:51]
	s_waitcnt vmcnt(22)
	ds_write_b128 v190, v[72:75] offset:36864
	v_mfma_f32_32x32x16_bf16 v[20:35], v[174:177], v[214:217], v[20:35]
	s_waitcnt vmcnt(21)
	ds_write_b128 v191, v[76:79]
	v_mfma_f32_32x32x16_bf16 v[4:19], v[174:177], v[178:181], v[4:19]
	s_waitcnt vmcnt(20)
	ds_write_b128 v191, v[80:83] offset:36864
	s_waitcnt lgkmcnt(4)
	v_mfma_f32_32x32x16_bf16 v[52:67], v[206:209], v[218:221], v[52:67]
	s_waitcnt vmcnt(19)
	ds_write_b128 v192, v[84:87]
	v_mfma_f32_32x32x16_bf16 v[36:51], v[206:209], v[222:225], v[36:51]
	s_setprio 0
	s_waitcnt vmcnt(18)
	ds_write_b128 v192, v[92:95] offset:36864
	v_mfma_f32_32x32x16_bf16 v[20:35], v[210:213], v[218:221], v[20:35]
	s_waitcnt vmcnt(17)
	ds_write_b128 v193, v[104:107]
	v_mfma_f32_32x32x16_bf16 v[4:19], v[210:213], v[222:225], v[4:19]
	s_waitcnt vmcnt(16)
	ds_write_b128 v193, v[112:115] offset:36864
	s_waitcnt lgkmcnt(0)
	s_barrier
; template <class Epi, class ColV>
; DI void gemm_tile(const bf16_t* __restrict__ A, int lda, const bf16_t* __restrict__ Bt, int ldb, int K, int m0, int n0, unsigned char* smem, Epi epi, ColV colv, const bf16_t* __restrict__ HYT = nullptr) {
;     ...
;     auto step = [&](int kt, u32x4 (&ldset)[8], const u32x4 (&stset)[8]) {
;         const int buf = kt & 1;
;         if (kt + 2 < nk) gload(ldset, kt + 2);
;         const bf16_t* Ab = As + (buf * 128 + 64 * wr + li) * LS + 8 * lh;
;         const bf16_t* Bb = Bs + (buf * 128 + 64 * wc + li) * LS + 8 * lh;
;         bf16x8 fa[2][2], fb[2][2], ga[2][2], gb[2][2];
; #pragma unroll
;         for (int k2 = 0; k2 < 2; ++k2) { fa[k2][0] = ld8(Ab + 16 * k2); fa[k2][1] = ld8(Ab + 32 * LS + 16 * k2); fb[k2][0] = ld8(Bb + 16 * k2); fb[k2][1] = ld8(Bb + 32 * LS + 16 * k2); }
;         __builtin_amdgcn_sched_barrier(0);
; #pragma unroll
;         for (int k2 = 0; k2 < 2; ++k2) {
;             acc[0][0] = MFMA(fa[k2][0], fb[k2][0], acc[0][0]); acc[0][1] = MFMA(fa[k2][0], fb[k2][1], acc[0][1]);
;             acc[1][0] = MFMA(fa[k2][1], fb[k2][0], acc[1][0]); acc[1][1] = MFMA(fa[k2][1], fb[k2][1], acc[1][1]);
;         }
; #pragma unroll
;         for (int k2 = 0; k2 < 2; ++k2) { const int ks = 2 + k2; ga[k2][0] = ld8(Ab + 16 * ks); ga[k2][1] = ld8(Ab + 32 * LS + 16 * ks); gb[k2][0] = ld8(Bb + 16 * ks); gb[k2][1] = ld8(Bb + 32 * LS + 16 * ks); }
; #pragma unroll
;         for (int k2 = 0; k2 < 2; ++k2) {
;             acc[0][0] = MFMA(ga[k2][0], gb[k2][0], acc[0][0]); acc[0][1] = MFMA(ga[k2][0], gb[k2][1], acc[0][1]);
;             acc[1][0] = MFMA(ga[k2][1], gb[k2][0], acc[1][0]); acc[1][1] = MFMA(ga[k2][1], gb[k2][1], acc[1][1]);
;         }
;         if (kt + 1 < nk) sstore(stset, buf ^ 1, kt + 1);
; #pragma unroll
;         for (int i = 0; i < 8; ++i) { __builtin_amdgcn_sched_group_barrier(0x008, 1, 0); __builtin_amdgcn_sched_group_barrier(0x100, 1, 0); }
; #pragma unroll
;         for (int i = 0; i < 8; ++i) { __builtin_amdgcn_sched_group_barrier(0x008, 1, 0); __builtin_amdgcn_sched_group_barrier(0x200, 1, 0); }
;         __builtin_amdgcn_sched_barrier(0);
;         __syncthreads();
;     };
;     gload(R0, 0); gload(R1, 1);
;     sstore(R0, 0, 0); __syncthreads();
;     for (int kt = 0; kt < nk; kt += 2) {
;         step(kt, R0, R1);
;         if (kt + 1 < nk) step(kt + 1, R1, R0);
;     }
	s_setprio 1
	v_lshl_add_u64 v[164:165], v[164:165], 0, s[100:101]
	v_lshl_add_u64 v[162:163], v[162:163], 0, s[100:101]
	v_lshl_add_u64 v[160:161], v[160:161], 0, s[100:101]
	v_lshl_add_u64 v[158:159], v[158:159], 0, s[100:101]
	v_lshl_add_u64 v[156:157], v[156:157], 0, s[100:101]
	v_lshl_add_u64 v[154:155], v[154:155], 0, s[100:101]
	v_lshl_add_u64 v[152:153], v[152:153], 0, s[100:101]
	v_lshl_add_u64 v[146:147], v[146:147], 0, s[100:101]
	s_sub_u32 s41, s41, 1
	s_cmp_lg_u32 s41, 0
	s_cbranch_scc1 .Lg3_phase11
	ds_read_b128 v[174:177], v194
	ds_read_b128 v[210:213], v195 offset:36864
	ds_read_b128 v[218:221], v195 offset:41472
	ds_read_b128 v[202:205], v194 offset:4608
	ds_read_b128 v[178:181], v194 offset:32
	ds_read_b128 v[222:225], v195 offset:41504
	ds_read_b128 v[206:209], v194 offset:4640
	ds_read_b128 v[214:217], v195 offset:36896
	s_waitcnt lgkmcnt(6)
	v_mfma_f32_32x32x16_bf16 v[52:67], v[174:177], v[210:213], v[52:67]
	global_load_dwordx4 v[68:71], v[164:165], off offset:384
	s_waitcnt lgkmcnt(5)
	v_mfma_f32_32x32x16_bf16 v[36:51], v[174:177], v[218:221], v[36:51]
	global_load_dwordx4 v[72:75], v[162:163], off offset:384
	s_waitcnt lgkmcnt(4)
	v_mfma_f32_32x32x16_bf16 v[4:19], v[202:205], v[218:221], v[4:19]
	global_load_dwordx4 v[76:79], v[160:161], off offset:384
	s_waitcnt lgkmcnt(2)
	v_mfma_f32_32x32x16_bf16 v[36:51], v[178:181], v[222:225], v[36:51]
	global_load_dwordx4 v[80:83], v[158:159], off offset:384
	s_waitcnt lgkmcnt(1)
	v_mfma_f32_32x32x16_bf16 v[4:19], v[206:209], v[222:225], v[4:19]
	global_load_dwordx4 v[84:87], v[156:157], off offset:384
	ds_read_b128 v[222:225], v195 offset:41568
	ds_read_b128 v[174:177], v194 offset:4672
	v_mfma_f32_32x32x16_bf16 v[20:35], v[202:205], v[210:213], v[20:35]
	global_load_dwordx4 v[92:95], v[154:155], off offset:384
	ds_read_b128 v[210:213], v194 offset:4704
	ds_read_b128 v[202:205], v194 offset:64
	s_waitcnt lgkmcnt(4)
	v_mfma_f32_32x32x16_bf16 v[52:67], v[178:181], v[214:217], v[52:67]
	global_load_dwordx4 v[104:107], v[152:153], off offset:384
	ds_read_b128 v[218:221], v195 offset:36960
	ds_read_b128 v[178:181], v195 offset:41536
	v_mfma_f32_32x32x16_bf16 v[20:35], v[206:209], v[214:217], v[20:35]
	global_load_dwordx4 v[112:115], v[146:147], off offset:384
	ds_read_b128 v[214:217], v195 offset:36928
	ds_read_b128 v[206:209], v194 offset:96
	s_waitcnt lgkmcnt(1)
	v_mfma_f32_32x32x16_bf16 v[52:67], v[202:205], v[214:217], v[52:67]
	s_waitcnt vmcnt(23)
	ds_write_b128 v190, v[88:91] offset:18432
	v_mfma_f32_32x32x16_bf16 v[36:51], v[202:205], v[178:181], v[36:51]
	s_waitcnt vmcnt(22)
	ds_write_b128 v190, v[96:99] offset:55296
	v_mfma_f32_32x32x16_bf16 v[20:35], v[174:177], v[214:217], v[20:35]
	s_waitcnt vmcnt(21)
	ds_write_b128 v191, v[100:103] offset:18432
	v_mfma_f32_32x32x16_bf16 v[4:19], v[174:177], v[178:181], v[4:19]
	s_waitcnt vmcnt(20)
	ds_write_b128 v191, v[108:111] offset:55296
	s_waitcnt lgkmcnt(4)
	v_mfma_f32_32x32x16_bf16 v[52:67], v[206:209], v[218:221], v[52:67]
	s_waitcnt vmcnt(19)
	ds_write_b128 v192, v[116:119] offset:18432
	v_mfma_f32_32x32x16_bf16 v[36:51], v[206:209], v[222:225], v[36:51]
	s_setprio 0
	s_waitcnt vmcnt(18)
	ds_write_b128 v192, v[120:123] offset:55296
	v_mfma_f32_32x32x16_bf16 v[20:35], v[210:213], v[218:221], v[20:35]
	s_waitcnt vmcnt(17)
	ds_write_b128 v193, v[124:127] offset:18432
	v_mfma_f32_32x32x16_bf16 v[4:19], v[210:213], v[222:225], v[4:19]
	s_waitcnt vmcnt(16)
	ds_write_b128 v193, v[128:131] offset:55296
	s_waitcnt lgkmcnt(0)
	s_barrier
	s_setprio 1
	ds_read_b128 v[174:177], v196
	ds_read_b128 v[178:181], v196 offset:32
	ds_read_b128 v[202:205], v196 offset:4608
	ds_read_b128 v[206:209], v196 offset:4640
	ds_read_b128 v[210:213], v197 offset:36864
	ds_read_b128 v[214:217], v197 offset:36896
	ds_read_b128 v[218:221], v197 offset:41472
	ds_read_b128 v[222:225], v197 offset:41504
	s_waitcnt lgkmcnt(3)
	v_mfma_f32_32x32x16_bf16 v[52:67], v[174:177], v[210:213], v[52:67]
	s_waitcnt lgkmcnt(1)
	v_mfma_f32_32x32x16_bf16 v[36:51], v[174:177], v[218:221], v[36:51]
	v_mfma_f32_32x32x16_bf16 v[4:19], v[202:205], v[218:221], v[4:19]
	s_waitcnt lgkmcnt(0)
	v_mfma_f32_32x32x16_bf16 v[36:51], v[178:181], v[222:225], v[36:51]
	v_mfma_f32_32x32x16_bf16 v[4:19], v[206:209], v[222:225], v[4:19]
	ds_read_b128 v[222:225], v197 offset:41568
	ds_read_b128 v[174:177], v196 offset:4672
	v_mfma_f32_32x32x16_bf16 v[20:35], v[202:205], v[210:213], v[20:35]
	ds_read_b128 v[210:213], v196 offset:4704
	ds_read_b128 v[202:205], v196 offset:64
	v_mfma_f32_32x32x16_bf16 v[52:67], v[178:181], v[214:217], v[52:67]
	ds_read_b128 v[218:221], v197 offset:36960
	ds_read_b128 v[178:181], v197 offset:41536
	v_mfma_f32_32x32x16_bf16 v[20:35], v[206:209], v[214:217], v[20:35]
	ds_read_b128 v[214:217], v197 offset:36928
	ds_read_b128 v[206:209], v196 offset:96
	s_waitcnt lgkmcnt(1)
	v_mfma_f32_32x32x16_bf16 v[52:67], v[202:205], v[214:217], v[52:67]
	s_waitcnt vmcnt(15)
	ds_write_b128 v190, v[132:135]
	v_mfma_f32_32x32x16_bf16 v[36:51], v[202:205], v[178:181], v[36:51]
	s_waitcnt vmcnt(14)
	ds_write_b128 v190, v[136:139] offset:36864
	v_mfma_f32_32x32x16_bf16 v[20:35], v[174:177], v[214:217], v[20:35]
	s_waitcnt vmcnt(13)
	ds_write_b128 v191, v[140:143]
	v_mfma_f32_32x32x16_bf16 v[4:19], v[174:177], v[178:181], v[4:19]
	s_waitcnt vmcnt(12)
	ds_write_b128 v191, v[198:201] offset:36864
	s_waitcnt lgkmcnt(4)
	v_mfma_f32_32x32x16_bf16 v[52:67], v[206:209], v[218:221], v[52:67]
	s_waitcnt vmcnt(11)
	ds_write_b128 v192, v[226:229]
	v_mfma_f32_32x32x16_bf16 v[36:51], v[206:209], v[222:225], v[36:51]
	s_setprio 0
	s_waitcnt vmcnt(10)
	ds_write_b128 v192, v[230:233] offset:36864
	v_mfma_f32_32x32x16_bf16 v[20:35], v[210:213], v[218:221], v[20:35]
	s_waitcnt vmcnt(9)
	ds_write_b128 v193, v[242:245]
	v_mfma_f32_32x32x16_bf16 v[4:19], v[210:213], v[222:225], v[4:19]
	s_waitcnt vmcnt(8)
	ds_write_b128 v193, v[246:249] offset:36864
	s_waitcnt lgkmcnt(0)
	s_barrier
; template <class Epi, class ColV>
; DI void gemm_tile(const bf16_t* __restrict__ A, int lda, const bf16_t* __restrict__ Bt, int ldb, int K, int m0, int n0, unsigned char* smem, Epi epi, ColV colv, const bf16_t* __restrict__ HYT = nullptr) {
;     ...
;     auto step = [&](int kt, u32x4 (&ldset)[8], const u32x4 (&stset)[8]) {
;         const int buf = kt & 1;
;         if (kt + 2 < nk) gload(ldset, kt + 2);
;         const bf16_t* Ab = As + (buf * 128 + 64 * wr + li) * LS + 8 * lh;
;         const bf16_t* Bb = Bs + (buf * 128 + 64 * wc + li) * LS + 8 * lh;
;         bf16x8 fa[2][2], fb[2][2], ga[2][2], gb[2][2];
; #pragma unroll
;         for (int k2 = 0; k2 < 2; ++k2) { fa[k2][0] = ld8(Ab + 16 * k2); fa[k2][1] = ld8(Ab + 32 * LS + 16 * k2); fb[k2][0] = ld8(Bb + 16 * k2); fb[k2][1] = ld8(Bb + 32 * LS + 16 * k2); }
;         __builtin_amdgcn_sched_barrier(0);
; #pragma unroll
;         for (int k2 = 0; k2 < 2; ++k2) {
;             acc[0][0] = MFMA(fa[k2][0], fb[k2][0], acc[0][0]); acc[0][1] = MFMA(fa[k2][0], fb[k2][1], acc[0][1]);
;             acc[1][0] = MFMA(fa[k2][1], fb[k2][0], acc[1][0]); acc[1][1] = MFMA(fa[k2][1], fb[k2][1], acc[1][1]);
;         }
; #pragma unroll
;         for (int k2 = 0; k2 < 2; ++k2) { const int ks = 2 + k2; ga[k2][0] = ld8(Ab + 16 * ks); ga[k2][1] = ld8(Ab + 32 * LS + 16 * ks); gb[k2][0] = ld8(Bb + 16 * ks); gb[k2][1] = ld8(Bb + 32 * LS + 16 * ks); }
; #pragma unroll
;         for (int k2 = 0; k2 < 2; ++k2) {
;             acc[0][0] = MFMA(ga[k2][0], gb[k2][0], acc[0][0]); acc[0][1] = MFMA(ga[k2][0], gb[k2][1], acc[0][1]);
;             acc[1][0] = MFMA(ga[k2][1], gb[k2][0], acc[1][0]); acc[1][1] = MFMA(ga[k2][1], gb[k2][1], acc[1][1]);
;         }
;         if (kt + 1 < nk) sstore(stset, buf ^ 1, kt + 1);
; #pragma unroll
;         for (int i = 0; i < 8; ++i) { __builtin_amdgcn_sched_group_barrier(0x008, 1, 0); __builtin_amdgcn_sched_group_barrier(0x100, 1, 0); }
; #pragma unroll
;         for (int i = 0; i < 8; ++i) { __builtin_amdgcn_sched_group_barrier(0x008, 1, 0); __builtin_amdgcn_sched_group_barrier(0x200, 1, 0); }
;         __builtin_amdgcn_sched_barrier(0);
;         __syncthreads();
;     };
;     gload(R0, 0); gload(R1, 1);
;     sstore(R0, 0, 0); __syncthreads();
;     for (int kt = 0; kt < nk; kt += 2) {
;         step(kt, R0, R1);
;         if (kt + 1 < nk) step(kt + 1, R1, R0);
;     }
	s_setprio 1
	ds_read_b128 v[174:177], v194
	ds_read_b128 v[178:181], v194 offset:32
	ds_read_b128 v[202:205], v194 offset:4608
	ds_read_b128 v[206:209], v194 offset:4640
	ds_read_b128 v[210:213], v195 offset:36864
	ds_read_b128 v[214:217], v195 offset:36896
	ds_read_b128 v[218:221], v195 offset:41472
	ds_read_b128 v[222:225], v195 offset:41504
	s_waitcnt lgkmcnt(3)
	v_mfma_f32_32x32x16_bf16 v[52:67], v[174:177], v[210:213], v[52:67]
	s_waitcnt lgkmcnt(1)
	v_mfma_f32_32x32x16_bf16 v[36:51], v[174:177], v[218:221], v[36:51]
	v_mfma_f32_32x32x16_bf16 v[4:19], v[202:205], v[218:221], v[4:19]
	s_waitcnt lgkmcnt(0)
	v_mfma_f32_32x32x16_bf16 v[36:51], v[178:181], v[222:225], v[36:51]
	v_mfma_f32_32x32x16_bf16 v[4:19], v[206:209], v[222:225], v[4:19]
	ds_read_b128 v[222:225], v195 offset:41568
	ds_read_b128 v[174:177], v194 offset:4672
	v_mfma_f32_32x32x16_bf16 v[20:35], v[202:205], v[210:213], v[20:35]
	ds_read_b128 v[210:213], v194 offset:4704
	ds_read_b128 v[202:205], v194 offset:64
	v_mfma_f32_32x32x16_bf16 v[52:67], v[178:181], v[214:217], v[52:67]
	ds_read_b128 v[218:221], v195 offset:36960
	ds_read_b128 v[178:181], v195 offset:41536
	v_mfma_f32_32x32x16_bf16 v[20:35], v[206:209], v[214:217], v[20:35]
	ds_read_b128 v[214:217], v195 offset:36928
	ds_read_b128 v[206:209], v194 offset:96
	s_waitcnt lgkmcnt(1)
	v_mfma_f32_32x32x16_bf16 v[52:67], v[202:205], v[214:217], v[52:67]
	s_waitcnt vmcnt(7)
	ds_write_b128 v190, v[68:71] offset:18432
	v_mfma_f32_32x32x16_bf16 v[36:51], v[202:205], v[178:181], v[36:51]
	s_waitcnt vmcnt(6)
	ds_write_b128 v190, v[72:75] offset:55296
	v_mfma_f32_32x32x16_bf16 v[20:35], v[174:177], v[214:217], v[20:35]
	s_waitcnt vmcnt(5)
	ds_write_b128 v191, v[76:79] offset:18432
	v_mfma_f32_32x32x16_bf16 v[4:19], v[174:177], v[178:181], v[4:19]
	s_waitcnt vmcnt(4)
	ds_write_b128 v191, v[80:83] offset:55296
	s_waitcnt lgkmcnt(4)
	v_mfma_f32_32x32x16_bf16 v[52:67], v[206:209], v[218:221], v[52:67]
	s_waitcnt vmcnt(3)
	ds_write_b128 v192, v[84:87] offset:18432
	v_mfma_f32_32x32x16_bf16 v[36:51], v[206:209], v[222:225], v[36:51]
	s_setprio 0
	s_waitcnt vmcnt(2)
	ds_write_b128 v192, v[92:95] offset:55296
	v_mfma_f32_32x32x16_bf16 v[20:35], v[210:213], v[218:221], v[20:35]
	s_waitcnt vmcnt(1)
	ds_write_b128 v193, v[104:107] offset:18432
	v_mfma_f32_32x32x16_bf16 v[4:19], v[210:213], v[222:225], v[4:19]
	s_waitcnt vmcnt(0)
	ds_write_b128 v193, v[112:115] offset:55296
	s_waitcnt lgkmcnt(0)
	s_barrier
	s_setprio 1
	ds_read_b128 v[174:177], v196
	ds_read_b128 v[178:181], v196 offset:32
	ds_read_b128 v[202:205], v196 offset:4608
	ds_read_b128 v[206:209], v196 offset:4640
	ds_read_b128 v[210:213], v197 offset:36864
	ds_read_b128 v[214:217], v197 offset:36896
	ds_read_b128 v[218:221], v197 offset:41472
	ds_read_b128 v[222:225], v197 offset:41504
	s_waitcnt lgkmcnt(3)
	v_mfma_f32_32x32x16_bf16 v[52:67], v[174:177], v[210:213], v[52:67]
	s_waitcnt lgkmcnt(1)
	v_mfma_f32_32x32x16_bf16 v[36:51], v[174:177], v[218:221], v[36:51]
	v_mfma_f32_32x32x16_bf16 v[4:19], v[202:205], v[218:221], v[4:19]
	s_waitcnt lgkmcnt(0)
	v_mfma_f32_32x32x16_bf16 v[36:51], v[178:181], v[222:225], v[36:51]
	v_mfma_f32_32x32x16_bf16 v[4:19], v[206:209], v[222:225], v[4:19]
	ds_read_b128 v[222:225], v197 offset:41568
	ds_read_b128 v[174:177], v196 offset:4672
	v_mfma_f32_32x32x16_bf16 v[20:35], v[202:205], v[210:213], v[20:35]
	ds_read_b128 v[210:213], v196 offset:4704
	ds_read_b128 v[202:205], v196 offset:64
	v_mfma_f32_32x32x16_bf16 v[52:67], v[178:181], v[214:217], v[52:67]
	ds_read_b128 v[218:221], v197 offset:36960
	ds_read_b128 v[178:181], v197 offset:41536
	v_mfma_f32_32x32x16_bf16 v[20:35], v[206:209], v[214:217], v[20:35]
	ds_read_b128 v[214:217], v197 offset:36928
	ds_read_b128 v[206:209], v196 offset:96
	s_waitcnt lgkmcnt(1)
	v_mfma_f32_32x32x16_bf16 v[52:67], v[202:205], v[214:217], v[52:67]
	v_mfma_f32_32x32x16_bf16 v[36:51], v[202:205], v[178:181], v[36:51]
	v_mfma_f32_32x32x16_bf16 v[20:35], v[174:177], v[214:217], v[20:35]
	v_mfma_f32_32x32x16_bf16 v[4:19], v[174:177], v[178:181], v[4:19]
	s_waitcnt lgkmcnt(0)
	v_mfma_f32_32x32x16_bf16 v[52:67], v[206:209], v[218:221], v[52:67]
	v_mfma_f32_32x32x16_bf16 v[36:51], v[206:209], v[222:225], v[36:51]
	s_setprio 0
	v_mfma_f32_32x32x16_bf16 v[20:35], v[210:213], v[218:221], v[20:35]
	v_mfma_f32_32x32x16_bf16 v[4:19], v[210:213], v[222:225], v[4:19]
	s_waitcnt lgkmcnt(0)
	s_barrier
	s_setprio 1
	s_nop 7
	s_nop 3
	s_branch .LBB0_37

; template <class Epi, class ColV>
; DI void gemm_tile(const bf16_t* __restrict__ A, int lda, const bf16_t* __restrict__ Bt, int ldb, int K, int m0, int n0, unsigned char* smem, Epi epi, ColV colv, const bf16_t* __restrict__ HYT = nullptr) {
;     ...
;     auto step = [&](int kt, u32x4 (&ldset)[8], const u32x4 (&stset)[8]) {
;         const int buf = kt & 1;
;         if (kt + 2 < nk) gload(ldset, kt + 2);
;         const bf16_t* Ab = As + (buf * 128 + 64 * wr + li) * LS + 8 * lh;
;         const bf16_t* Bb = Bs + (buf * 128 + 64 * wc + li) * LS + 8 * lh;
;         bf16x8 fa[2][2], fb[2][2], ga[2][2], gb[2][2];
; #pragma unroll
;         for (int k2 = 0; k2 < 2; ++k2) { fa[k2][0] = ld8(Ab + 16 * k2); fa[k2][1] = ld8(Ab + 32 * LS + 16 * k2); fb[k2][0] = ld8(Bb + 16 * k2); fb[k2][1] = ld8(Bb + 32 * LS + 16 * k2); }
;         __builtin_amdgcn_sched_barrier(0);
; #pragma unroll
;         for (int k2 = 0; k2 < 2; ++k2) {
;             acc[0][0] = MFMA(fa[k2][0], fb[k2][0], acc[0][0]); acc[0][1] = MFMA(fa[k2][0], fb[k2][1], acc[0][1]);
;             acc[1][0] = MFMA(fa[k2][1], fb[k2][0], acc[1][0]); acc[1][1] = MFMA(fa[k2][1], fb[k2][1], acc[1][1]);
;         }
; #pragma unroll
;         for (int k2 = 0; k2 < 2; ++k2) { const int ks = 2 + k2; ga[k2][0] = ld8(Ab + 16 * ks); ga[k2][1] = ld8(Ab + 32 * LS + 16 * ks); gb[k2][0] = ld8(Bb + 16 * ks); gb[k2][1] = ld8(Bb + 32 * LS + 16 * ks); }
; #pragma unroll
;         for (int k2 = 0; k2 < 2; ++k2) {
;             acc[0][0] = MFMA(ga[k2][0], gb[k2][0], acc[0][0]); acc[0][1] = MFMA(ga[k2][0], gb[k2][1], acc[0][1]);
;             acc[1][0] = MFMA(ga[k2][1], gb[k2][0], acc[1][0]); acc[1][1] = MFMA(ga[k2][1], gb[k2][1], acc[1][1]);
;         }
;         if (kt + 1 < nk) sstore(stset, buf ^ 1, kt + 1);
; #pragma unroll
;         for (int i = 0; i < 8; ++i) { __builtin_amdgcn_sched_group_barrier(0x008, 1, 0); __builtin_amdgcn_sched_group_barrier(0x100, 1, 0); }
; #pragma unroll
;         for (int i = 0; i < 8; ++i) { __builtin_amdgcn_sched_group_barrier(0x008, 1, 0); __builtin_amdgcn_sched_group_barrier(0x200, 1, 0); }
;         __builtin_amdgcn_sched_barrier(0);
;         __syncthreads();
;     };
;     gload(R0, 0); gload(R1, 1);
;     sstore(R0, 0, 0); __syncthreads();
;     for (int kt = 0; kt < nk; kt += 2) {
;         step(kt, R0, R1);
;         if (kt + 1 < nk) step(kt + 1, R1, R0);
;     }
.LBB0_56:
	s_cmp_lt_u32 s40, 14
	s_cselect_b64 s[18:19], -1, 0
	s_cmp_gt_u32 s40, 13
	s_cselect_b64 s[12:13], -1, 0
	s_and_b64 vcc, exec, s[12:13]
	v_lshl_add_u64 v[164:165], v[144:145], 0, v[2:3]
	v_lshl_add_u64 v[162:163], v[142:143], 0, v[2:3]
	v_lshl_add_u64 v[160:161], v[140:141], 0, v[2:3]
	v_lshl_add_u64 v[158:159], v[138:139], 0, v[2:3]
	v_lshl_add_u64 v[156:157], v[136:137], 0, v[2:3]
	v_lshl_add_u64 v[154:155], v[134:135], 0, v[2:3]
	v_lshl_add_u64 v[152:153], v[132:133], 0, v[2:3]
	v_lshl_add_u64 v[146:147], v[0:1], 0, v[2:3]
	s_mov_b32 s100, 0x26ca000
	s_mov_b32 s101, 0
	v_lshl_add_u64 v[164:165], v[164:165], 0, s[100:101]
	v_lshl_add_u64 v[160:161], v[160:161], 0, s[100:101]
	v_lshl_add_u64 v[156:157], v[156:157], 0, s[100:101]
	v_lshl_add_u64 v[152:153], v[152:153], 0, s[100:101]
	s_mov_b32 s100, 0x680000
	s_mov_b32 s101, 0
	v_lshl_add_u64 v[162:163], v[162:163], 0, s[100:101]
	v_lshl_add_u64 v[158:159], v[158:159], 0, s[100:101]
	v_lshl_add_u64 v[154:155], v[154:155], 0, s[100:101]
	v_lshl_add_u64 v[146:147], v[146:147], 0, s[100:101]
	ds_read_b128 v[174:177], v194
	ds_read_b128 v[210:213], v195 offset:36864
	ds_read_b128 v[218:221], v195 offset:41472
	ds_read_b128 v[202:205], v194 offset:4608
	ds_read_b128 v[178:181], v194 offset:32
	ds_read_b128 v[222:225], v195 offset:41504
	ds_read_b128 v[206:209], v194 offset:4640
	ds_read_b128 v[214:217], v195 offset:36896
	s_waitcnt lgkmcnt(6)
	v_mfma_f32_32x32x16_bf16 v[52:67], v[174:177], v[210:213], v[52:67]
	global_load_dwordx4 v[132:135], v[164:165], off offset:256
	global_load_dwordx4 v[136:139], v[162:163], off offset:256
	s_waitcnt lgkmcnt(5)
	v_mfma_f32_32x32x16_bf16 v[36:51], v[174:177], v[218:221], v[36:51]
	global_load_dwordx4 v[140:143], v[160:161], off offset:256
	global_load_dwordx4 v[198:201], v[158:159], off offset:256
	s_waitcnt lgkmcnt(4)
	v_mfma_f32_32x32x16_bf16 v[4:19], v[202:205], v[218:221], v[4:19]
	global_load_dwordx4 v[226:229], v[156:157], off offset:256
	global_load_dwordx4 v[230:233], v[154:155], off offset:256
	s_waitcnt lgkmcnt(2)
	v_mfma_f32_32x32x16_bf16 v[36:51], v[178:181], v[222:225], v[36:51]
	global_load_dwordx4 v[242:245], v[152:153], off offset:256
	global_load_dwordx4 v[246:249], v[146:147], off offset:256
	s_waitcnt lgkmcnt(1)
	v_mfma_f32_32x32x16_bf16 v[4:19], v[206:209], v[222:225], v[4:19]
	global_load_dwordx4 v[68:71], v[164:165], off offset:384
	global_load_dwordx4 v[72:75], v[162:163], off offset:384
	ds_read_b128 v[222:225], v195 offset:41568
	ds_read_b128 v[174:177], v194 offset:4672
	v_mfma_f32_32x32x16_bf16 v[20:35], v[202:205], v[210:213], v[20:35]
	global_load_dwordx4 v[76:79], v[160:161], off offset:384
	global_load_dwordx4 v[80:83], v[158:159], off offset:384
	ds_read_b128 v[210:213], v194 offset:4704
	ds_read_b128 v[202:205], v194 offset:64
	s_waitcnt lgkmcnt(4)
	v_mfma_f32_32x32x16_bf16 v[52:67], v[178:181], v[214:217], v[52:67]
	global_load_dwordx4 v[84:87], v[156:157], off offset:384
	global_load_dwordx4 v[92:95], v[154:155], off offset:384
	ds_read_b128 v[218:221], v195 offset:36960
	ds_read_b128 v[178:181], v195 offset:41536
	v_mfma_f32_32x32x16_bf16 v[20:35], v[206:209], v[214:217], v[20:35]
	global_load_dwordx4 v[104:107], v[152:153], off offset:384
	global_load_dwordx4 v[112:115], v[146:147], off offset:384
	ds_read_b128 v[214:217], v195 offset:36928
	ds_read_b128 v[206:209], v194 offset:96
	s_waitcnt lgkmcnt(1)
	v_mfma_f32_32x32x16_bf16 v[52:67], v[202:205], v[214:217], v[52:67]
	s_waitcnt vmcnt(16)
	ds_write_b128 v167, v[88:91] offset:18432
	v_mfma_f32_32x32x16_bf16 v[36:51], v[202:205], v[178:181], v[36:51]
	ds_write_b128 v167, v[96:99] offset:55296
	v_mfma_f32_32x32x16_bf16 v[20:35], v[174:177], v[214:217], v[20:35]
	ds_write_b128 v190, v[100:103] offset:18432
	v_mfma_f32_32x32x16_bf16 v[4:19], v[174:177], v[178:181], v[4:19]
	ds_write_b128 v190, v[108:111] offset:55296
	s_waitcnt lgkmcnt(4)
	v_mfma_f32_32x32x16_bf16 v[52:67], v[206:209], v[218:221], v[52:67]
	ds_write_b128 v191, v[116:119] offset:18432
	v_mfma_f32_32x32x16_bf16 v[36:51], v[206:209], v[222:225], v[36:51]
	s_setprio 0
	ds_write_b128 v191, v[120:123] offset:55296
	v_mfma_f32_32x32x16_bf16 v[20:35], v[210:213], v[218:221], v[20:35]
	ds_write_b128 v192, v[124:127] offset:18432
	v_mfma_f32_32x32x16_bf16 v[4:19], v[210:213], v[222:225], v[4:19]
	ds_write_b128 v192, v[128:131] offset:55296
	s_waitcnt lgkmcnt(0)
	s_barrier
; template <class Epi, class ColV>
; DI void gemm_tile(const bf16_t* __restrict__ A, int lda, const bf16_t* __restrict__ Bt, int ldb, int K, int m0, int n0, unsigned char* smem, Epi epi, ColV colv, const bf16_t* __restrict__ HYT = nullptr) {
;     ...
;     auto step = [&](int kt, u32x4 (&ldset)[8], const u32x4 (&stset)[8]) {
;         const int buf = kt & 1;
;         if (kt + 2 < nk) gload(ldset, kt + 2);
;         const bf16_t* Ab = As + (buf * 128 + 64 * wr + li) * LS + 8 * lh;
;         const bf16_t* Bb = Bs + (buf * 128 + 64 * wc + li) * LS + 8 * lh;
;         bf16x8 fa[2][2], fb[2][2], ga[2][2], gb[2][2];
; #pragma unroll
;         for (int k2 = 0; k2 < 2; ++k2) { fa[k2][0] = ld8(Ab + 16 * k2); fa[k2][1] = ld8(Ab + 32 * LS + 16 * k2); fb[k2][0] = ld8(Bb + 16 * k2); fb[k2][1] = ld8(Bb + 32 * LS + 16 * k2); }
;         __builtin_amdgcn_sched_barrier(0);
; #pragma unroll
;         for (int k2 = 0; k2 < 2; ++k2) {
;             acc[0][0] = MFMA(fa[k2][0], fb[k2][0], acc[0][0]); acc[0][1] = MFMA(fa[k2][0], fb[k2][1], acc[0][1]);
;             acc[1][0] = MFMA(fa[k2][1], fb[k2][0], acc[1][0]); acc[1][1] = MFMA(fa[k2][1], fb[k2][1], acc[1][1]);
;         }
; #pragma unroll
;         for (int k2 = 0; k2 < 2; ++k2) { const int ks = 2 + k2; ga[k2][0] = ld8(Ab + 16 * ks); ga[k2][1] = ld8(Ab + 32 * LS + 16 * ks); gb[k2][0] = ld8(Bb + 16 * ks); gb[k2][1] = ld8(Bb + 32 * LS + 16 * ks); }
; #pragma unroll
;         for (int k2 = 0; k2 < 2; ++k2) {
;             acc[0][0] = MFMA(ga[k2][0], gb[k2][0], acc[0][0]); acc[0][1] = MFMA(ga[k2][0], gb[k2][1], acc[0][1]);
;             acc[1][0] = MFMA(ga[k2][1], gb[k2][0], acc[1][0]); acc[1][1] = MFMA(ga[k2][1], gb[k2][1], acc[1][1]);
;         }
;         if (kt + 1 < nk) sstore(stset, buf ^ 1, kt + 1);
; #pragma unroll
;         for (int i = 0; i < 8; ++i) { __builtin_amdgcn_sched_group_barrier(0x008, 1, 0); __builtin_amdgcn_sched_group_barrier(0x100, 1, 0); }
; #pragma unroll
;         for (int i = 0; i < 8; ++i) { __builtin_amdgcn_sched_group_barrier(0x008, 1, 0); __builtin_amdgcn_sched_group_barrier(0x200, 1, 0); }
;         __builtin_amdgcn_sched_barrier(0);
;         __syncthreads();
;     };
;     ...
;         XCD_TILE_LOOP((layer == 0 ? NT : NL) / 128, 32, tm, tn) gemm_tile((const bf16_t*)(p.ws + WS_H), 1024, (const bf16_t*)(p.ws + wbase(layer) + W_FF1), 1024, 1024, tm * 128, tn * 128, smem, epi, nocol);
	s_setprio 1
	ds_read_b128 v[174:177], v196
	ds_read_b128 v[210:213], v197 offset:36864
	ds_read_b128 v[218:221], v197 offset:41472
	ds_read_b128 v[202:205], v196 offset:4608
	ds_read_b128 v[178:181], v196 offset:32
	ds_read_b128 v[222:225], v197 offset:41504
	ds_read_b128 v[206:209], v196 offset:4640
	ds_read_b128 v[214:217], v197 offset:36896
	s_waitcnt lgkmcnt(6)
	v_mfma_f32_32x32x16_bf16 v[52:67], v[174:177], v[210:213], v[52:67]
	global_load_dwordx4 v[88:91], v[164:165], off offset:512
	s_waitcnt lgkmcnt(5)
	v_mfma_f32_32x32x16_bf16 v[36:51], v[174:177], v[218:221], v[36:51]
	global_load_dwordx4 v[96:99], v[162:163], off offset:512
	s_waitcnt lgkmcnt(4)
	v_mfma_f32_32x32x16_bf16 v[4:19], v[202:205], v[218:221], v[4:19]
	global_load_dwordx4 v[100:103], v[160:161], off offset:512
	s_waitcnt lgkmcnt(2)
	v_mfma_f32_32x32x16_bf16 v[36:51], v[178:181], v[222:225], v[36:51]
	global_load_dwordx4 v[108:111], v[158:159], off offset:512
	s_waitcnt lgkmcnt(1)
	v_mfma_f32_32x32x16_bf16 v[4:19], v[206:209], v[222:225], v[4:19]
	global_load_dwordx4 v[116:119], v[156:157], off offset:512
	ds_read_b128 v[222:225], v197 offset:41568
	ds_read_b128 v[174:177], v196 offset:4672
	v_mfma_f32_32x32x16_bf16 v[20:35], v[202:205], v[210:213], v[20:35]
	global_load_dwordx4 v[120:123], v[154:155], off offset:512
	ds_read_b128 v[210:213], v196 offset:4704
	ds_read_b128 v[202:205], v196 offset:64
	s_waitcnt lgkmcnt(4)
	v_mfma_f32_32x32x16_bf16 v[52:67], v[178:181], v[214:217], v[52:67]
	global_load_dwordx4 v[124:127], v[152:153], off offset:512
	ds_read_b128 v[218:221], v197 offset:36960
	ds_read_b128 v[178:181], v197 offset:41536
	v_mfma_f32_32x32x16_bf16 v[20:35], v[206:209], v[214:217], v[20:35]
	global_load_dwordx4 v[128:131], v[146:147], off offset:512
	ds_read_b128 v[214:217], v197 offset:36928
	ds_read_b128 v[206:209], v196 offset:96
	s_waitcnt lgkmcnt(1)
	v_mfma_f32_32x32x16_bf16 v[52:67], v[202:205], v[214:217], v[52:67]
	s_waitcnt vmcnt(23)
	ds_write_b128 v167, v[132:135]
	v_mfma_f32_32x32x16_bf16 v[36:51], v[202:205], v[178:181], v[36:51]
	s_waitcnt vmcnt(22)
	ds_write_b128 v167, v[136:139] offset:36864
	v_mfma_f32_32x32x16_bf16 v[20:35], v[174:177], v[214:217], v[20:35]
	s_waitcnt vmcnt(21)
	ds_write_b128 v190, v[140:143]
	v_mfma_f32_32x32x16_bf16 v[4:19], v[174:177], v[178:181], v[4:19]
	s_waitcnt vmcnt(20)
	ds_write_b128 v190, v[198:201] offset:36864
	s_waitcnt lgkmcnt(4)
	v_mfma_f32_32x32x16_bf16 v[52:67], v[206:209], v[218:221], v[52:67]
	s_waitcnt vmcnt(19)
	ds_write_b128 v191, v[226:229]
	v_mfma_f32_32x32x16_bf16 v[36:51], v[206:209], v[222:225], v[36:51]
	s_setprio 0
	s_waitcnt vmcnt(18)
	ds_write_b128 v191, v[230:233] offset:36864
	v_mfma_f32_32x32x16_bf16 v[20:35], v[210:213], v[218:221], v[20:35]
	s_waitcnt vmcnt(17)
	ds_write_b128 v192, v[242:245]
	v_mfma_f32_32x32x16_bf16 v[4:19], v[210:213], v[222:225], v[4:19]
	s_waitcnt vmcnt(16)
	ds_write_b128 v192, v[246:249] offset:36864
	s_waitcnt lgkmcnt(0)
	s_barrier
	s_setprio 1
	ds_read_b128 v[174:177], v194
	ds_read_b128 v[210:213], v195 offset:36864
	ds_read_b128 v[218:221], v195 offset:41472
	ds_read_b128 v[202:205], v194 offset:4608
	ds_read_b128 v[178:181], v194 offset:32
	ds_read_b128 v[222:225], v195 offset:41504
	ds_read_b128 v[206:209], v194 offset:4640
	ds_read_b128 v[214:217], v195 offset:36896
	s_waitcnt lgkmcnt(6)
	v_mfma_f32_32x32x16_bf16 v[52:67], v[174:177], v[210:213], v[52:67]
	global_load_dwordx4 v[132:135], v[164:165], off offset:640
	s_waitcnt lgkmcnt(5)
	v_mfma_f32_32x32x16_bf16 v[36:51], v[174:177], v[218:221], v[36:51]
	global_load_dwordx4 v[136:139], v[162:163], off offset:640
	s_waitcnt lgkmcnt(4)
	v_mfma_f32_32x32x16_bf16 v[4:19], v[202:205], v[218:221], v[4:19]
	global_load_dwordx4 v[140:143], v[160:161], off offset:640
	s_waitcnt lgkmcnt(2)
	v_mfma_f32_32x32x16_bf16 v[36:51], v[178:181], v[222:225], v[36:51]
	global_load_dwordx4 v[198:201], v[158:159], off offset:640
	s_waitcnt lgkmcnt(1)
	v_mfma_f32_32x32x16_bf16 v[4:19], v[206:209], v[222:225], v[4:19]
	global_load_dwordx4 v[226:229], v[156:157], off offset:640
	ds_read_b128 v[222:225], v195 offset:41568
	ds_read_b128 v[174:177], v194 offset:4672
	v_mfma_f32_32x32x16_bf16 v[20:35], v[202:205], v[210:213], v[20:35]
	global_load_dwordx4 v[230:233], v[154:155], off offset:640
	ds_read_b128 v[210:213], v194 offset:4704
	ds_read_b128 v[202:205], v194 offset:64
	s_waitcnt lgkmcnt(4)
	v_mfma_f32_32x32x16_bf16 v[52:67], v[178:181], v[214:217], v[52:67]
	global_load_dwordx4 v[242:245], v[152:153], off offset:640
	ds_read_b128 v[218:221], v195 offset:36960
	ds_read_b128 v[178:181], v195 offset:41536
	v_mfma_f32_32x32x16_bf16 v[20:35], v[206:209], v[214:217], v[20:35]
	global_load_dwordx4 v[246:249], v[146:147], off offset:640
	ds_read_b128 v[214:217], v195 offset:36928
	ds_read_b128 v[206:209], v194 offset:96
	s_waitcnt lgkmcnt(1)
	v_mfma_f32_32x32x16_bf16 v[52:67], v[202:205], v[214:217], v[52:67]
	s_waitcnt vmcnt(23)
	ds_write_b128 v167, v[68:71] offset:18432
	v_mfma_f32_32x32x16_bf16 v[36:51], v[202:205], v[178:181], v[36:51]
	s_waitcnt vmcnt(22)
	ds_write_b128 v167, v[72:75] offset:55296
	v_mfma_f32_32x32x16_bf16 v[20:35], v[174:177], v[214:217], v[20:35]
	s_waitcnt vmcnt(21)
	ds_write_b128 v190, v[76:79] offset:18432
	v_mfma_f32_32x32x16_bf16 v[4:19], v[174:177], v[178:181], v[4:19]
	s_waitcnt vmcnt(20)
	ds_write_b128 v190, v[80:83] offset:55296
	s_waitcnt lgkmcnt(4)
	v_mfma_f32_32x32x16_bf16 v[52:67], v[206:209], v[218:221], v[52:67]
	s_waitcnt vmcnt(19)
	ds_write_b128 v191, v[84:87] offset:18432
	v_mfma_f32_32x32x16_bf16 v[36:51], v[206:209], v[222:225], v[36:51]
	s_setprio 0
	s_waitcnt vmcnt(18)
	ds_write_b128 v191, v[92:95] offset:55296
	v_mfma_f32_32x32x16_bf16 v[20:35], v[210:213], v[218:221], v[20:35]
	s_waitcnt vmcnt(17)
	ds_write_b128 v192, v[104:107] offset:18432
	v_mfma_f32_32x32x16_bf16 v[4:19], v[210:213], v[222:225], v[4:19]
	s_waitcnt vmcnt(16)
	ds_write_b128 v192, v[112:115] offset:55296
	s_waitcnt lgkmcnt(0)
	s_barrier
; template <class Epi, class ColV>
; DI void gemm_tile(const bf16_t* __restrict__ A, int lda, const bf16_t* __restrict__ Bt, int ldb, int K, int m0, int n0, unsigned char* smem, Epi epi, ColV colv, const bf16_t* __restrict__ HYT = nullptr) {
;     ...
;     auto step = [&](int kt, u32x4 (&ldset)[8], const u32x4 (&stset)[8]) {
;         const int buf = kt & 1;
;         if (kt + 2 < nk) gload(ldset, kt + 2);
;         const bf16_t* Ab = As + (buf * 128 + 64 * wr + li) * LS + 8 * lh;
;         const bf16_t* Bb = Bs + (buf * 128 + 64 * wc + li) * LS + 8 * lh;
;         bf16x8 fa[2][2], fb[2][2], ga[2][2], gb[2][2];
; #pragma unroll
;         for (int k2 = 0; k2 < 2; ++k2) { fa[k2][0] = ld8(Ab + 16 * k2); fa[k2][1] = ld8(Ab + 32 * LS + 16 * k2); fb[k2][0] = ld8(Bb + 16 * k2); fb[k2][1] = ld8(Bb + 32 * LS + 16 * k2); }
;         __builtin_amdgcn_sched_barrier(0);
; #pragma unroll
;         for (int k2 = 0; k2 < 2; ++k2) {
;             acc[0][0] = MFMA(fa[k2][0], fb[k2][0], acc[0][0]); acc[0][1] = MFMA(fa[k2][0], fb[k2][1], acc[0][1]);
;             acc[1][0] = MFMA(fa[k2][1], fb[k2][0], acc[1][0]); acc[1][1] = MFMA(fa[k2][1], fb[k2][1], acc[1][1]);
;         }
; #pragma unroll
;         for (int k2 = 0; k2 < 2; ++k2) { const int ks = 2 + k2; ga[k2][0] = ld8(Ab + 16 * ks); ga[k2][1] = ld8(Ab + 32 * LS + 16 * ks); gb[k2][0] = ld8(Bb + 16 * ks); gb[k2][1] = ld8(Bb + 32 * LS + 16 * ks); }
; #pragma unroll
;         for (int k2 = 0; k2 < 2; ++k2) {
;             acc[0][0] = MFMA(ga[k2][0], gb[k2][0], acc[0][0]); acc[0][1] = MFMA(ga[k2][0], gb[k2][1], acc[0][1]);
;             acc[1][0] = MFMA(ga[k2][1], gb[k2][0], acc[1][0]); acc[1][1] = MFMA(ga[k2][1], gb[k2][1], acc[1][1]);
;         }
;         if (kt + 1 < nk) sstore(stset, buf ^ 1, kt + 1);
; #pragma unroll
;         for (int i = 0; i < 8; ++i) { __builtin_amdgcn_sched_group_barrier(0x008, 1, 0); __builtin_amdgcn_sched_group_barrier(0x100, 1, 0); }
; #pragma unroll
;         for (int i = 0; i < 8; ++i) { __builtin_amdgcn_sched_group_barrier(0x008, 1, 0); __builtin_amdgcn_sched_group_barrier(0x200, 1, 0); }
;         __builtin_amdgcn_sched_barrier(0);
;         __syncthreads();
;     };
;     ...
;         XCD_TILE_LOOP((layer == 0 ? NT : NL) / 128, 32, tm, tn) gemm_tile((const bf16_t*)(p.ws + WS_H), 1024, (const bf16_t*)(p.ws + wbase(layer) + W_FF1), 1024, 1024, tm * 128, tn * 128, smem, epi, nocol);
	s_setprio 1
	ds_read_b128 v[174:177], v196
	ds_read_b128 v[210:213], v197 offset:36864
	ds_read_b128 v[218:221], v197 offset:41472
	ds_read_b128 v[202:205], v196 offset:4608
	ds_read_b128 v[178:181], v196 offset:32
	ds_read_b128 v[222:225], v197 offset:41504
	ds_read_b128 v[206:209], v196 offset:4640
	ds_read_b128 v[214:217], v197 offset:36896
	s_waitcnt lgkmcnt(6)
	v_mfma_f32_32x32x16_bf16 v[52:67], v[174:177], v[210:213], v[52:67]
	global_load_dwordx4 v[68:71], v[164:165], off offset:768
	s_waitcnt lgkmcnt(5)
	v_mfma_f32_32x32x16_bf16 v[36:51], v[174:177], v[218:221], v[36:51]
	global_load_dwordx4 v[72:75], v[162:163], off offset:768
	s_waitcnt lgkmcnt(4)
	v_mfma_f32_32x32x16_bf16 v[4:19], v[202:205], v[218:221], v[4:19]
	global_load_dwordx4 v[76:79], v[160:161], off offset:768
	s_waitcnt lgkmcnt(2)
	v_mfma_f32_32x32x16_bf16 v[36:51], v[178:181], v[222:225], v[36:51]
	global_load_dwordx4 v[80:83], v[158:159], off offset:768
	s_waitcnt lgkmcnt(1)
	v_mfma_f32_32x32x16_bf16 v[4:19], v[206:209], v[222:225], v[4:19]
	global_load_dwordx4 v[84:87], v[156:157], off offset:768
	ds_read_b128 v[222:225], v197 offset:41568
	ds_read_b128 v[174:177], v196 offset:4672
	v_mfma_f32_32x32x16_bf16 v[20:35], v[202:205], v[210:213], v[20:35]
	global_load_dwordx4 v[92:95], v[154:155], off offset:768
	ds_read_b128 v[210:213], v196 offset:4704
	ds_read_b128 v[202:205], v196 offset:64
	s_waitcnt lgkmcnt(4)
	v_mfma_f32_32x32x16_bf16 v[52:67], v[178:181], v[214:217], v[52:67]
	global_load_dwordx4 v[104:107], v[152:153], off offset:768
	ds_read_b128 v[218:221], v197 offset:36960
	ds_read_b128 v[178:181], v197 offset:41536
	v_mfma_f32_32x32x16_bf16 v[20:35], v[206:209], v[214:217], v[20:35]
	global_load_dwordx4 v[112:115], v[146:147], off offset:768
	ds_read_b128 v[214:217], v197 offset:36928
	ds_read_b128 v[206:209], v196 offset:96
	s_waitcnt lgkmcnt(1)
	v_mfma_f32_32x32x16_bf16 v[52:67], v[202:205], v[214:217], v[52:67]
	s_waitcnt vmcnt(23)
	ds_write_b128 v167, v[88:91]
	v_mfma_f32_32x32x16_bf16 v[36:51], v[202:205], v[178:181], v[36:51]
	s_waitcnt vmcnt(22)
	ds_write_b128 v167, v[96:99] offset:36864
	v_mfma_f32_32x32x16_bf16 v[20:35], v[174:177], v[214:217], v[20:35]
	s_waitcnt vmcnt(21)
	ds_write_b128 v190, v[100:103]
	v_mfma_f32_32x32x16_bf16 v[4:19], v[174:177], v[178:181], v[4:19]
	s_waitcnt vmcnt(20)
	ds_write_b128 v190, v[108:111] offset:36864
	s_waitcnt lgkmcnt(4)
	v_mfma_f32_32x32x16_bf16 v[52:67], v[206:209], v[218:221], v[52:67]
	s_waitcnt vmcnt(19)
	ds_write_b128 v191, v[116:119]
	v_mfma_f32_32x32x16_bf16 v[36:51], v[206:209], v[222:225], v[36:51]
	s_setprio 0
	s_waitcnt vmcnt(18)
	ds_write_b128 v191, v[120:123] offset:36864
	v_mfma_f32_32x32x16_bf16 v[20:35], v[210:213], v[218:221], v[20:35]
	s_waitcnt vmcnt(17)
	ds_write_b128 v192, v[124:127]
	v_mfma_f32_32x32x16_bf16 v[4:19], v[210:213], v[222:225], v[4:19]
	s_waitcnt vmcnt(16)
	ds_write_b128 v192, v[128:131] offset:36864
	s_waitcnt lgkmcnt(0)
	s_barrier
	s_setprio 1
	ds_read_b128 v[174:177], v194
	ds_read_b128 v[210:213], v195 offset:36864
	ds_read_b128 v[218:221], v195 offset:41472
	ds_read_b128 v[202:205], v194 offset:4608
	ds_read_b128 v[178:181], v194 offset:32
	ds_read_b128 v[222:225], v195 offset:41504
	ds_read_b128 v[206:209], v194 offset:4640
	ds_read_b128 v[214:217], v195 offset:36896
	s_waitcnt lgkmcnt(6)
	v_mfma_f32_32x32x16_bf16 v[52:67], v[174:177], v[210:213], v[52:67]
	global_load_dwordx4 v[88:91], v[164:165], off offset:896
	s_waitcnt lgkmcnt(5)
	v_mfma_f32_32x32x16_bf16 v[36:51], v[174:177], v[218:221], v[36:51]
	global_load_dwordx4 v[96:99], v[162:163], off offset:896
	s_waitcnt lgkmcnt(4)
	v_mfma_f32_32x32x16_bf16 v[4:19], v[202:205], v[218:221], v[4:19]
	global_load_dwordx4 v[100:103], v[160:161], off offset:896
	s_waitcnt lgkmcnt(2)
	v_mfma_f32_32x32x16_bf16 v[36:51], v[178:181], v[222:225], v[36:51]
	global_load_dwordx4 v[108:111], v[158:159], off offset:896
	s_waitcnt lgkmcnt(1)
	v_mfma_f32_32x32x16_bf16 v[4:19], v[206:209], v[222:225], v[4:19]
	global_load_dwordx4 v[116:119], v[156:157], off offset:896
	ds_read_b128 v[222:225], v195 offset:41568
	ds_read_b128 v[174:177], v194 offset:4672
	v_mfma_f32_32x32x16_bf16 v[20:35], v[202:205], v[210:213], v[20:35]
	global_load_dwordx4 v[120:123], v[154:155], off offset:896
	ds_read_b128 v[210:213], v194 offset:4704
	ds_read_b128 v[202:205], v194 offset:64
	s_waitcnt lgkmcnt(4)
	v_mfma_f32_32x32x16_bf16 v[52:67], v[178:181], v[214:217], v[52:67]
	global_load_dwordx4 v[124:127], v[152:153], off offset:896
	ds_read_b128 v[218:221], v195 offset:36960
	ds_read_b128 v[178:181], v195 offset:41536
	v_mfma_f32_32x32x16_bf16 v[20:35], v[206:209], v[214:217], v[20:35]
	global_load_dwordx4 v[128:131], v[146:147], off offset:896
	ds_read_b128 v[214:217], v195 offset:36928
	ds_read_b128 v[206:209], v194 offset:96
	s_waitcnt lgkmcnt(1)
	v_mfma_f32_32x32x16_bf16 v[52:67], v[202:205], v[214:217], v[52:67]
	s_waitcnt vmcnt(23)
	ds_write_b128 v167, v[132:135] offset:18432
	v_mfma_f32_32x32x16_bf16 v[36:51], v[202:205], v[178:181], v[36:51]
	s_waitcnt vmcnt(22)
	ds_write_b128 v167, v[136:139] offset:55296
	v_mfma_f32_32x32x16_bf16 v[20:35], v[174:177], v[214:217], v[20:35]
	s_waitcnt vmcnt(21)
	ds_write_b128 v190, v[140:143] offset:18432
	v_mfma_f32_32x32x16_bf16 v[4:19], v[174:177], v[178:181], v[4:19]
	s_waitcnt vmcnt(20)
	ds_write_b128 v190, v[198:201] offset:55296
	s_waitcnt lgkmcnt(4)
	v_mfma_f32_32x32x16_bf16 v[52:67], v[206:209], v[218:221], v[52:67]
	s_waitcnt vmcnt(19)
	ds_write_b128 v191, v[226:229] offset:18432
	v_mfma_f32_32x32x16_bf16 v[36:51], v[206:209], v[222:225], v[36:51]
	s_setprio 0
	s_waitcnt vmcnt(18)
	ds_write_b128 v191, v[230:233] offset:55296
	v_mfma_f32_32x32x16_bf16 v[20:35], v[210:213], v[218:221], v[20:35]
	s_waitcnt vmcnt(17)
	ds_write_b128 v192, v[242:245] offset:18432
	v_mfma_f32_32x32x16_bf16 v[4:19], v[210:213], v[222:225], v[4:19]
	s_waitcnt vmcnt(16)
	ds_write_b128 v192, v[246:249] offset:55296
	s_waitcnt lgkmcnt(0)
	s_barrier
; template <class Epi, class ColV>
; DI void gemm_tile(const bf16_t* __restrict__ A, int lda, const bf16_t* __restrict__ Bt, int ldb, int K, int m0, int n0, unsigned char* smem, Epi epi, ColV colv, const bf16_t* __restrict__ HYT = nullptr) {
;     ...
;     auto step = [&](int kt, u32x4 (&ldset)[8], const u32x4 (&stset)[8]) {
;         const int buf = kt & 1;
;         if (kt + 2 < nk) gload(ldset, kt + 2);
;         const bf16_t* Ab = As + (buf * 128 + 64 * wr + li) * LS + 8 * lh;
;         const bf16_t* Bb = Bs + (buf * 128 + 64 * wc + li) * LS + 8 * lh;
;         bf16x8 fa[2][2], fb[2][2], ga[2][2], gb[2][2];
; #pragma unroll
;         for (int k2 = 0; k2 < 2; ++k2) { fa[k2][0] = ld8(Ab + 16 * k2); fa[k2][1] = ld8(Ab + 32 * LS + 16 * k2); fb[k2][0] = ld8(Bb + 16 * k2); fb[k2][1] = ld8(Bb + 32 * LS + 16 * k2); }
;         __builtin_amdgcn_sched_barrier(0);
; #pragma unroll
;         for (int k2 = 0; k2 < 2; ++k2) {
;             acc[0][0] = MFMA(fa[k2][0], fb[k2][0], acc[0][0]); acc[0][1] = MFMA(fa[k2][0], fb[k2][1], acc[0][1]);
;             acc[1][0] = MFMA(fa[k2][1], fb[k2][0], acc[1][0]); acc[1][1] = MFMA(fa[k2][1], fb[k2][1], acc[1][1]);
;         }
; #pragma unroll
;         for (int k2 = 0; k2 < 2; ++k2) { const int ks = 2 + k2; ga[k2][0] = ld8(Ab + 16 * ks); ga[k2][1] = ld8(Ab + 32 * LS + 16 * ks); gb[k2][0] = ld8(Bb + 16 * ks); gb[k2][1] = ld8(Bb + 32 * LS + 16 * ks); }
; #pragma unroll
;         for (int k2 = 0; k2 < 2; ++k2) {
;             acc[0][0] = MFMA(ga[k2][0], gb[k2][0], acc[0][0]); acc[0][1] = MFMA(ga[k2][0], gb[k2][1], acc[0][1]);
;             acc[1][0] = MFMA(ga[k2][1], gb[k2][0], acc[1][0]); acc[1][1] = MFMA(ga[k2][1], gb[k2][1], acc[1][1]);
;         }
;         if (kt + 1 < nk) sstore(stset, buf ^ 1, kt + 1);
; #pragma unroll
;         for (int i = 0; i < 8; ++i) { __builtin_amdgcn_sched_group_barrier(0x008, 1, 0); __builtin_amdgcn_sched_group_barrier(0x100, 1, 0); }
; #pragma unroll
;         for (int i = 0; i < 8; ++i) { __builtin_amdgcn_sched_group_barrier(0x008, 1, 0); __builtin_amdgcn_sched_group_barrier(0x200, 1, 0); }
;         __builtin_amdgcn_sched_barrier(0);
;         __syncthreads();
;     };
;     ...
;         XCD_TILE_LOOP((layer == 0 ? NT : NL) / 128, 32, tm, tn) gemm_tile((const bf16_t*)(p.ws + WS_H), 1024, (const bf16_t*)(p.ws + wbase(layer) + W_FF1), 1024, 1024, tm * 128, tn * 128, smem, epi, nocol);
	s_setprio 1
	ds_read_b128 v[174:177], v196
	ds_read_b128 v[210:213], v197 offset:36864
	ds_read_b128 v[218:221], v197 offset:41472
	ds_read_b128 v[202:205], v196 offset:4608
	ds_read_b128 v[178:181], v196 offset:32
	ds_read_b128 v[222:225], v197 offset:41504
	ds_read_b128 v[206:209], v196 offset:4640
	ds_read_b128 v[214:217], v197 offset:36896
	s_waitcnt lgkmcnt(6)
	v_mfma_f32_32x32x16_bf16 v[52:67], v[174:177], v[210:213], v[52:67]
	global_load_dwordx4 v[132:135], v[164:165], off offset:1024
	s_waitcnt lgkmcnt(5)
	v_mfma_f32_32x32x16_bf16 v[36:51], v[174:177], v[218:221], v[36:51]
	global_load_dwordx4 v[136:139], v[162:163], off offset:1024
	s_waitcnt lgkmcnt(4)
	v_mfma_f32_32x32x16_bf16 v[4:19], v[202:205], v[218:221], v[4:19]
	global_load_dwordx4 v[140:143], v[160:161], off offset:1024
	s_waitcnt lgkmcnt(2)
	v_mfma_f32_32x32x16_bf16 v[36:51], v[178:181], v[222:225], v[36:51]
	global_load_dwordx4 v[198:201], v[158:159], off offset:1024
	s_waitcnt lgkmcnt(1)
	v_mfma_f32_32x32x16_bf16 v[4:19], v[206:209], v[222:225], v[4:19]
	global_load_dwordx4 v[226:229], v[156:157], off offset:1024
	ds_read_b128 v[222:225], v197 offset:41568
	ds_read_b128 v[174:177], v196 offset:4672
	v_mfma_f32_32x32x16_bf16 v[20:35], v[202:205], v[210:213], v[20:35]
	global_load_dwordx4 v[230:233], v[154:155], off offset:1024
	ds_read_b128 v[210:213], v196 offset:4704
	ds_read_b128 v[202:205], v196 offset:64
	s_waitcnt lgkmcnt(4)
	v_mfma_f32_32x32x16_bf16 v[52:67], v[178:181], v[214:217], v[52:67]
	global_load_dwordx4 v[242:245], v[152:153], off offset:1024
	ds_read_b128 v[218:221], v197 offset:36960
	ds_read_b128 v[178:181], v197 offset:41536
	v_mfma_f32_32x32x16_bf16 v[20:35], v[206:209], v[214:217], v[20:35]
	global_load_dwordx4 v[246:249], v[146:147], off offset:1024
	ds_read_b128 v[214:217], v197 offset:36928
	ds_read_b128 v[206:209], v196 offset:96
	s_waitcnt lgkmcnt(1)
	v_mfma_f32_32x32x16_bf16 v[52:67], v[202:205], v[214:217], v[52:67]
	s_waitcnt vmcnt(23)
	ds_write_b128 v167, v[68:71]
	v_mfma_f32_32x32x16_bf16 v[36:51], v[202:205], v[178:181], v[36:51]
	s_waitcnt vmcnt(22)
	ds_write_b128 v167, v[72:75] offset:36864
	v_mfma_f32_32x32x16_bf16 v[20:35], v[174:177], v[214:217], v[20:35]
	s_waitcnt vmcnt(21)
	ds_write_b128 v190, v[76:79]
	v_mfma_f32_32x32x16_bf16 v[4:19], v[174:177], v[178:181], v[4:19]
	s_waitcnt vmcnt(20)
	ds_write_b128 v190, v[80:83] offset:36864
	s_waitcnt lgkmcnt(4)
	v_mfma_f32_32x32x16_bf16 v[52:67], v[206:209], v[218:221], v[52:67]
	s_waitcnt vmcnt(19)
	ds_write_b128 v191, v[84:87]
	v_mfma_f32_32x32x16_bf16 v[36:51], v[206:209], v[222:225], v[36:51]
	s_setprio 0
	s_waitcnt vmcnt(18)
	ds_write_b128 v191, v[92:95] offset:36864
	v_mfma_f32_32x32x16_bf16 v[20:35], v[210:213], v[218:221], v[20:35]
	s_waitcnt vmcnt(17)
	ds_write_b128 v192, v[104:107]
	v_mfma_f32_32x32x16_bf16 v[4:19], v[210:213], v[222:225], v[4:19]
	s_waitcnt vmcnt(16)
	ds_write_b128 v192, v[112:115] offset:36864
	s_waitcnt lgkmcnt(0)
	s_barrier
	s_setprio 1
	ds_read_b128 v[174:177], v194
	ds_read_b128 v[210:213], v195 offset:36864
	ds_read_b128 v[218:221], v195 offset:41472
	ds_read_b128 v[202:205], v194 offset:4608
	ds_read_b128 v[178:181], v194 offset:32
	ds_read_b128 v[222:225], v195 offset:41504
	ds_read_b128 v[206:209], v194 offset:4640
	ds_read_b128 v[214:217], v195 offset:36896
	s_waitcnt lgkmcnt(6)
	v_mfma_f32_32x32x16_bf16 v[52:67], v[174:177], v[210:213], v[52:67]
	global_load_dwordx4 v[68:71], v[164:165], off offset:1152
	s_waitcnt lgkmcnt(5)
	v_mfma_f32_32x32x16_bf16 v[36:51], v[174:177], v[218:221], v[36:51]
	global_load_dwordx4 v[72:75], v[162:163], off offset:1152
	s_waitcnt lgkmcnt(4)
	v_mfma_f32_32x32x16_bf16 v[4:19], v[202:205], v[218:221], v[4:19]
	global_load_dwordx4 v[76:79], v[160:161], off offset:1152
	s_waitcnt lgkmcnt(2)
	v_mfma_f32_32x32x16_bf16 v[36:51], v[178:181], v[222:225], v[36:51]
	global_load_dwordx4 v[80:83], v[158:159], off offset:1152
	s_waitcnt lgkmcnt(1)
	v_mfma_f32_32x32x16_bf16 v[4:19], v[206:209], v[222:225], v[4:19]
	global_load_dwordx4 v[84:87], v[156:157], off offset:1152
	ds_read_b128 v[222:225], v195 offset:41568
	ds_read_b128 v[174:177], v194 offset:4672
	v_mfma_f32_32x32x16_bf16 v[20:35], v[202:205], v[210:213], v[20:35]
	global_load_dwordx4 v[92:95], v[154:155], off offset:1152
	ds_read_b128 v[210:213], v194 offset:4704
	ds_read_b128 v[202:205], v194 offset:64
	s_waitcnt lgkmcnt(4)
	v_mfma_f32_32x32x16_bf16 v[52:67], v[178:181], v[214:217], v[52:67]
	global_load_dwordx4 v[104:107], v[152:153], off offset:1152
	ds_read_b128 v[218:221], v195 offset:36960
	ds_read_b128 v[178:181], v195 offset:41536
	v_mfma_f32_32x32x16_bf16 v[20:35], v[206:209], v[214:217], v[20:35]
	global_load_dwordx4 v[112:115], v[146:147], off offset:1152
	ds_read_b128 v[214:217], v195 offset:36928
	ds_read_b128 v[206:209], v194 offset:96
	s_waitcnt lgkmcnt(1)
	v_mfma_f32_32x32x16_bf16 v[52:67], v[202:205], v[214:217], v[52:67]
	s_waitcnt vmcnt(23)
	ds_write_b128 v167, v[88:91] offset:18432
	v_mfma_f32_32x32x16_bf16 v[36:51], v[202:205], v[178:181], v[36:51]
	s_waitcnt vmcnt(22)
	ds_write_b128 v167, v[96:99] offset:55296
	v_mfma_f32_32x32x16_bf16 v[20:35], v[174:177], v[214:217], v[20:35]
	s_waitcnt vmcnt(21)
	ds_write_b128 v190, v[100:103] offset:18432
	v_mfma_f32_32x32x16_bf16 v[4:19], v[174:177], v[178:181], v[4:19]
	s_waitcnt vmcnt(20)
	ds_write_b128 v190, v[108:111] offset:55296
	s_waitcnt lgkmcnt(4)
	v_mfma_f32_32x32x16_bf16 v[52:67], v[206:209], v[218:221], v[52:67]
	s_waitcnt vmcnt(19)
	ds_write_b128 v191, v[116:119] offset:18432
	v_mfma_f32_32x32x16_bf16 v[36:51], v[206:209], v[222:225], v[36:51]
	s_setprio 0
	s_waitcnt vmcnt(18)
	ds_write_b128 v191, v[120:123] offset:55296
	v_mfma_f32_32x32x16_bf16 v[20:35], v[210:213], v[218:221], v[20:35]
	s_waitcnt vmcnt(17)
	ds_write_b128 v192, v[124:127] offset:18432
	v_mfma_f32_32x32x16_bf16 v[4:19], v[210:213], v[222:225], v[4:19]
	s_waitcnt vmcnt(16)
	ds_write_b128 v192, v[128:131] offset:55296
	s_waitcnt lgkmcnt(0)
	s_barrier
; template <class Epi, class ColV>
; DI void gemm_tile(const bf16_t* __restrict__ A, int lda, const bf16_t* __restrict__ Bt, int ldb, int K, int m0, int n0, unsigned char* smem, Epi epi, ColV colv, const bf16_t* __restrict__ HYT = nullptr) {
;     ...
;     auto step = [&](int kt, u32x4 (&ldset)[8], const u32x4 (&stset)[8]) {
;         const int buf = kt & 1;
;         if (kt + 2 < nk) gload(ldset, kt + 2);
;         const bf16_t* Ab = As + (buf * 128 + 64 * wr + li) * LS + 8 * lh;
;         const bf16_t* Bb = Bs + (buf * 128 + 64 * wc + li) * LS + 8 * lh;
;         bf16x8 fa[2][2], fb[2][2], ga[2][2], gb[2][2];
; #pragma unroll
;         for (int k2 = 0; k2 < 2; ++k2) { fa[k2][0] = ld8(Ab + 16 * k2); fa[k2][1] = ld8(Ab + 32 * LS + 16 * k2); fb[k2][0] = ld8(Bb + 16 * k2); fb[k2][1] = ld8(Bb + 32 * LS + 16 * k2); }
;         __builtin_amdgcn_sched_barrier(0);
; #pragma unroll
;         for (int k2 = 0; k2 < 2; ++k2) {
;             acc[0][0] = MFMA(fa[k2][0], fb[k2][0], acc[0][0]); acc[0][1] = MFMA(fa[k2][0], fb[k2][1], acc[0][1]);
;             acc[1][0] = MFMA(fa[k2][1], fb[k2][0], acc[1][0]); acc[1][1] = MFMA(fa[k2][1], fb[k2][1], acc[1][1]);
;         }
; #pragma unroll
;         for (int k2 = 0; k2 < 2; ++k2) { const int ks = 2 + k2; ga[k2][0] = ld8(Ab + 16 * ks); ga[k2][1] = ld8(Ab + 32 * LS + 16 * ks); gb[k2][0] = ld8(Bb + 16 * ks); gb[k2][1] = ld8(Bb + 32 * LS + 16 * ks); }
; #pragma unroll
;         for (int k2 = 0; k2 < 2; ++k2) {
;             acc[0][0] = MFMA(ga[k2][0], gb[k2][0], acc[0][0]); acc[0][1] = MFMA(ga[k2][0], gb[k2][1], acc[0][1]);
;             acc[1][0] = MFMA(ga[k2][1], gb[k2][0], acc[1][0]); acc[1][1] = MFMA(ga[k2][1], gb[k2][1], acc[1][1]);
;         }
;         if (kt + 1 < nk) sstore(stset, buf ^ 1, kt + 1);
; #pragma unroll
;         for (int i = 0; i < 8; ++i) { __builtin_amdgcn_sched_group_barrier(0x008, 1, 0); __builtin_amdgcn_sched_group_barrier(0x100, 1, 0); }
; #pragma unroll
;         for (int i = 0; i < 8; ++i) { __builtin_amdgcn_sched_group_barrier(0x008, 1, 0); __builtin_amdgcn_sched_group_barrier(0x200, 1, 0); }
;         __builtin_amdgcn_sched_barrier(0);
;         __syncthreads();
;     };
;     ...
;         XCD_TILE_LOOP((layer == 0 ? NT : NL) / 128, 32, tm, tn) gemm_tile((const bf16_t*)(p.ws + WS_H), 1024, (const bf16_t*)(p.ws + wbase(layer) + W_FF1), 1024, 1024, tm * 128, tn * 128, smem, epi, nocol);
	s_setprio 1
	ds_read_b128 v[174:177], v196
	ds_read_b128 v[210:213], v197 offset:36864
	ds_read_b128 v[218:221], v197 offset:41472
	ds_read_b128 v[202:205], v196 offset:4608
	ds_read_b128 v[178:181], v196 offset:32
	ds_read_b128 v[222:225], v197 offset:41504
	ds_read_b128 v[206:209], v196 offset:4640
	ds_read_b128 v[214:217], v197 offset:36896
	s_waitcnt lgkmcnt(6)
	v_mfma_f32_32x32x16_bf16 v[52:67], v[174:177], v[210:213], v[52:67]
	global_load_dwordx4 v[88:91], v[164:165], off offset:1280
	s_waitcnt lgkmcnt(5)
	v_mfma_f32_32x32x16_bf16 v[36:51], v[174:177], v[218:221], v[36:51]
	global_load_dwordx4 v[96:99], v[162:163], off offset:1280
	s_waitcnt lgkmcnt(4)
	v_mfma_f32_32x32x16_bf16 v[4:19], v[202:205], v[218:221], v[4:19]
	global_load_dwordx4 v[100:103], v[160:161], off offset:1280
	s_waitcnt lgkmcnt(2)
	v_mfma_f32_32x32x16_bf16 v[36:51], v[178:181], v[222:225], v[36:51]
	global_load_dwordx4 v[108:111], v[158:159], off offset:1280
	s_waitcnt lgkmcnt(1)
	v_mfma_f32_32x32x16_bf16 v[4:19], v[206:209], v[222:225], v[4:19]
	global_load_dwordx4 v[116:119], v[156:157], off offset:1280
	ds_read_b128 v[222:225], v197 offset:41568
	ds_read_b128 v[174:177], v196 offset:4672
	v_mfma_f32_32x32x16_bf16 v[20:35], v[202:205], v[210:213], v[20:35]
	global_load_dwordx4 v[120:123], v[154:155], off offset:1280
	ds_read_b128 v[210:213], v196 offset:4704
	ds_read_b128 v[202:205], v196 offset:64
	s_waitcnt lgkmcnt(4)
	v_mfma_f32_32x32x16_bf16 v[52:67], v[178:181], v[214:217], v[52:67]
	global_load_dwordx4 v[124:127], v[152:153], off offset:1280
	ds_read_b128 v[218:221], v197 offset:36960
	ds_read_b128 v[178:181], v197 offset:41536
	v_mfma_f32_32x32x16_bf16 v[20:35], v[206:209], v[214:217], v[20:35]
	global_load_dwordx4 v[128:131], v[146:147], off offset:1280
	ds_read_b128 v[214:217], v197 offset:36928
	ds_read_b128 v[206:209], v196 offset:96
	s_waitcnt lgkmcnt(1)
	v_mfma_f32_32x32x16_bf16 v[52:67], v[202:205], v[214:217], v[52:67]
	s_waitcnt vmcnt(23)
	ds_write_b128 v167, v[132:135]
	v_mfma_f32_32x32x16_bf16 v[36:51], v[202:205], v[178:181], v[36:51]
	s_waitcnt vmcnt(22)
	ds_write_b128 v167, v[136:139] offset:36864
	v_mfma_f32_32x32x16_bf16 v[20:35], v[174:177], v[214:217], v[20:35]
	s_waitcnt vmcnt(21)
	ds_write_b128 v190, v[140:143]
	v_mfma_f32_32x32x16_bf16 v[4:19], v[174:177], v[178:181], v[4:19]
	s_waitcnt vmcnt(20)
	ds_write_b128 v190, v[198:201] offset:36864
	s_waitcnt lgkmcnt(4)
	v_mfma_f32_32x32x16_bf16 v[52:67], v[206:209], v[218:221], v[52:67]
	s_waitcnt vmcnt(19)
	ds_write_b128 v191, v[226:229]
	v_mfma_f32_32x32x16_bf16 v[36:51], v[206:209], v[222:225], v[36:51]
	s_setprio 0
	s_waitcnt vmcnt(18)
	ds_write_b128 v191, v[230:233] offset:36864
	v_mfma_f32_32x32x16_bf16 v[20:35], v[210:213], v[218:221], v[20:35]
	s_waitcnt vmcnt(17)
	ds_write_b128 v192, v[242:245]
	v_mfma_f32_32x32x16_bf16 v[4:19], v[210:213], v[222:225], v[4:19]
	s_waitcnt vmcnt(16)
	ds_write_b128 v192, v[246:249] offset:36864
	s_waitcnt lgkmcnt(0)
	s_barrier
	s_setprio 1
	ds_read_b128 v[174:177], v194
	ds_read_b128 v[210:213], v195 offset:36864
	ds_read_b128 v[218:221], v195 offset:41472
	ds_read_b128 v[202:205], v194 offset:4608
	ds_read_b128 v[178:181], v194 offset:32
	ds_read_b128 v[222:225], v195 offset:41504
	ds_read_b128 v[206:209], v194 offset:4640
	ds_read_b128 v[214:217], v195 offset:36896
	s_waitcnt lgkmcnt(6)
	v_mfma_f32_32x32x16_bf16 v[52:67], v[174:177], v[210:213], v[52:67]
	global_load_dwordx4 v[132:135], v[164:165], off offset:1408
	s_waitcnt lgkmcnt(5)
	v_mfma_f32_32x32x16_bf16 v[36:51], v[174:177], v[218:221], v[36:51]
	global_load_dwordx4 v[136:139], v[162:163], off offset:1408
	s_waitcnt lgkmcnt(4)
	v_mfma_f32_32x32x16_bf16 v[4:19], v[202:205], v[218:221], v[4:19]
	global_load_dwordx4 v[140:143], v[160:161], off offset:1408
	s_waitcnt lgkmcnt(2)
	v_mfma_f32_32x32x16_bf16 v[36:51], v[178:181], v[222:225], v[36:51]
	global_load_dwordx4 v[198:201], v[158:159], off offset:1408
	s_waitcnt lgkmcnt(1)
	v_mfma_f32_32x32x16_bf16 v[4:19], v[206:209], v[222:225], v[4:19]
	global_load_dwordx4 v[226:229], v[156:157], off offset:1408
	ds_read_b128 v[222:225], v195 offset:41568
	ds_read_b128 v[174:177], v194 offset:4672
	v_mfma_f32_32x32x16_bf16 v[20:35], v[202:205], v[210:213], v[20:35]
	global_load_dwordx4 v[230:233], v[154:155], off offset:1408
	ds_read_b128 v[210:213], v194 offset:4704
	ds_read_b128 v[202:205], v194 offset:64
	s_waitcnt lgkmcnt(4)
	v_mfma_f32_32x32x16_bf16 v[52:67], v[178:181], v[214:217], v[52:67]
	global_load_dwordx4 v[242:245], v[152:153], off offset:1408
	ds_read_b128 v[218:221], v195 offset:36960
	ds_read_b128 v[178:181], v195 offset:41536
	v_mfma_f32_32x32x16_bf16 v[20:35], v[206:209], v[214:217], v[20:35]
	global_load_dwordx4 v[246:249], v[146:147], off offset:1408
	ds_read_b128 v[214:217], v195 offset:36928
	ds_read_b128 v[206:209], v194 offset:96
	s_waitcnt lgkmcnt(1)
	v_mfma_f32_32x32x16_bf16 v[52:67], v[202:205], v[214:217], v[52:67]
	s_waitcnt vmcnt(23)
	ds_write_b128 v167, v[68:71] offset:18432
	v_mfma_f32_32x32x16_bf16 v[36:51], v[202:205], v[178:181], v[36:51]
	s_waitcnt vmcnt(22)
	ds_write_b128 v167, v[72:75] offset:55296
	v_mfma_f32_32x32x16_bf16 v[20:35], v[174:177], v[214:217], v[20:35]
	s_waitcnt vmcnt(21)
	ds_write_b128 v190, v[76:79] offset:18432
	v_mfma_f32_32x32x16_bf16 v[4:19], v[174:177], v[178:181], v[4:19]
	s_waitcnt vmcnt(20)
	ds_write_b128 v190, v[80:83] offset:55296
	s_waitcnt lgkmcnt(4)
	v_mfma_f32_32x32x16_bf16 v[52:67], v[206:209], v[218:221], v[52:67]
	s_waitcnt vmcnt(19)
	ds_write_b128 v191, v[84:87] offset:18432
	v_mfma_f32_32x32x16_bf16 v[36:51], v[206:209], v[222:225], v[36:51]
	s_setprio 0
	s_waitcnt vmcnt(18)
	ds_write_b128 v191, v[92:95] offset:55296
	v_mfma_f32_32x32x16_bf16 v[20:35], v[210:213], v[218:221], v[20:35]
	s_waitcnt vmcnt(17)
	ds_write_b128 v192, v[104:107] offset:18432
	v_mfma_f32_32x32x16_bf16 v[4:19], v[210:213], v[222:225], v[4:19]
	s_waitcnt vmcnt(16)
	ds_write_b128 v192, v[112:115] offset:55296
	s_waitcnt lgkmcnt(0)
	s_barrier
; template <class Epi, class ColV>
; DI void gemm_tile(const bf16_t* __restrict__ A, int lda, const bf16_t* __restrict__ Bt, int ldb, int K, int m0, int n0, unsigned char* smem, Epi epi, ColV colv, const bf16_t* __restrict__ HYT = nullptr) {
;     ...
;     auto step = [&](int kt, u32x4 (&ldset)[8], const u32x4 (&stset)[8]) {
;         const int buf = kt & 1;
;         if (kt + 2 < nk) gload(ldset, kt + 2);
;         const bf16_t* Ab = As + (buf * 128 + 64 * wr + li) * LS + 8 * lh;
;         const bf16_t* Bb = Bs + (buf * 128 + 64 * wc + li) * LS + 8 * lh;
;         bf16x8 fa[2][2], fb[2][2], ga[2][2], gb[2][2];
; #pragma unroll
;         for (int k2 = 0; k2 < 2; ++k2) { fa[k2][0] = ld8(Ab + 16 * k2); fa[k2][1] = ld8(Ab + 32 * LS + 16 * k2); fb[k2][0] = ld8(Bb + 16 * k2); fb[k2][1] = ld8(Bb + 32 * LS + 16 * k2); }
;         __builtin_amdgcn_sched_barrier(0);
; #pragma unroll
;         for (int k2 = 0; k2 < 2; ++k2) {
;             acc[0][0] = MFMA(fa[k2][0], fb[k2][0], acc[0][0]); acc[0][1] = MFMA(fa[k2][0], fb[k2][1], acc[0][1]);
;             acc[1][0] = MFMA(fa[k2][1], fb[k2][0], acc[1][0]); acc[1][1] = MFMA(fa[k2][1], fb[k2][1], acc[1][1]);
;         }
; #pragma unroll
;         for (int k2 = 0; k2 < 2; ++k2) { const int ks = 2 + k2; ga[k2][0] = ld8(Ab + 16 * ks); ga[k2][1] = ld8(Ab + 32 * LS + 16 * ks); gb[k2][0] = ld8(Bb + 16 * ks); gb[k2][1] = ld8(Bb + 32 * LS + 16 * ks); }
; #pragma unroll
;         for (int k2 = 0; k2 < 2; ++k2) {
;             acc[0][0] = MFMA(ga[k2][0], gb[k2][0], acc[0][0]); acc[0][1] = MFMA(ga[k2][0], gb[k2][1], acc[0][1]);
;             acc[1][0] = MFMA(ga[k2][1], gb[k2][0], acc[1][0]); acc[1][1] = MFMA(ga[k2][1], gb[k2][1], acc[1][1]);
;         }
;         if (kt + 1 < nk) sstore(stset, buf ^ 1, kt + 1);
; #pragma unroll
;         for (int i = 0; i < 8; ++i) { __builtin_amdgcn_sched_group_barrier(0x008, 1, 0); __builtin_amdgcn_sched_group_barrier(0x100, 1, 0); }
; #pragma unroll
;         for (int i = 0; i < 8; ++i) { __builtin_amdgcn_sched_group_barrier(0x008, 1, 0); __builtin_amdgcn_sched_group_barrier(0x200, 1, 0); }
;         __builtin_amdgcn_sched_barrier(0);
;         __syncthreads();
;     };
;     ...
;         XCD_TILE_LOOP((layer == 0 ? NT : NL) / 128, 32, tm, tn) gemm_tile((const bf16_t*)(p.ws + WS_H), 1024, (const bf16_t*)(p.ws + wbase(layer) + W_FF1), 1024, 1024, tm * 128, tn * 128, smem, epi, nocol);
	s_setprio 1
	ds_read_b128 v[174:177], v196
	ds_read_b128 v[210:213], v197 offset:36864
	ds_read_b128 v[218:221], v197 offset:41472
	ds_read_b128 v[202:205], v196 offset:4608
	ds_read_b128 v[178:181], v196 offset:32
	ds_read_b128 v[222:225], v197 offset:41504
	ds_read_b128 v[206:209], v196 offset:4640
	ds_read_b128 v[214:217], v197 offset:36896
	s_waitcnt lgkmcnt(6)
	v_mfma_f32_32x32x16_bf16 v[52:67], v[174:177], v[210:213], v[52:67]
	global_load_dwordx4 v[68:71], v[164:165], off offset:1536
	s_waitcnt lgkmcnt(5)
	v_mfma_f32_32x32x16_bf16 v[36:51], v[174:177], v[218:221], v[36:51]
	global_load_dwordx4 v[72:75], v[162:163], off offset:1536
	s_waitcnt lgkmcnt(4)
	v_mfma_f32_32x32x16_bf16 v[4:19], v[202:205], v[218:221], v[4:19]
	global_load_dwordx4 v[76:79], v[160:161], off offset:1536
	s_waitcnt lgkmcnt(2)
	v_mfma_f32_32x32x16_bf16 v[36:51], v[178:181], v[222:225], v[36:51]
	global_load_dwordx4 v[80:83], v[158:159], off offset:1536
	s_waitcnt lgkmcnt(1)
	v_mfma_f32_32x32x16_bf16 v[4:19], v[206:209], v[222:225], v[4:19]
	global_load_dwordx4 v[84:87], v[156:157], off offset:1536
	ds_read_b128 v[222:225], v197 offset:41568
	ds_read_b128 v[174:177], v196 offset:4672
	v_mfma_f32_32x32x16_bf16 v[20:35], v[202:205], v[210:213], v[20:35]
	global_load_dwordx4 v[92:95], v[154:155], off offset:1536
	ds_read_b128 v[210:213], v196 offset:4704
	ds_read_b128 v[202:205], v196 offset:64
	s_waitcnt lgkmcnt(4)
	v_mfma_f32_32x32x16_bf16 v[52:67], v[178:181], v[214:217], v[52:67]
	global_load_dwordx4 v[104:107], v[152:153], off offset:1536
	ds_read_b128 v[218:221], v197 offset:36960
	ds_read_b128 v[178:181], v197 offset:41536
	v_mfma_f32_32x32x16_bf16 v[20:35], v[206:209], v[214:217], v[20:35]
	global_load_dwordx4 v[112:115], v[146:147], off offset:1536
	ds_read_b128 v[214:217], v197 offset:36928
	ds_read_b128 v[206:209], v196 offset:96
	s_waitcnt lgkmcnt(1)
	v_mfma_f32_32x32x16_bf16 v[52:67], v[202:205], v[214:217], v[52:67]
	s_waitcnt vmcnt(23)
	ds_write_b128 v167, v[88:91]
	v_mfma_f32_32x32x16_bf16 v[36:51], v[202:205], v[178:181], v[36:51]
	s_waitcnt vmcnt(22)
	ds_write_b128 v167, v[96:99] offset:36864
	v_mfma_f32_32x32x16_bf16 v[20:35], v[174:177], v[214:217], v[20:35]
	s_waitcnt vmcnt(21)
	ds_write_b128 v190, v[100:103]
	v_mfma_f32_32x32x16_bf16 v[4:19], v[174:177], v[178:181], v[4:19]
	s_waitcnt vmcnt(20)
	ds_write_b128 v190, v[108:111] offset:36864
	s_waitcnt lgkmcnt(4)
	v_mfma_f32_32x32x16_bf16 v[52:67], v[206:209], v[218:221], v[52:67]
	s_waitcnt vmcnt(19)
	ds_write_b128 v191, v[116:119]
	v_mfma_f32_32x32x16_bf16 v[36:51], v[206:209], v[222:225], v[36:51]
	s_setprio 0
	s_waitcnt vmcnt(18)
	ds_write_b128 v191, v[120:123] offset:36864
	v_mfma_f32_32x32x16_bf16 v[20:35], v[210:213], v[218:221], v[20:35]
	s_waitcnt vmcnt(17)
	ds_write_b128 v192, v[124:127]
	v_mfma_f32_32x32x16_bf16 v[4:19], v[210:213], v[222:225], v[4:19]
	s_waitcnt vmcnt(16)
	ds_write_b128 v192, v[128:131] offset:36864
	s_waitcnt lgkmcnt(0)
	s_barrier
	s_setprio 1
	ds_read_b128 v[174:177], v194
	ds_read_b128 v[210:213], v195 offset:36864
	ds_read_b128 v[218:221], v195 offset:41472
	ds_read_b128 v[202:205], v194 offset:4608
	ds_read_b128 v[178:181], v194 offset:32
	ds_read_b128 v[222:225], v195 offset:41504
	ds_read_b128 v[206:209], v194 offset:4640
	ds_read_b128 v[214:217], v195 offset:36896
	s_waitcnt lgkmcnt(6)
	v_mfma_f32_32x32x16_bf16 v[52:67], v[174:177], v[210:213], v[52:67]
	global_load_dwordx4 v[88:91], v[164:165], off offset:1664
	s_waitcnt lgkmcnt(5)
	v_mfma_f32_32x32x16_bf16 v[36:51], v[174:177], v[218:221], v[36:51]
	global_load_dwordx4 v[96:99], v[162:163], off offset:1664
	s_waitcnt lgkmcnt(4)
	v_mfma_f32_32x32x16_bf16 v[4:19], v[202:205], v[218:221], v[4:19]
	global_load_dwordx4 v[100:103], v[160:161], off offset:1664
	s_waitcnt lgkmcnt(2)
	v_mfma_f32_32x32x16_bf16 v[36:51], v[178:181], v[222:225], v[36:51]
	global_load_dwordx4 v[108:111], v[158:159], off offset:1664
	s_waitcnt lgkmcnt(1)
	v_mfma_f32_32x32x16_bf16 v[4:19], v[206:209], v[222:225], v[4:19]
	global_load_dwordx4 v[116:119], v[156:157], off offset:1664
	ds_read_b128 v[222:225], v195 offset:41568
	ds_read_b128 v[174:177], v194 offset:4672
	v_mfma_f32_32x32x16_bf16 v[20:35], v[202:205], v[210:213], v[20:35]
	global_load_dwordx4 v[120:123], v[154:155], off offset:1664
	ds_read_b128 v[210:213], v194 offset:4704
	ds_read_b128 v[202:205], v194 offset:64
	s_waitcnt lgkmcnt(4)
	v_mfma_f32_32x32x16_bf16 v[52:67], v[178:181], v[214:217], v[52:67]
	global_load_dwordx4 v[124:127], v[152:153], off offset:1664
	ds_read_b128 v[218:221], v195 offset:36960
	ds_read_b128 v[178:181], v195 offset:41536
	v_mfma_f32_32x32x16_bf16 v[20:35], v[206:209], v[214:217], v[20:35]
	global_load_dwordx4 v[128:131], v[146:147], off offset:1664
	ds_read_b128 v[214:217], v195 offset:36928
	ds_read_b128 v[206:209], v194 offset:96
	s_waitcnt lgkmcnt(1)
	v_mfma_f32_32x32x16_bf16 v[52:67], v[202:205], v[214:217], v[52:67]
	s_waitcnt vmcnt(23)
	ds_write_b128 v167, v[132:135] offset:18432
	v_mfma_f32_32x32x16_bf16 v[36:51], v[202:205], v[178:181], v[36:51]
	s_waitcnt vmcnt(22)
	ds_write_b128 v167, v[136:139] offset:55296
	v_mfma_f32_32x32x16_bf16 v[20:35], v[174:177], v[214:217], v[20:35]
	s_waitcnt vmcnt(21)
	ds_write_b128 v190, v[140:143] offset:18432
	v_mfma_f32_32x32x16_bf16 v[4:19], v[174:177], v[178:181], v[4:19]
	s_waitcnt vmcnt(20)
	ds_write_b128 v190, v[198:201] offset:55296
	s_waitcnt lgkmcnt(4)
	v_mfma_f32_32x32x16_bf16 v[52:67], v[206:209], v[218:221], v[52:67]
	s_waitcnt vmcnt(19)
	ds_write_b128 v191, v[226:229] offset:18432
	v_mfma_f32_32x32x16_bf16 v[36:51], v[206:209], v[222:225], v[36:51]
	s_setprio 0
	s_waitcnt vmcnt(18)
	ds_write_b128 v191, v[230:233] offset:55296
	v_mfma_f32_32x32x16_bf16 v[20:35], v[210:213], v[218:221], v[20:35]
	s_waitcnt vmcnt(17)
	ds_write_b128 v192, v[242:245] offset:18432
	v_mfma_f32_32x32x16_bf16 v[4:19], v[210:213], v[222:225], v[4:19]
	s_waitcnt vmcnt(16)
	ds_write_b128 v192, v[246:249] offset:55296
	s_waitcnt lgkmcnt(0)
	s_barrier
; template <class Epi, class ColV>
; DI void gemm_tile(const bf16_t* __restrict__ A, int lda, const bf16_t* __restrict__ Bt, int ldb, int K, int m0, int n0, unsigned char* smem, Epi epi, ColV colv, const bf16_t* __restrict__ HYT = nullptr) {
;     ...
;     auto step = [&](int kt, u32x4 (&ldset)[8], const u32x4 (&stset)[8]) {
;         const int buf = kt & 1;
;         if (kt + 2 < nk) gload(ldset, kt + 2);
;         const bf16_t* Ab = As + (buf * 128 + 64 * wr + li) * LS + 8 * lh;
;         const bf16_t* Bb = Bs + (buf * 128 + 64 * wc + li) * LS + 8 * lh;
;         bf16x8 fa[2][2], fb[2][2], ga[2][2], gb[2][2];
; #pragma unroll
;         for (int k2 = 0; k2 < 2; ++k2) { fa[k2][0] = ld8(Ab + 16 * k2); fa[k2][1] = ld8(Ab + 32 * LS + 16 * k2); fb[k2][0] = ld8(Bb + 16 * k2); fb[k2][1] = ld8(Bb + 32 * LS + 16 * k2); }
;         __builtin_amdgcn_sched_barrier(0);
; #pragma unroll
;         for (int k2 = 0; k2 < 2; ++k2) {
;             acc[0][0] = MFMA(fa[k2][0], fb[k2][0], acc[0][0]); acc[0][1] = MFMA(fa[k2][0], fb[k2][1], acc[0][1]);
;             acc[1][0] = MFMA(fa[k2][1], fb[k2][0], acc[1][0]); acc[1][1] = MFMA(fa[k2][1], fb[k2][1], acc[1][1]);
;         }
; #pragma unroll
;         for (int k2 = 0; k2 < 2; ++k2) { const int ks = 2 + k2; ga[k2][0] = ld8(Ab + 16 * ks); ga[k2][1] = ld8(Ab + 32 * LS + 16 * ks); gb[k2][0] = ld8(Bb + 16 * ks); gb[k2][1] = ld8(Bb + 32 * LS + 16 * ks); }
; #pragma unroll
;         for (int k2 = 0; k2 < 2; ++k2) {
;             acc[0][0] = MFMA(ga[k2][0], gb[k2][0], acc[0][0]); acc[0][1] = MFMA(ga[k2][0], gb[k2][1], acc[0][1]);
;             acc[1][0] = MFMA(ga[k2][1], gb[k2][0], acc[1][0]); acc[1][1] = MFMA(ga[k2][1], gb[k2][1], acc[1][1]);
;         }
;         if (kt + 1 < nk) sstore(stset, buf ^ 1, kt + 1);
; #pragma unroll
;         for (int i = 0; i < 8; ++i) { __builtin_amdgcn_sched_group_barrier(0x008, 1, 0); __builtin_amdgcn_sched_group_barrier(0x100, 1, 0); }
; #pragma unroll
;         for (int i = 0; i < 8; ++i) { __builtin_amdgcn_sched_group_barrier(0x008, 1, 0); __builtin_amdgcn_sched_group_barrier(0x200, 1, 0); }
;         __builtin_amdgcn_sched_barrier(0);
;         __syncthreads();
;     };
;     ...
;         XCD_TILE_LOOP((layer == 0 ? NT : NL) / 128, 32, tm, tn) gemm_tile((const bf16_t*)(p.ws + WS_H), 1024, (const bf16_t*)(p.ws + wbase(layer) + W_FF1), 1024, 1024, tm * 128, tn * 128, smem, epi, nocol);
	s_setprio 1
	ds_read_b128 v[174:177], v196
	ds_read_b128 v[210:213], v197 offset:36864
	ds_read_b128 v[218:221], v197 offset:41472
	ds_read_b128 v[202:205], v196 offset:4608
	ds_read_b128 v[178:181], v196 offset:32
	ds_read_b128 v[222:225], v197 offset:41504
	ds_read_b128 v[206:209], v196 offset:4640
	ds_read_b128 v[214:217], v197 offset:36896
	s_waitcnt lgkmcnt(6)
	v_mfma_f32_32x32x16_bf16 v[52:67], v[174:177], v[210:213], v[52:67]
	global_load_dwordx4 v[132:135], v[164:165], off offset:1792
	s_waitcnt lgkmcnt(5)
	v_mfma_f32_32x32x16_bf16 v[36:51], v[174:177], v[218:221], v[36:51]
	global_load_dwordx4 v[136:139], v[162:163], off offset:1792
	s_waitcnt lgkmcnt(4)
	v_mfma_f32_32x32x16_bf16 v[4:19], v[202:205], v[218:221], v[4:19]
	global_load_dwordx4 v[140:143], v[160:161], off offset:1792
	s_waitcnt lgkmcnt(2)
	v_mfma_f32_32x32x16_bf16 v[36:51], v[178:181], v[222:225], v[36:51]
	global_load_dwordx4 v[198:201], v[158:159], off offset:1792
	s_waitcnt lgkmcnt(1)
	v_mfma_f32_32x32x16_bf16 v[4:19], v[206:209], v[222:225], v[4:19]
	global_load_dwordx4 v[226:229], v[156:157], off offset:1792
	ds_read_b128 v[222:225], v197 offset:41568
	ds_read_b128 v[174:177], v196 offset:4672
	v_mfma_f32_32x32x16_bf16 v[20:35], v[202:205], v[210:213], v[20:35]
	global_load_dwordx4 v[230:233], v[154:155], off offset:1792
	ds_read_b128 v[210:213], v196 offset:4704
	ds_read_b128 v[202:205], v196 offset:64
	s_waitcnt lgkmcnt(4)
	v_mfma_f32_32x32x16_bf16 v[52:67], v[178:181], v[214:217], v[52:67]
	global_load_dwordx4 v[242:245], v[152:153], off offset:1792
	ds_read_b128 v[218:221], v197 offset:36960
	ds_read_b128 v[178:181], v197 offset:41536
	v_mfma_f32_32x32x16_bf16 v[20:35], v[206:209], v[214:217], v[20:35]
	global_load_dwordx4 v[246:249], v[146:147], off offset:1792
	ds_read_b128 v[214:217], v197 offset:36928
	ds_read_b128 v[206:209], v196 offset:96
	s_waitcnt lgkmcnt(1)
	v_mfma_f32_32x32x16_bf16 v[52:67], v[202:205], v[214:217], v[52:67]
	s_waitcnt vmcnt(23)
	ds_write_b128 v167, v[68:71]
	v_mfma_f32_32x32x16_bf16 v[36:51], v[202:205], v[178:181], v[36:51]
	s_waitcnt vmcnt(22)
	ds_write_b128 v167, v[72:75] offset:36864
	v_mfma_f32_32x32x16_bf16 v[20:35], v[174:177], v[214:217], v[20:35]
	s_waitcnt vmcnt(21)
	ds_write_b128 v190, v[76:79]
	v_mfma_f32_32x32x16_bf16 v[4:19], v[174:177], v[178:181], v[4:19]
	s_waitcnt vmcnt(20)
	ds_write_b128 v190, v[80:83] offset:36864
	s_waitcnt lgkmcnt(4)
	v_mfma_f32_32x32x16_bf16 v[52:67], v[206:209], v[218:221], v[52:67]
	s_waitcnt vmcnt(19)
	ds_write_b128 v191, v[84:87]
	v_mfma_f32_32x32x16_bf16 v[36:51], v[206:209], v[222:225], v[36:51]
	s_setprio 0
	s_waitcnt vmcnt(18)
	ds_write_b128 v191, v[92:95] offset:36864
	v_mfma_f32_32x32x16_bf16 v[20:35], v[210:213], v[218:221], v[20:35]
	s_waitcnt vmcnt(17)
	ds_write_b128 v192, v[104:107]
	v_mfma_f32_32x32x16_bf16 v[4:19], v[210:213], v[222:225], v[4:19]
	s_waitcnt vmcnt(16)
	ds_write_b128 v192, v[112:115] offset:36864
	s_waitcnt lgkmcnt(0)
	s_barrier
	s_setprio 1
	ds_read_b128 v[174:177], v194
	ds_read_b128 v[210:213], v195 offset:36864
	ds_read_b128 v[218:221], v195 offset:41472
	ds_read_b128 v[202:205], v194 offset:4608
	ds_read_b128 v[178:181], v194 offset:32
	ds_read_b128 v[222:225], v195 offset:41504
	ds_read_b128 v[206:209], v194 offset:4640
	ds_read_b128 v[214:217], v195 offset:36896
	s_waitcnt lgkmcnt(6)
	v_mfma_f32_32x32x16_bf16 v[52:67], v[174:177], v[210:213], v[52:67]
	global_load_dwordx4 v[68:71], v[164:165], off offset:1920
	s_waitcnt lgkmcnt(5)
	v_mfma_f32_32x32x16_bf16 v[36:51], v[174:177], v[218:221], v[36:51]
	global_load_dwordx4 v[72:75], v[162:163], off offset:1920
	s_waitcnt lgkmcnt(4)
	v_mfma_f32_32x32x16_bf16 v[4:19], v[202:205], v[218:221], v[4:19]
	global_load_dwordx4 v[76:79], v[160:161], off offset:1920
	s_waitcnt lgkmcnt(2)
	v_mfma_f32_32x32x16_bf16 v[36:51], v[178:181], v[222:225], v[36:51]
	global_load_dwordx4 v[80:83], v[158:159], off offset:1920
	s_waitcnt lgkmcnt(1)
	v_mfma_f32_32x32x16_bf16 v[4:19], v[206:209], v[222:225], v[4:19]
	global_load_dwordx4 v[84:87], v[156:157], off offset:1920
	ds_read_b128 v[222:225], v195 offset:41568
	ds_read_b128 v[174:177], v194 offset:4672
	v_mfma_f32_32x32x16_bf16 v[20:35], v[202:205], v[210:213], v[20:35]
	global_load_dwordx4 v[92:95], v[154:155], off offset:1920
	ds_read_b128 v[210:213], v194 offset:4704
	ds_read_b128 v[202:205], v194 offset:64
	s_waitcnt lgkmcnt(4)
	v_mfma_f32_32x32x16_bf16 v[52:67], v[178:181], v[214:217], v[52:67]
	global_load_dwordx4 v[104:107], v[152:153], off offset:1920
	ds_read_b128 v[218:221], v195 offset:36960
	ds_read_b128 v[178:181], v195 offset:41536
	v_mfma_f32_32x32x16_bf16 v[20:35], v[206:209], v[214:217], v[20:35]
	global_load_dwordx4 v[112:115], v[146:147], off offset:1920
	ds_read_b128 v[214:217], v195 offset:36928
	ds_read_b128 v[206:209], v194 offset:96
	s_waitcnt lgkmcnt(1)
	v_mfma_f32_32x32x16_bf16 v[52:67], v[202:205], v[214:217], v[52:67]
	s_waitcnt vmcnt(23)
	ds_write_b128 v167, v[88:91] offset:18432
	v_mfma_f32_32x32x16_bf16 v[36:51], v[202:205], v[178:181], v[36:51]
	s_waitcnt vmcnt(22)
	ds_write_b128 v167, v[96:99] offset:55296
	v_mfma_f32_32x32x16_bf16 v[20:35], v[174:177], v[214:217], v[20:35]
	s_waitcnt vmcnt(21)
	ds_write_b128 v190, v[100:103] offset:18432
	v_mfma_f32_32x32x16_bf16 v[4:19], v[174:177], v[178:181], v[4:19]
	s_waitcnt vmcnt(20)
	ds_write_b128 v190, v[108:111] offset:55296
	s_waitcnt lgkmcnt(4)
	v_mfma_f32_32x32x16_bf16 v[52:67], v[206:209], v[218:221], v[52:67]
	s_waitcnt vmcnt(19)
	ds_write_b128 v191, v[116:119] offset:18432
	v_mfma_f32_32x32x16_bf16 v[36:51], v[206:209], v[222:225], v[36:51]
	s_setprio 0
	s_waitcnt vmcnt(18)
	ds_write_b128 v191, v[120:123] offset:55296
	v_mfma_f32_32x32x16_bf16 v[20:35], v[210:213], v[218:221], v[20:35]
	s_waitcnt vmcnt(17)
	ds_write_b128 v192, v[124:127] offset:18432
	v_mfma_f32_32x32x16_bf16 v[4:19], v[210:213], v[222:225], v[4:19]
	s_waitcnt vmcnt(16)
	ds_write_b128 v192, v[128:131] offset:55296
	s_waitcnt lgkmcnt(0)
	s_barrier
; template <class Epi, class ColV>
; DI void gemm_tile(const bf16_t* __restrict__ A, int lda, const bf16_t* __restrict__ Bt, int ldb, int K, int m0, int n0, unsigned char* smem, Epi epi, ColV colv, const bf16_t* __restrict__ HYT = nullptr) {
;     ...
;     auto step = [&](int kt, u32x4 (&ldset)[8], const u32x4 (&stset)[8]) {
;         const int buf = kt & 1;
;         if (kt + 2 < nk) gload(ldset, kt + 2);
;         const bf16_t* Ab = As + (buf * 128 + 64 * wr + li) * LS + 8 * lh;
;         const bf16_t* Bb = Bs + (buf * 128 + 64 * wc + li) * LS + 8 * lh;
;         bf16x8 fa[2][2], fb[2][2], ga[2][2], gb[2][2];
; #pragma unroll
;         for (int k2 = 0; k2 < 2; ++k2) { fa[k2][0] = ld8(Ab + 16 * k2); fa[k2][1] = ld8(Ab + 32 * LS + 16 * k2); fb[k2][0] = ld8(Bb + 16 * k2); fb[k2][1] = ld8(Bb + 32 * LS + 16 * k2); }
;         __builtin_amdgcn_sched_barrier(0);
; #pragma unroll
;         for (int k2 = 0; k2 < 2; ++k2) {
;             acc[0][0] = MFMA(fa[k2][0], fb[k2][0], acc[0][0]); acc[0][1] = MFMA(fa[k2][0], fb[k2][1], acc[0][1]);
;             acc[1][0] = MFMA(fa[k2][1], fb[k2][0], acc[1][0]); acc[1][1] = MFMA(fa[k2][1], fb[k2][1], acc[1][1]);
;         }
; #pragma unroll
;         for (int k2 = 0; k2 < 2; ++k2) { const int ks = 2 + k2; ga[k2][0] = ld8(Ab + 16 * ks); ga[k2][1] = ld8(Ab + 32 * LS + 16 * ks); gb[k2][0] = ld8(Bb + 16 * ks); gb[k2][1] = ld8(Bb + 32 * LS + 16 * ks); }
; #pragma unroll
;         for (int k2 = 0; k2 < 2; ++k2) {
;             acc[0][0] = MFMA(ga[k2][0], gb[k2][0], acc[0][0]); acc[0][1] = MFMA(ga[k2][0], gb[k2][1], acc[0][1]);
;             acc[1][0] = MFMA(ga[k2][1], gb[k2][0], acc[1][0]); acc[1][1] = MFMA(ga[k2][1], gb[k2][1], acc[1][1]);
;         }
;         if (kt + 1 < nk) sstore(stset, buf ^ 1, kt + 1);
; #pragma unroll
;         for (int i = 0; i < 8; ++i) { __builtin_amdgcn_sched_group_barrier(0x008, 1, 0); __builtin_amdgcn_sched_group_barrier(0x100, 1, 0); }
; #pragma unroll
;         for (int i = 0; i < 8; ++i) { __builtin_amdgcn_sched_group_barrier(0x008, 1, 0); __builtin_amdgcn_sched_group_barrier(0x200, 1, 0); }
;         __builtin_amdgcn_sched_barrier(0);
;         __syncthreads();
;     };
;     ...
;         XCD_TILE_LOOP((layer == 0 ? NT : NL) / 128, 32, tm, tn) gemm_tile((const bf16_t*)(p.ws + WS_H), 1024, (const bf16_t*)(p.ws + wbase(layer) + W_FF1), 1024, 1024, tm * 128, tn * 128, smem, epi, nocol);
	s_setprio 1
	ds_read_b128 v[174:177], v196
	ds_read_b128 v[210:213], v197 offset:36864
	ds_read_b128 v[218:221], v197 offset:41472
	ds_read_b128 v[202:205], v196 offset:4608
	ds_read_b128 v[178:181], v196 offset:32
	ds_read_b128 v[222:225], v197 offset:41504
	ds_read_b128 v[206:209], v196 offset:4640
	ds_read_b128 v[214:217], v197 offset:36896
	s_waitcnt lgkmcnt(6)
	v_mfma_f32_32x32x16_bf16 v[52:67], v[174:177], v[210:213], v[52:67]
	s_waitcnt lgkmcnt(5)
	v_mfma_f32_32x32x16_bf16 v[36:51], v[174:177], v[218:221], v[36:51]
	s_waitcnt lgkmcnt(4)
	v_mfma_f32_32x32x16_bf16 v[4:19], v[202:205], v[218:221], v[4:19]
	s_waitcnt lgkmcnt(2)
	v_mfma_f32_32x32x16_bf16 v[36:51], v[178:181], v[222:225], v[36:51]
	s_waitcnt lgkmcnt(1)
	v_mfma_f32_32x32x16_bf16 v[4:19], v[206:209], v[222:225], v[4:19]
	ds_read_b128 v[222:225], v197 offset:41568
	ds_read_b128 v[174:177], v196 offset:4672
	v_mfma_f32_32x32x16_bf16 v[20:35], v[202:205], v[210:213], v[20:35]
	ds_read_b128 v[210:213], v196 offset:4704
	ds_read_b128 v[202:205], v196 offset:64
	s_waitcnt lgkmcnt(4)
	v_mfma_f32_32x32x16_bf16 v[52:67], v[178:181], v[214:217], v[52:67]
	ds_read_b128 v[218:221], v197 offset:36960
	ds_read_b128 v[178:181], v197 offset:41536
	v_mfma_f32_32x32x16_bf16 v[20:35], v[206:209], v[214:217], v[20:35]
	ds_read_b128 v[214:217], v197 offset:36928
	ds_read_b128 v[206:209], v196 offset:96
	s_waitcnt lgkmcnt(1)
	v_mfma_f32_32x32x16_bf16 v[52:67], v[202:205], v[214:217], v[52:67]
	s_waitcnt vmcnt(15)
	ds_write_b128 v167, v[132:135]
	v_mfma_f32_32x32x16_bf16 v[36:51], v[202:205], v[178:181], v[36:51]
	s_waitcnt vmcnt(14)
	ds_write_b128 v167, v[136:139] offset:36864
	v_mfma_f32_32x32x16_bf16 v[20:35], v[174:177], v[214:217], v[20:35]
	s_waitcnt vmcnt(13)
	ds_write_b128 v190, v[140:143]
	v_mfma_f32_32x32x16_bf16 v[4:19], v[174:177], v[178:181], v[4:19]
	s_waitcnt vmcnt(12)
	ds_write_b128 v190, v[198:201] offset:36864
	s_waitcnt lgkmcnt(4)
	v_mfma_f32_32x32x16_bf16 v[52:67], v[206:209], v[218:221], v[52:67]
	s_waitcnt vmcnt(11)
	ds_write_b128 v191, v[226:229]
	v_mfma_f32_32x32x16_bf16 v[36:51], v[206:209], v[222:225], v[36:51]
	s_setprio 0
	s_waitcnt vmcnt(10)
	ds_write_b128 v191, v[230:233] offset:36864
	v_mfma_f32_32x32x16_bf16 v[20:35], v[210:213], v[218:221], v[20:35]
	s_waitcnt vmcnt(9)
	ds_write_b128 v192, v[242:245]
	v_mfma_f32_32x32x16_bf16 v[4:19], v[210:213], v[222:225], v[4:19]
	s_waitcnt vmcnt(8)
	ds_write_b128 v192, v[246:249] offset:36864
	s_waitcnt lgkmcnt(0)
	s_barrier
; template <class Epi, class ColV>
; DI void gemm_tile(const bf16_t* __restrict__ A, int lda, const bf16_t* __restrict__ Bt, int ldb, int K, int m0, int n0, unsigned char* smem, Epi epi, ColV colv, const bf16_t* __restrict__ HYT = nullptr) {
;     ...
;     auto step = [&](int kt, u32x4 (&ldset)[8], const u32x4 (&stset)[8]) {
;         const int buf = kt & 1;
;         if (kt + 2 < nk) gload(ldset, kt + 2);
;         const bf16_t* Ab = As + (buf * 128 + 64 * wr + li) * LS + 8 * lh;
;         const bf16_t* Bb = Bs + (buf * 128 + 64 * wc + li) * LS + 8 * lh;
;         bf16x8 fa[2][2], fb[2][2], ga[2][2], gb[2][2];
; #pragma unroll
;         for (int k2 = 0; k2 < 2; ++k2) { fa[k2][0] = ld8(Ab + 16 * k2); fa[k2][1] = ld8(Ab + 32 * LS + 16 * k2); fb[k2][0] = ld8(Bb + 16 * k2); fb[k2][1] = ld8(Bb + 32 * LS + 16 * k2); }
;         __builtin_amdgcn_sched_barrier(0);
; #pragma unroll
;         for (int k2 = 0; k2 < 2; ++k2) {
;             acc[0][0] = MFMA(fa[k2][0], fb[k2][0], acc[0][0]); acc[0][1] = MFMA(fa[k2][0], fb[k2][1], acc[0][1]);
;             acc[1][0] = MFMA(fa[k2][1], fb[k2][0], acc[1][0]); acc[1][1] = MFMA(fa[k2][1], fb[k2][1], acc[1][1]);
;         }
; #pragma unroll
;         for (int k2 = 0; k2 < 2; ++k2) { const int ks = 2 + k2; ga[k2][0] = ld8(Ab + 16 * ks); ga[k2][1] = ld8(Ab + 32 * LS + 16 * ks); gb[k2][0] = ld8(Bb + 16 * ks); gb[k2][1] = ld8(Bb + 32 * LS + 16 * ks); }
; #pragma unroll
;         for (int k2 = 0; k2 < 2; ++k2) {
;             acc[0][0] = MFMA(ga[k2][0], gb[k2][0], acc[0][0]); acc[0][1] = MFMA(ga[k2][0], gb[k2][1], acc[0][1]);
;             acc[1][0] = MFMA(ga[k2][1], gb[k2][0], acc[1][0]); acc[1][1] = MFMA(ga[k2][1], gb[k2][1], acc[1][1]);
;         }
;         if (kt + 1 < nk) sstore(stset, buf ^ 1, kt + 1);
; #pragma unroll
;         for (int i = 0; i < 8; ++i) { __builtin_amdgcn_sched_group_barrier(0x008, 1, 0); __builtin_amdgcn_sched_group_barrier(0x100, 1, 0); }
; #pragma unroll
;         for (int i = 0; i < 8; ++i) { __builtin_amdgcn_sched_group_barrier(0x008, 1, 0); __builtin_amdgcn_sched_group_barrier(0x200, 1, 0); }
;         __builtin_amdgcn_sched_barrier(0);
;         __syncthreads();
;     };
;     gload(R0, 0); gload(R1, 1);
;     sstore(R0, 0, 0); __syncthreads();
;     for (int kt = 0; kt < nk; kt += 2) {
;         step(kt, R0, R1);
;         if (kt + 1 < nk) step(kt + 1, R1, R0);
;     }
	s_setprio 1
	ds_read_b128 v[174:177], v194
	ds_read_b128 v[210:213], v195 offset:36864
	ds_read_b128 v[218:221], v195 offset:41472
	ds_read_b128 v[202:205], v194 offset:4608
	ds_read_b128 v[178:181], v194 offset:32
	ds_read_b128 v[222:225], v195 offset:41504
	ds_read_b128 v[206:209], v194 offset:4640
	ds_read_b128 v[214:217], v195 offset:36896
	s_waitcnt lgkmcnt(6)
	v_mfma_f32_32x32x16_bf16 v[52:67], v[174:177], v[210:213], v[52:67]
	s_waitcnt lgkmcnt(5)
	v_mfma_f32_32x32x16_bf16 v[36:51], v[174:177], v[218:221], v[36:51]
	s_waitcnt lgkmcnt(4)
	v_mfma_f32_32x32x16_bf16 v[4:19], v[202:205], v[218:221], v[4:19]
	s_waitcnt lgkmcnt(2)
	v_mfma_f32_32x32x16_bf16 v[36:51], v[178:181], v[222:225], v[36:51]
	s_waitcnt lgkmcnt(1)
	v_mfma_f32_32x32x16_bf16 v[4:19], v[206:209], v[222:225], v[4:19]
	ds_read_b128 v[222:225], v195 offset:41568
	ds_read_b128 v[174:177], v194 offset:4672
	v_mfma_f32_32x32x16_bf16 v[20:35], v[202:205], v[210:213], v[20:35]
	ds_read_b128 v[210:213], v194 offset:4704
	ds_read_b128 v[202:205], v194 offset:64
	s_waitcnt lgkmcnt(4)
	v_mfma_f32_32x32x16_bf16 v[52:67], v[178:181], v[214:217], v[52:67]
	ds_read_b128 v[218:221], v195 offset:36960
	ds_read_b128 v[178:181], v195 offset:41536
	v_mfma_f32_32x32x16_bf16 v[20:35], v[206:209], v[214:217], v[20:35]
	ds_read_b128 v[214:217], v195 offset:36928
	ds_read_b128 v[206:209], v194 offset:96
	s_waitcnt lgkmcnt(1)
	v_mfma_f32_32x32x16_bf16 v[52:67], v[202:205], v[214:217], v[52:67]
	s_waitcnt vmcnt(7)
	ds_write_b128 v167, v[68:71] offset:18432
	v_mfma_f32_32x32x16_bf16 v[36:51], v[202:205], v[178:181], v[36:51]
	s_waitcnt vmcnt(6)
	ds_write_b128 v167, v[72:75] offset:55296
	v_mfma_f32_32x32x16_bf16 v[20:35], v[174:177], v[214:217], v[20:35]
	s_waitcnt vmcnt(5)
	ds_write_b128 v190, v[76:79] offset:18432
	v_mfma_f32_32x32x16_bf16 v[4:19], v[174:177], v[178:181], v[4:19]
	s_waitcnt vmcnt(4)
	ds_write_b128 v190, v[80:83] offset:55296
	s_waitcnt lgkmcnt(4)
	v_mfma_f32_32x32x16_bf16 v[52:67], v[206:209], v[218:221], v[52:67]
	s_waitcnt vmcnt(3)
	ds_write_b128 v191, v[84:87] offset:18432
	v_mfma_f32_32x32x16_bf16 v[36:51], v[206:209], v[222:225], v[36:51]
	s_setprio 0
	s_waitcnt vmcnt(2)
	ds_write_b128 v191, v[92:95] offset:55296
	v_mfma_f32_32x32x16_bf16 v[20:35], v[210:213], v[218:221], v[20:35]
	s_waitcnt vmcnt(1)
	ds_write_b128 v192, v[104:107] offset:18432
	v_mfma_f32_32x32x16_bf16 v[4:19], v[210:213], v[222:225], v[4:19]
	s_waitcnt vmcnt(0)
	ds_write_b128 v192, v[112:115] offset:55296
	s_waitcnt lgkmcnt(0)
	s_barrier
	s_setprio 1
	ds_read_b128 v[174:177], v196
	ds_read_b128 v[210:213], v197 offset:36864
	ds_read_b128 v[218:221], v197 offset:41472
	ds_read_b128 v[202:205], v196 offset:4608
	ds_read_b128 v[178:181], v196 offset:32
	ds_read_b128 v[222:225], v197 offset:41504
	ds_read_b128 v[206:209], v196 offset:4640
	ds_read_b128 v[214:217], v197 offset:36896
	s_waitcnt lgkmcnt(6)
	v_mfma_f32_32x32x16_bf16 v[52:67], v[174:177], v[210:213], v[52:67]
	s_waitcnt lgkmcnt(5)
	v_mfma_f32_32x32x16_bf16 v[36:51], v[174:177], v[218:221], v[36:51]
	s_waitcnt lgkmcnt(4)
	v_mfma_f32_32x32x16_bf16 v[4:19], v[202:205], v[218:221], v[4:19]
	s_waitcnt lgkmcnt(2)
	v_mfma_f32_32x32x16_bf16 v[36:51], v[178:181], v[222:225], v[36:51]
	s_waitcnt lgkmcnt(1)
	v_mfma_f32_32x32x16_bf16 v[4:19], v[206:209], v[222:225], v[4:19]
	ds_read_b128 v[222:225], v197 offset:41568
	ds_read_b128 v[174:177], v196 offset:4672
	v_mfma_f32_32x32x16_bf16 v[20:35], v[202:205], v[210:213], v[20:35]
	ds_read_b128 v[210:213], v196 offset:4704
	ds_read_b128 v[202:205], v196 offset:64
	s_waitcnt lgkmcnt(4)
	v_mfma_f32_32x32x16_bf16 v[52:67], v[178:181], v[214:217], v[52:67]
	ds_read_b128 v[218:221], v197 offset:36960
	ds_read_b128 v[178:181], v197 offset:41536
	v_mfma_f32_32x32x16_bf16 v[20:35], v[206:209], v[214:217], v[20:35]
	ds_read_b128 v[214:217], v197 offset:36928
	ds_read_b128 v[206:209], v196 offset:96
	s_waitcnt lgkmcnt(1)
	v_mfma_f32_32x32x16_bf16 v[52:67], v[202:205], v[214:217], v[52:67]
	v_mfma_f32_32x32x16_bf16 v[36:51], v[202:205], v[178:181], v[36:51]
	v_mfma_f32_32x32x16_bf16 v[20:35], v[174:177], v[214:217], v[20:35]
	v_mfma_f32_32x32x16_bf16 v[4:19], v[174:177], v[178:181], v[4:19]
	s_waitcnt lgkmcnt(0)
	v_mfma_f32_32x32x16_bf16 v[52:67], v[206:209], v[218:221], v[52:67]
	v_mfma_f32_32x32x16_bf16 v[36:51], v[206:209], v[222:225], v[36:51]
	s_setprio 0
	v_mfma_f32_32x32x16_bf16 v[20:35], v[210:213], v[218:221], v[20:35]
	v_mfma_f32_32x32x16_bf16 v[4:19], v[210:213], v[222:225], v[4:19]
	s_waitcnt lgkmcnt(0)
	s_barrier
	s_setprio 1
	s_nop 7
	s_nop 3
	s_branch .LBB0_53

; template <class Epi, class ColV>
; DI void gemm_tile(const bf16_t* __restrict__ A, int lda, const bf16_t* __restrict__ Bt, int ldb, int K, int m0, int n0, unsigned char* smem, Epi epi, ColV colv, const bf16_t* __restrict__ HYT = nullptr) {
;     ...
;     auto step = [&](int kt, u32x4 (&ldset)[8], const u32x4 (&stset)[8]) {
;         const int buf = kt & 1;
;         if (kt + 2 < nk) gload(ldset, kt + 2);
;         const bf16_t* Ab = As + (buf * 128 + 64 * wr + li) * LS + 8 * lh;
;         const bf16_t* Bb = Bs + (buf * 128 + 64 * wc + li) * LS + 8 * lh;
;         bf16x8 fa[2][2], fb[2][2], ga[2][2], gb[2][2];
; #pragma unroll
;         for (int k2 = 0; k2 < 2; ++k2) { fa[k2][0] = ld8(Ab + 16 * k2); fa[k2][1] = ld8(Ab + 32 * LS + 16 * k2); fb[k2][0] = ld8(Bb + 16 * k2); fb[k2][1] = ld8(Bb + 32 * LS + 16 * k2); }
;         __builtin_amdgcn_sched_barrier(0);
; #pragma unroll
;         for (int k2 = 0; k2 < 2; ++k2) {
;             acc[0][0] = MFMA(fa[k2][0], fb[k2][0], acc[0][0]); acc[0][1] = MFMA(fa[k2][0], fb[k2][1], acc[0][1]);
;             acc[1][0] = MFMA(fa[k2][1], fb[k2][0], acc[1][0]); acc[1][1] = MFMA(fa[k2][1], fb[k2][1], acc[1][1]);
;         }
; #pragma unroll
;         for (int k2 = 0; k2 < 2; ++k2) { const int ks = 2 + k2; ga[k2][0] = ld8(Ab + 16 * ks); ga[k2][1] = ld8(Ab + 32 * LS + 16 * ks); gb[k2][0] = ld8(Bb + 16 * ks); gb[k2][1] = ld8(Bb + 32 * LS + 16 * ks); }
; #pragma unroll
;         for (int k2 = 0; k2 < 2; ++k2) {
;             acc[0][0] = MFMA(ga[k2][0], gb[k2][0], acc[0][0]); acc[0][1] = MFMA(ga[k2][0], gb[k2][1], acc[0][1]);
;             acc[1][0] = MFMA(ga[k2][1], gb[k2][0], acc[1][0]); acc[1][1] = MFMA(ga[k2][1], gb[k2][1], acc[1][1]);
;         }
;         if (kt + 1 < nk) sstore(stset, buf ^ 1, kt + 1);
; #pragma unroll
;         for (int i = 0; i < 8; ++i) { __builtin_amdgcn_sched_group_barrier(0x008, 1, 0); __builtin_amdgcn_sched_group_barrier(0x100, 1, 0); }
; #pragma unroll
;         for (int i = 0; i < 8; ++i) { __builtin_amdgcn_sched_group_barrier(0x008, 1, 0); __builtin_amdgcn_sched_group_barrier(0x200, 1, 0); }
;         __builtin_amdgcn_sched_barrier(0);
;         __syncthreads();
;     };
;     gload(R0, 0); gload(R1, 1);
;     sstore(R0, 0, 0); __syncthreads();
;     for (int kt = 0; kt < nk; kt += 2) {
;         step(kt, R0, R1);
;         if (kt + 1 < nk) step(kt + 1, R1, R0);
;     }
;     ...
;     case 2: {
.LBB0_1558:
	s_cmp_lt_u32 s19, 14
	s_cselect_b64 s[12:13], -1, 0
	s_cmp_gt_u32 s19, 13
	s_cselect_b64 s[10:11], -1, 0
	s_and_b64 vcc, exec, s[10:11]
	v_lshl_add_u64 v[164:165], v[144:145], 0, v[2:3]
	v_lshl_add_u64 v[162:163], v[0:1], 0, v[2:3]
	v_lshl_add_u64 v[160:161], v[142:143], 0, v[2:3]
	v_lshl_add_u64 v[158:159], v[132:133], 0, v[2:3]
	v_lshl_add_u64 v[156:157], v[140:141], 0, v[2:3]
	v_lshl_add_u64 v[154:155], v[134:135], 0, v[2:3]
	v_lshl_add_u64 v[152:153], v[138:139], 0, v[2:3]
	v_lshl_add_u64 v[146:147], v[136:137], 0, v[2:3]
	s_mov_b32 s100, 0x26ca000
	s_mov_b32 s101, 0
	v_lshl_add_u64 v[164:165], v[164:165], 0, s[100:101]
	v_lshl_add_u64 v[160:161], v[160:161], 0, s[100:101]
	v_lshl_add_u64 v[156:157], v[156:157], 0, s[100:101]
	v_lshl_add_u64 v[152:153], v[152:153], 0, s[100:101]
	ds_read_b128 v[202:205], v194
	ds_read_b128 v[218:221], v195 offset:36864
	ds_read_b128 v[226:229], v195 offset:41472
	ds_read_b128 v[210:213], v194 offset:4608
	ds_read_b128 v[206:209], v194 offset:32
	ds_read_b128 v[230:233], v195 offset:41504
	ds_read_b128 v[214:217], v194 offset:4640
	ds_read_b128 v[222:225], v195 offset:36896
	s_waitcnt lgkmcnt(6)
	v_mfma_f32_32x32x16_bf16 v[52:67], v[202:205], v[218:221], v[52:67]
	global_load_dwordx4 v[132:135], v[164:165], off offset:256
	global_load_dwordx4 v[136:139], v[162:163], off offset:256
	s_waitcnt lgkmcnt(5)
	v_mfma_f32_32x32x16_bf16 v[36:51], v[202:205], v[226:229], v[36:51]
	global_load_dwordx4 v[140:143], v[160:161], off offset:256
	global_load_dwordx4 v[198:201], v[158:159], off offset:256
	s_waitcnt lgkmcnt(4)
	v_mfma_f32_32x32x16_bf16 v[4:19], v[210:213], v[226:229], v[4:19]
	global_load_dwordx4 v[174:177], v[156:157], off offset:256
	global_load_dwordx4 v[178:181], v[154:155], off offset:256
	s_waitcnt lgkmcnt(2)
	v_mfma_f32_32x32x16_bf16 v[36:51], v[206:209], v[230:233], v[36:51]
	global_load_dwordx4 v[242:245], v[152:153], off offset:256
	global_load_dwordx4 v[246:249], v[146:147], off offset:256
	s_waitcnt lgkmcnt(1)
	v_mfma_f32_32x32x16_bf16 v[4:19], v[214:217], v[230:233], v[4:19]
	global_load_dwordx4 v[68:71], v[164:165], off offset:384
	global_load_dwordx4 v[72:75], v[162:163], off offset:384
	ds_read_b128 v[230:233], v195 offset:41568
	ds_read_b128 v[202:205], v194 offset:4672
	v_mfma_f32_32x32x16_bf16 v[20:35], v[210:213], v[218:221], v[20:35]
	global_load_dwordx4 v[76:79], v[160:161], off offset:384
	global_load_dwordx4 v[80:83], v[158:159], off offset:384
	ds_read_b128 v[218:221], v194 offset:4704
	ds_read_b128 v[210:213], v194 offset:64
	s_waitcnt lgkmcnt(4)
	v_mfma_f32_32x32x16_bf16 v[52:67], v[206:209], v[222:225], v[52:67]
	global_load_dwordx4 v[84:87], v[156:157], off offset:384
	global_load_dwordx4 v[88:91], v[154:155], off offset:384
	ds_read_b128 v[226:229], v195 offset:36960
	ds_read_b128 v[206:209], v195 offset:41536
	v_mfma_f32_32x32x16_bf16 v[20:35], v[214:217], v[222:225], v[20:35]
	global_load_dwordx4 v[92:95], v[152:153], off offset:384
	global_load_dwordx4 v[104:107], v[146:147], off offset:384
	ds_read_b128 v[222:225], v195 offset:36928
	ds_read_b128 v[214:217], v194 offset:96
	s_waitcnt lgkmcnt(1)
	v_mfma_f32_32x32x16_bf16 v[52:67], v[210:213], v[222:225], v[52:67]
	s_waitcnt vmcnt(16)
	ds_write_b128 v167, v[96:99] offset:18432
	v_mfma_f32_32x32x16_bf16 v[36:51], v[210:213], v[206:209], v[36:51]
	ds_write_b128 v167, v[100:103] offset:55296
	v_mfma_f32_32x32x16_bf16 v[20:35], v[202:205], v[222:225], v[20:35]
	ds_write_b128 v190, v[108:111] offset:18432
	v_mfma_f32_32x32x16_bf16 v[4:19], v[202:205], v[206:209], v[4:19]
	ds_write_b128 v190, v[112:115] offset:55296
	s_waitcnt lgkmcnt(4)
	v_mfma_f32_32x32x16_bf16 v[52:67], v[214:217], v[226:229], v[52:67]
	ds_write_b128 v191, v[116:119] offset:18432
	v_mfma_f32_32x32x16_bf16 v[36:51], v[214:217], v[230:233], v[36:51]
	s_setprio 0
	ds_write_b128 v191, v[120:123] offset:55296
	v_mfma_f32_32x32x16_bf16 v[20:35], v[218:221], v[226:229], v[20:35]
	ds_write_b128 v192, v[124:127] offset:18432
	v_mfma_f32_32x32x16_bf16 v[4:19], v[218:221], v[230:233], v[4:19]
	ds_write_b128 v192, v[128:131] offset:55296
	s_waitcnt lgkmcnt(0)
	s_barrier
	s_setprio 1
	ds_read_b128 v[202:205], v196
	ds_read_b128 v[218:221], v197 offset:36864
	ds_read_b128 v[226:229], v197 offset:41472
	ds_read_b128 v[210:213], v196 offset:4608
	ds_read_b128 v[206:209], v196 offset:32
	ds_read_b128 v[230:233], v197 offset:41504
	ds_read_b128 v[214:217], v196 offset:4640
	ds_read_b128 v[222:225], v197 offset:36896
	s_waitcnt lgkmcnt(6)
	v_mfma_f32_32x32x16_bf16 v[52:67], v[202:205], v[218:221], v[52:67]
	global_load_dwordx4 v[96:99], v[164:165], off offset:512
	s_waitcnt lgkmcnt(5)
	v_mfma_f32_32x32x16_bf16 v[36:51], v[202:205], v[226:229], v[36:51]
	global_load_dwordx4 v[100:103], v[162:163], off offset:512
	s_waitcnt lgkmcnt(4)
	v_mfma_f32_32x32x16_bf16 v[4:19], v[210:213], v[226:229], v[4:19]
	global_load_dwordx4 v[108:111], v[160:161], off offset:512
	s_waitcnt lgkmcnt(2)
	v_mfma_f32_32x32x16_bf16 v[36:51], v[206:209], v[230:233], v[36:51]
	global_load_dwordx4 v[112:115], v[158:159], off offset:512
	s_waitcnt lgkmcnt(1)
	v_mfma_f32_32x32x16_bf16 v[4:19], v[214:217], v[230:233], v[4:19]
	global_load_dwordx4 v[116:119], v[156:157], off offset:512
	ds_read_b128 v[230:233], v197 offset:41568
	ds_read_b128 v[202:205], v196 offset:4672
	v_mfma_f32_32x32x16_bf16 v[20:35], v[210:213], v[218:221], v[20:35]
	global_load_dwordx4 v[120:123], v[154:155], off offset:512
	ds_read_b128 v[218:221], v196 offset:4704
	ds_read_b128 v[210:213], v196 offset:64
	s_waitcnt lgkmcnt(4)
; template <class Epi, class ColV>
; DI void gemm_tile(const bf16_t* __restrict__ A, int lda, const bf16_t* __restrict__ Bt, int ldb, int K, int m0, int n0, unsigned char* smem, Epi epi, ColV colv, const bf16_t* __restrict__ HYT = nullptr) {
;     ...
;     auto step = [&](int kt, u32x4 (&ldset)[8], const u32x4 (&stset)[8]) {
;         const int buf = kt & 1;
;         if (kt + 2 < nk) gload(ldset, kt + 2);
;         const bf16_t* Ab = As + (buf * 128 + 64 * wr + li) * LS + 8 * lh;
;         const bf16_t* Bb = Bs + (buf * 128 + 64 * wc + li) * LS + 8 * lh;
;         bf16x8 fa[2][2], fb[2][2], ga[2][2], gb[2][2];
; #pragma unroll
;         for (int k2 = 0; k2 < 2; ++k2) { fa[k2][0] = ld8(Ab + 16 * k2); fa[k2][1] = ld8(Ab + 32 * LS + 16 * k2); fb[k2][0] = ld8(Bb + 16 * k2); fb[k2][1] = ld8(Bb + 32 * LS + 16 * k2); }
;         __builtin_amdgcn_sched_barrier(0);
; #pragma unroll
;         for (int k2 = 0; k2 < 2; ++k2) {
;             acc[0][0] = MFMA(fa[k2][0], fb[k2][0], acc[0][0]); acc[0][1] = MFMA(fa[k2][0], fb[k2][1], acc[0][1]);
;             acc[1][0] = MFMA(fa[k2][1], fb[k2][0], acc[1][0]); acc[1][1] = MFMA(fa[k2][1], fb[k2][1], acc[1][1]);
;         }
; #pragma unroll
;         for (int k2 = 0; k2 < 2; ++k2) { const int ks = 2 + k2; ga[k2][0] = ld8(Ab + 16 * ks); ga[k2][1] = ld8(Ab + 32 * LS + 16 * ks); gb[k2][0] = ld8(Bb + 16 * ks); gb[k2][1] = ld8(Bb + 32 * LS + 16 * ks); }
; #pragma unroll
;         for (int k2 = 0; k2 < 2; ++k2) {
;             acc[0][0] = MFMA(ga[k2][0], gb[k2][0], acc[0][0]); acc[0][1] = MFMA(ga[k2][0], gb[k2][1], acc[0][1]);
;             acc[1][0] = MFMA(ga[k2][1], gb[k2][0], acc[1][0]); acc[1][1] = MFMA(ga[k2][1], gb[k2][1], acc[1][1]);
;         }
;         if (kt + 1 < nk) sstore(stset, buf ^ 1, kt + 1);
; #pragma unroll
;         for (int i = 0; i < 8; ++i) { __builtin_amdgcn_sched_group_barrier(0x008, 1, 0); __builtin_amdgcn_sched_group_barrier(0x100, 1, 0); }
; #pragma unroll
;         for (int i = 0; i < 8; ++i) { __builtin_amdgcn_sched_group_barrier(0x008, 1, 0); __builtin_amdgcn_sched_group_barrier(0x200, 1, 0); }
;         __builtin_amdgcn_sched_barrier(0);
;         __syncthreads();
;     };
;     ...
;         XCD_TILE_LOOP(NT / 128, INP / 128, tm, tn) gemm_tile((const bf16_t*)(p.ws + WS_H), 1024, (const bf16_t*)(p.ws + wbase(layer) + W_IN), 1024, 1024, tm * 128, tn * 128, smem, epi, nocol);
	v_mfma_f32_32x32x16_bf16 v[52:67], v[206:209], v[222:225], v[52:67]
	global_load_dwordx4 v[124:127], v[152:153], off offset:512
	ds_read_b128 v[226:229], v197 offset:36960
	ds_read_b128 v[206:209], v197 offset:41536
	v_mfma_f32_32x32x16_bf16 v[20:35], v[214:217], v[222:225], v[20:35]
	global_load_dwordx4 v[128:131], v[146:147], off offset:512
	ds_read_b128 v[222:225], v197 offset:36928
	ds_read_b128 v[214:217], v196 offset:96
	s_waitcnt lgkmcnt(1)
	v_mfma_f32_32x32x16_bf16 v[52:67], v[210:213], v[222:225], v[52:67]
	s_waitcnt vmcnt(23)
	ds_write_b128 v167, v[132:135]
	v_mfma_f32_32x32x16_bf16 v[36:51], v[210:213], v[206:209], v[36:51]
	s_waitcnt vmcnt(22)
	ds_write_b128 v167, v[136:139] offset:36864
	v_mfma_f32_32x32x16_bf16 v[20:35], v[202:205], v[222:225], v[20:35]
	s_waitcnt vmcnt(21)
	ds_write_b128 v190, v[140:143]
	v_mfma_f32_32x32x16_bf16 v[4:19], v[202:205], v[206:209], v[4:19]
	s_waitcnt vmcnt(20)
	ds_write_b128 v190, v[198:201] offset:36864
	s_waitcnt lgkmcnt(4)
	v_mfma_f32_32x32x16_bf16 v[52:67], v[214:217], v[226:229], v[52:67]
	s_waitcnt vmcnt(19)
	ds_write_b128 v191, v[174:177]
	v_mfma_f32_32x32x16_bf16 v[36:51], v[214:217], v[230:233], v[36:51]
	s_setprio 0
	s_waitcnt vmcnt(18)
	ds_write_b128 v191, v[178:181] offset:36864
	v_mfma_f32_32x32x16_bf16 v[20:35], v[218:221], v[226:229], v[20:35]
	s_waitcnt vmcnt(17)
	ds_write_b128 v192, v[242:245]
	v_mfma_f32_32x32x16_bf16 v[4:19], v[218:221], v[230:233], v[4:19]
	s_waitcnt vmcnt(16)
	ds_write_b128 v192, v[246:249] offset:36864
	s_waitcnt lgkmcnt(0)
	s_barrier
	s_setprio 1
	ds_read_b128 v[202:205], v194
	ds_read_b128 v[218:221], v195 offset:36864
	ds_read_b128 v[226:229], v195 offset:41472
	ds_read_b128 v[210:213], v194 offset:4608
	ds_read_b128 v[206:209], v194 offset:32
	ds_read_b128 v[230:233], v195 offset:41504
	ds_read_b128 v[214:217], v194 offset:4640
	ds_read_b128 v[222:225], v195 offset:36896
	s_waitcnt lgkmcnt(6)
	v_mfma_f32_32x32x16_bf16 v[52:67], v[202:205], v[218:221], v[52:67]
	global_load_dwordx4 v[132:135], v[164:165], off offset:640
	s_waitcnt lgkmcnt(5)
	v_mfma_f32_32x32x16_bf16 v[36:51], v[202:205], v[226:229], v[36:51]
	global_load_dwordx4 v[136:139], v[162:163], off offset:640
	s_waitcnt lgkmcnt(4)
	v_mfma_f32_32x32x16_bf16 v[4:19], v[210:213], v[226:229], v[4:19]
	global_load_dwordx4 v[140:143], v[160:161], off offset:640
	s_waitcnt lgkmcnt(2)
	v_mfma_f32_32x32x16_bf16 v[36:51], v[206:209], v[230:233], v[36:51]
	global_load_dwordx4 v[198:201], v[158:159], off offset:640
	s_waitcnt lgkmcnt(1)
	v_mfma_f32_32x32x16_bf16 v[4:19], v[214:217], v[230:233], v[4:19]
	global_load_dwordx4 v[174:177], v[156:157], off offset:640
	ds_read_b128 v[230:233], v195 offset:41568
	ds_read_b128 v[202:205], v194 offset:4672
	v_mfma_f32_32x32x16_bf16 v[20:35], v[210:213], v[218:221], v[20:35]
	global_load_dwordx4 v[178:181], v[154:155], off offset:640
	ds_read_b128 v[218:221], v194 offset:4704
	ds_read_b128 v[210:213], v194 offset:64
	s_waitcnt lgkmcnt(4)
	v_mfma_f32_32x32x16_bf16 v[52:67], v[206:209], v[222:225], v[52:67]
	global_load_dwordx4 v[242:245], v[152:153], off offset:640
	ds_read_b128 v[226:229], v195 offset:36960
	ds_read_b128 v[206:209], v195 offset:41536
	v_mfma_f32_32x32x16_bf16 v[20:35], v[214:217], v[222:225], v[20:35]
	global_load_dwordx4 v[246:249], v[146:147], off offset:640
	ds_read_b128 v[222:225], v195 offset:36928
	ds_read_b128 v[214:217], v194 offset:96
	s_waitcnt lgkmcnt(1)
	v_mfma_f32_32x32x16_bf16 v[52:67], v[210:213], v[222:225], v[52:67]
	s_waitcnt vmcnt(23)
	ds_write_b128 v167, v[68:71] offset:18432
	v_mfma_f32_32x32x16_bf16 v[36:51], v[210:213], v[206:209], v[36:51]
	s_waitcnt vmcnt(22)
	ds_write_b128 v167, v[72:75] offset:55296
	v_mfma_f32_32x32x16_bf16 v[20:35], v[202:205], v[222:225], v[20:35]
	s_waitcnt vmcnt(21)
	ds_write_b128 v190, v[76:79] offset:18432
	v_mfma_f32_32x32x16_bf16 v[4:19], v[202:205], v[206:209], v[4:19]
	s_waitcnt vmcnt(20)
	ds_write_b128 v190, v[80:83] offset:55296
	s_waitcnt lgkmcnt(4)
	v_mfma_f32_32x32x16_bf16 v[52:67], v[214:217], v[226:229], v[52:67]
	s_waitcnt vmcnt(19)
	ds_write_b128 v191, v[84:87] offset:18432
	v_mfma_f32_32x32x16_bf16 v[36:51], v[214:217], v[230:233], v[36:51]
	s_setprio 0
	s_waitcnt vmcnt(18)
	ds_write_b128 v191, v[88:91] offset:55296
	v_mfma_f32_32x32x16_bf16 v[20:35], v[218:221], v[226:229], v[20:35]
	s_waitcnt vmcnt(17)
	ds_write_b128 v192, v[92:95] offset:18432
	v_mfma_f32_32x32x16_bf16 v[4:19], v[218:221], v[230:233], v[4:19]
	s_waitcnt vmcnt(16)
	ds_write_b128 v192, v[104:107] offset:55296
	s_waitcnt lgkmcnt(0)
	s_barrier
; template <class Epi, class ColV>
; DI void gemm_tile(const bf16_t* __restrict__ A, int lda, const bf16_t* __restrict__ Bt, int ldb, int K, int m0, int n0, unsigned char* smem, Epi epi, ColV colv, const bf16_t* __restrict__ HYT = nullptr) {
;     ...
;     auto step = [&](int kt, u32x4 (&ldset)[8], const u32x4 (&stset)[8]) {
;         const int buf = kt & 1;
;         if (kt + 2 < nk) gload(ldset, kt + 2);
;         const bf16_t* Ab = As + (buf * 128 + 64 * wr + li) * LS + 8 * lh;
;         const bf16_t* Bb = Bs + (buf * 128 + 64 * wc + li) * LS + 8 * lh;
;         bf16x8 fa[2][2], fb[2][2], ga[2][2], gb[2][2];
; #pragma unroll
;         for (int k2 = 0; k2 < 2; ++k2) { fa[k2][0] = ld8(Ab + 16 * k2); fa[k2][1] = ld8(Ab + 32 * LS + 16 * k2); fb[k2][0] = ld8(Bb + 16 * k2); fb[k2][1] = ld8(Bb + 32 * LS + 16 * k2); }
;         __builtin_amdgcn_sched_barrier(0);
; #pragma unroll
;         for (int k2 = 0; k2 < 2; ++k2) {
;             acc[0][0] = MFMA(fa[k2][0], fb[k2][0], acc[0][0]); acc[0][1] = MFMA(fa[k2][0], fb[k2][1], acc[0][1]);
;             acc[1][0] = MFMA(fa[k2][1], fb[k2][0], acc[1][0]); acc[1][1] = MFMA(fa[k2][1], fb[k2][1], acc[1][1]);
;         }
; #pragma unroll
;         for (int k2 = 0; k2 < 2; ++k2) { const int ks = 2 + k2; ga[k2][0] = ld8(Ab + 16 * ks); ga[k2][1] = ld8(Ab + 32 * LS + 16 * ks); gb[k2][0] = ld8(Bb + 16 * ks); gb[k2][1] = ld8(Bb + 32 * LS + 16 * ks); }
; #pragma unroll
;         for (int k2 = 0; k2 < 2; ++k2) {
;             acc[0][0] = MFMA(ga[k2][0], gb[k2][0], acc[0][0]); acc[0][1] = MFMA(ga[k2][0], gb[k2][1], acc[0][1]);
;             acc[1][0] = MFMA(ga[k2][1], gb[k2][0], acc[1][0]); acc[1][1] = MFMA(ga[k2][1], gb[k2][1], acc[1][1]);
;         }
;         if (kt + 1 < nk) sstore(stset, buf ^ 1, kt + 1);
; #pragma unroll
;         for (int i = 0; i < 8; ++i) { __builtin_amdgcn_sched_group_barrier(0x008, 1, 0); __builtin_amdgcn_sched_group_barrier(0x100, 1, 0); }
; #pragma unroll
;         for (int i = 0; i < 8; ++i) { __builtin_amdgcn_sched_group_barrier(0x008, 1, 0); __builtin_amdgcn_sched_group_barrier(0x200, 1, 0); }
;         __builtin_amdgcn_sched_barrier(0);
;         __syncthreads();
;     };
;     ...
;         XCD_TILE_LOOP(NT / 128, INP / 128, tm, tn) gemm_tile((const bf16_t*)(p.ws + WS_H), 1024, (const bf16_t*)(p.ws + wbase(layer) + W_IN), 1024, 1024, tm * 128, tn * 128, smem, epi, nocol);
	s_setprio 1
	ds_read_b128 v[202:205], v196
	ds_read_b128 v[218:221], v197 offset:36864
	ds_read_b128 v[226:229], v197 offset:41472
	ds_read_b128 v[210:213], v196 offset:4608
	ds_read_b128 v[206:209], v196 offset:32
	ds_read_b128 v[230:233], v197 offset:41504
	ds_read_b128 v[214:217], v196 offset:4640
	ds_read_b128 v[222:225], v197 offset:36896
	s_waitcnt lgkmcnt(6)
	v_mfma_f32_32x32x16_bf16 v[52:67], v[202:205], v[218:221], v[52:67]
	global_load_dwordx4 v[68:71], v[164:165], off offset:768
	s_waitcnt lgkmcnt(5)
	v_mfma_f32_32x32x16_bf16 v[36:51], v[202:205], v[226:229], v[36:51]
	global_load_dwordx4 v[72:75], v[162:163], off offset:768
	s_waitcnt lgkmcnt(4)
	v_mfma_f32_32x32x16_bf16 v[4:19], v[210:213], v[226:229], v[4:19]
	global_load_dwordx4 v[76:79], v[160:161], off offset:768
	s_waitcnt lgkmcnt(2)
	v_mfma_f32_32x32x16_bf16 v[36:51], v[206:209], v[230:233], v[36:51]
	global_load_dwordx4 v[80:83], v[158:159], off offset:768
	s_waitcnt lgkmcnt(1)
	v_mfma_f32_32x32x16_bf16 v[4:19], v[214:217], v[230:233], v[4:19]
	global_load_dwordx4 v[84:87], v[156:157], off offset:768
	ds_read_b128 v[230:233], v197 offset:41568
	ds_read_b128 v[202:205], v196 offset:4672
	v_mfma_f32_32x32x16_bf16 v[20:35], v[210:213], v[218:221], v[20:35]
	global_load_dwordx4 v[88:91], v[154:155], off offset:768
	ds_read_b128 v[218:221], v196 offset:4704
	ds_read_b128 v[210:213], v196 offset:64
	s_waitcnt lgkmcnt(4)
	v_mfma_f32_32x32x16_bf16 v[52:67], v[206:209], v[222:225], v[52:67]
	global_load_dwordx4 v[92:95], v[152:153], off offset:768
	ds_read_b128 v[226:229], v197 offset:36960
	ds_read_b128 v[206:209], v197 offset:41536
	v_mfma_f32_32x32x16_bf16 v[20:35], v[214:217], v[222:225], v[20:35]
	global_load_dwordx4 v[104:107], v[146:147], off offset:768
	ds_read_b128 v[222:225], v197 offset:36928
	ds_read_b128 v[214:217], v196 offset:96
	s_waitcnt lgkmcnt(1)
	v_mfma_f32_32x32x16_bf16 v[52:67], v[210:213], v[222:225], v[52:67]
	s_waitcnt vmcnt(23)
	ds_write_b128 v167, v[96:99]
	v_mfma_f32_32x32x16_bf16 v[36:51], v[210:213], v[206:209], v[36:51]
	s_waitcnt vmcnt(22)
	ds_write_b128 v167, v[100:103] offset:36864
	v_mfma_f32_32x32x16_bf16 v[20:35], v[202:205], v[222:225], v[20:35]
	s_waitcnt vmcnt(21)
	ds_write_b128 v190, v[108:111]
	v_mfma_f32_32x32x16_bf16 v[4:19], v[202:205], v[206:209], v[4:19]
	s_waitcnt vmcnt(20)
	ds_write_b128 v190, v[112:115] offset:36864
	s_waitcnt lgkmcnt(4)
	v_mfma_f32_32x32x16_bf16 v[52:67], v[214:217], v[226:229], v[52:67]
	s_waitcnt vmcnt(19)
	ds_write_b128 v191, v[116:119]
	v_mfma_f32_32x32x16_bf16 v[36:51], v[214:217], v[230:233], v[36:51]
	s_setprio 0
	s_waitcnt vmcnt(18)
	ds_write_b128 v191, v[120:123] offset:36864
	v_mfma_f32_32x32x16_bf16 v[20:35], v[218:221], v[226:229], v[20:35]
	s_waitcnt vmcnt(17)
	ds_write_b128 v192, v[124:127]
	v_mfma_f32_32x32x16_bf16 v[4:19], v[218:221], v[230:233], v[4:19]
	s_waitcnt vmcnt(16)
	ds_write_b128 v192, v[128:131] offset:36864
	s_waitcnt lgkmcnt(0)
	s_barrier
	s_setprio 1
	ds_read_b128 v[202:205], v194
	ds_read_b128 v[218:221], v195 offset:36864
	ds_read_b128 v[226:229], v195 offset:41472
	ds_read_b128 v[210:213], v194 offset:4608
	ds_read_b128 v[206:209], v194 offset:32
	ds_read_b128 v[230:233], v195 offset:41504
	ds_read_b128 v[214:217], v194 offset:4640
	ds_read_b128 v[222:225], v195 offset:36896
	s_waitcnt lgkmcnt(6)
	v_mfma_f32_32x32x16_bf16 v[52:67], v[202:205], v[218:221], v[52:67]
	global_load_dwordx4 v[96:99], v[164:165], off offset:896
	s_waitcnt lgkmcnt(5)
	v_mfma_f32_32x32x16_bf16 v[36:51], v[202:205], v[226:229], v[36:51]
	global_load_dwordx4 v[100:103], v[162:163], off offset:896
	s_waitcnt lgkmcnt(4)
	v_mfma_f32_32x32x16_bf16 v[4:19], v[210:213], v[226:229], v[4:19]
	global_load_dwordx4 v[108:111], v[160:161], off offset:896
	s_waitcnt lgkmcnt(2)
	v_mfma_f32_32x32x16_bf16 v[36:51], v[206:209], v[230:233], v[36:51]
	global_load_dwordx4 v[112:115], v[158:159], off offset:896
	s_waitcnt lgkmcnt(1)
	v_mfma_f32_32x32x16_bf16 v[4:19], v[214:217], v[230:233], v[4:19]
	global_load_dwordx4 v[116:119], v[156:157], off offset:896
	ds_read_b128 v[230:233], v195 offset:41568
	ds_read_b128 v[202:205], v194 offset:4672
	v_mfma_f32_32x32x16_bf16 v[20:35], v[210:213], v[218:221], v[20:35]
	global_load_dwordx4 v[120:123], v[154:155], off offset:896
	ds_read_b128 v[218:221], v194 offset:4704
	ds_read_b128 v[210:213], v194 offset:64
	s_waitcnt lgkmcnt(4)
	v_mfma_f32_32x32x16_bf16 v[52:67], v[206:209], v[222:225], v[52:67]
	global_load_dwordx4 v[124:127], v[152:153], off offset:896
	ds_read_b128 v[226:229], v195 offset:36960
	ds_read_b128 v[206:209], v195 offset:41536
	v_mfma_f32_32x32x16_bf16 v[20:35], v[214:217], v[222:225], v[20:35]
	global_load_dwordx4 v[128:131], v[146:147], off offset:896
	ds_read_b128 v[222:225], v195 offset:36928
	ds_read_b128 v[214:217], v194 offset:96
	s_waitcnt lgkmcnt(1)
	v_mfma_f32_32x32x16_bf16 v[52:67], v[210:213], v[222:225], v[52:67]
	s_waitcnt vmcnt(23)
	ds_write_b128 v167, v[132:135] offset:18432
	v_mfma_f32_32x32x16_bf16 v[36:51], v[210:213], v[206:209], v[36:51]
	s_waitcnt vmcnt(22)
	ds_write_b128 v167, v[136:139] offset:55296
	v_mfma_f32_32x32x16_bf16 v[20:35], v[202:205], v[222:225], v[20:35]
	s_waitcnt vmcnt(21)
	ds_write_b128 v190, v[140:143] offset:18432
	v_mfma_f32_32x32x16_bf16 v[4:19], v[202:205], v[206:209], v[4:19]
	s_waitcnt vmcnt(20)
	ds_write_b128 v190, v[198:201] offset:55296
	s_waitcnt lgkmcnt(4)
	v_mfma_f32_32x32x16_bf16 v[52:67], v[214:217], v[226:229], v[52:67]
	s_waitcnt vmcnt(19)
	ds_write_b128 v191, v[174:177] offset:18432
	v_mfma_f32_32x32x16_bf16 v[36:51], v[214:217], v[230:233], v[36:51]
	s_setprio 0
	s_waitcnt vmcnt(18)
	ds_write_b128 v191, v[178:181] offset:55296
	v_mfma_f32_32x32x16_bf16 v[20:35], v[218:221], v[226:229], v[20:35]
	s_waitcnt vmcnt(17)
	ds_write_b128 v192, v[242:245] offset:18432
	v_mfma_f32_32x32x16_bf16 v[4:19], v[218:221], v[230:233], v[4:19]
	s_waitcnt vmcnt(16)
	ds_write_b128 v192, v[246:249] offset:55296
	s_waitcnt lgkmcnt(0)
	s_barrier
; template <class Epi, class ColV>
; DI void gemm_tile(const bf16_t* __restrict__ A, int lda, const bf16_t* __restrict__ Bt, int ldb, int K, int m0, int n0, unsigned char* smem, Epi epi, ColV colv, const bf16_t* __restrict__ HYT = nullptr) {
;     ...
;     auto step = [&](int kt, u32x4 (&ldset)[8], const u32x4 (&stset)[8]) {
;         const int buf = kt & 1;
;         if (kt + 2 < nk) gload(ldset, kt + 2);
;         const bf16_t* Ab = As + (buf * 128 + 64 * wr + li) * LS + 8 * lh;
;         const bf16_t* Bb = Bs + (buf * 128 + 64 * wc + li) * LS + 8 * lh;
;         bf16x8 fa[2][2], fb[2][2], ga[2][2], gb[2][2];
; #pragma unroll
;         for (int k2 = 0; k2 < 2; ++k2) { fa[k2][0] = ld8(Ab + 16 * k2); fa[k2][1] = ld8(Ab + 32 * LS + 16 * k2); fb[k2][0] = ld8(Bb + 16 * k2); fb[k2][1] = ld8(Bb + 32 * LS + 16 * k2); }
;         __builtin_amdgcn_sched_barrier(0);
; #pragma unroll
;         for (int k2 = 0; k2 < 2; ++k2) {
;             acc[0][0] = MFMA(fa[k2][0], fb[k2][0], acc[0][0]); acc[0][1] = MFMA(fa[k2][0], fb[k2][1], acc[0][1]);
;             acc[1][0] = MFMA(fa[k2][1], fb[k2][0], acc[1][0]); acc[1][1] = MFMA(fa[k2][1], fb[k2][1], acc[1][1]);
;         }
; #pragma unroll
;         for (int k2 = 0; k2 < 2; ++k2) { const int ks = 2 + k2; ga[k2][0] = ld8(Ab + 16 * ks); ga[k2][1] = ld8(Ab + 32 * LS + 16 * ks); gb[k2][0] = ld8(Bb + 16 * ks); gb[k2][1] = ld8(Bb + 32 * LS + 16 * ks); }
; #pragma unroll
;         for (int k2 = 0; k2 < 2; ++k2) {
;             acc[0][0] = MFMA(ga[k2][0], gb[k2][0], acc[0][0]); acc[0][1] = MFMA(ga[k2][0], gb[k2][1], acc[0][1]);
;             acc[1][0] = MFMA(ga[k2][1], gb[k2][0], acc[1][0]); acc[1][1] = MFMA(ga[k2][1], gb[k2][1], acc[1][1]);
;         }
;         if (kt + 1 < nk) sstore(stset, buf ^ 1, kt + 1);
; #pragma unroll
;         for (int i = 0; i < 8; ++i) { __builtin_amdgcn_sched_group_barrier(0x008, 1, 0); __builtin_amdgcn_sched_group_barrier(0x100, 1, 0); }
; #pragma unroll
;         for (int i = 0; i < 8; ++i) { __builtin_amdgcn_sched_group_barrier(0x008, 1, 0); __builtin_amdgcn_sched_group_barrier(0x200, 1, 0); }
;         __builtin_amdgcn_sched_barrier(0);
;         __syncthreads();
;     };
;     ...
;         XCD_TILE_LOOP(NT / 128, INP / 128, tm, tn) gemm_tile((const bf16_t*)(p.ws + WS_H), 1024, (const bf16_t*)(p.ws + wbase(layer) + W_IN), 1024, 1024, tm * 128, tn * 128, smem, epi, nocol);
	s_setprio 1
	ds_read_b128 v[202:205], v196
	ds_read_b128 v[218:221], v197 offset:36864
	ds_read_b128 v[226:229], v197 offset:41472
	ds_read_b128 v[210:213], v196 offset:4608
	ds_read_b128 v[206:209], v196 offset:32
	ds_read_b128 v[230:233], v197 offset:41504
	ds_read_b128 v[214:217], v196 offset:4640
	ds_read_b128 v[222:225], v197 offset:36896
	s_waitcnt lgkmcnt(6)
	v_mfma_f32_32x32x16_bf16 v[52:67], v[202:205], v[218:221], v[52:67]
	global_load_dwordx4 v[132:135], v[164:165], off offset:1024
	s_waitcnt lgkmcnt(5)
	v_mfma_f32_32x32x16_bf16 v[36:51], v[202:205], v[226:229], v[36:51]
	global_load_dwordx4 v[136:139], v[162:163], off offset:1024
	s_waitcnt lgkmcnt(4)
	v_mfma_f32_32x32x16_bf16 v[4:19], v[210:213], v[226:229], v[4:19]
	global_load_dwordx4 v[140:143], v[160:161], off offset:1024
	s_waitcnt lgkmcnt(2)
	v_mfma_f32_32x32x16_bf16 v[36:51], v[206:209], v[230:233], v[36:51]
	global_load_dwordx4 v[198:201], v[158:159], off offset:1024
	s_waitcnt lgkmcnt(1)
	v_mfma_f32_32x32x16_bf16 v[4:19], v[214:217], v[230:233], v[4:19]
	global_load_dwordx4 v[174:177], v[156:157], off offset:1024
	ds_read_b128 v[230:233], v197 offset:41568
	ds_read_b128 v[202:205], v196 offset:4672
	v_mfma_f32_32x32x16_bf16 v[20:35], v[210:213], v[218:221], v[20:35]
	global_load_dwordx4 v[178:181], v[154:155], off offset:1024
	ds_read_b128 v[218:221], v196 offset:4704
	ds_read_b128 v[210:213], v196 offset:64
	s_waitcnt lgkmcnt(4)
	v_mfma_f32_32x32x16_bf16 v[52:67], v[206:209], v[222:225], v[52:67]
	global_load_dwordx4 v[242:245], v[152:153], off offset:1024
	ds_read_b128 v[226:229], v197 offset:36960
	ds_read_b128 v[206:209], v197 offset:41536
	v_mfma_f32_32x32x16_bf16 v[20:35], v[214:217], v[222:225], v[20:35]
	global_load_dwordx4 v[246:249], v[146:147], off offset:1024
	ds_read_b128 v[222:225], v197 offset:36928
	ds_read_b128 v[214:217], v196 offset:96
	s_waitcnt lgkmcnt(1)
	v_mfma_f32_32x32x16_bf16 v[52:67], v[210:213], v[222:225], v[52:67]
	s_waitcnt vmcnt(23)
	ds_write_b128 v167, v[68:71]
	v_mfma_f32_32x32x16_bf16 v[36:51], v[210:213], v[206:209], v[36:51]
	s_waitcnt vmcnt(22)
	ds_write_b128 v167, v[72:75] offset:36864
	v_mfma_f32_32x32x16_bf16 v[20:35], v[202:205], v[222:225], v[20:35]
	s_waitcnt vmcnt(21)
	ds_write_b128 v190, v[76:79]
	v_mfma_f32_32x32x16_bf16 v[4:19], v[202:205], v[206:209], v[4:19]
	s_waitcnt vmcnt(20)
	ds_write_b128 v190, v[80:83] offset:36864
	s_waitcnt lgkmcnt(4)
	v_mfma_f32_32x32x16_bf16 v[52:67], v[214:217], v[226:229], v[52:67]
	s_waitcnt vmcnt(19)
	ds_write_b128 v191, v[84:87]
	v_mfma_f32_32x32x16_bf16 v[36:51], v[214:217], v[230:233], v[36:51]
	s_setprio 0
	s_waitcnt vmcnt(18)
	ds_write_b128 v191, v[88:91] offset:36864
	v_mfma_f32_32x32x16_bf16 v[20:35], v[218:221], v[226:229], v[20:35]
	s_waitcnt vmcnt(17)
	ds_write_b128 v192, v[92:95]
	v_mfma_f32_32x32x16_bf16 v[4:19], v[218:221], v[230:233], v[4:19]
	s_waitcnt vmcnt(16)
	ds_write_b128 v192, v[104:107] offset:36864
	s_waitcnt lgkmcnt(0)
	s_barrier
	s_setprio 1
	ds_read_b128 v[202:205], v194
	ds_read_b128 v[218:221], v195 offset:36864
	ds_read_b128 v[226:229], v195 offset:41472
	ds_read_b128 v[210:213], v194 offset:4608
	ds_read_b128 v[206:209], v194 offset:32
	ds_read_b128 v[230:233], v195 offset:41504
	ds_read_b128 v[214:217], v194 offset:4640
	ds_read_b128 v[222:225], v195 offset:36896
	s_waitcnt lgkmcnt(6)
	v_mfma_f32_32x32x16_bf16 v[52:67], v[202:205], v[218:221], v[52:67]
	global_load_dwordx4 v[68:71], v[164:165], off offset:1152
	s_waitcnt lgkmcnt(5)
	v_mfma_f32_32x32x16_bf16 v[36:51], v[202:205], v[226:229], v[36:51]
	global_load_dwordx4 v[72:75], v[162:163], off offset:1152
	s_waitcnt lgkmcnt(4)
	v_mfma_f32_32x32x16_bf16 v[4:19], v[210:213], v[226:229], v[4:19]
	global_load_dwordx4 v[76:79], v[160:161], off offset:1152
	s_waitcnt lgkmcnt(2)
	v_mfma_f32_32x32x16_bf16 v[36:51], v[206:209], v[230:233], v[36:51]
	global_load_dwordx4 v[80:83], v[158:159], off offset:1152
	s_waitcnt lgkmcnt(1)
	v_mfma_f32_32x32x16_bf16 v[4:19], v[214:217], v[230:233], v[4:19]
	global_load_dwordx4 v[84:87], v[156:157], off offset:1152
	ds_read_b128 v[230:233], v195 offset:41568
	ds_read_b128 v[202:205], v194 offset:4672
	v_mfma_f32_32x32x16_bf16 v[20:35], v[210:213], v[218:221], v[20:35]
	global_load_dwordx4 v[88:91], v[154:155], off offset:1152
	ds_read_b128 v[218:221], v194 offset:4704
	ds_read_b128 v[210:213], v194 offset:64
	s_waitcnt lgkmcnt(4)
	v_mfma_f32_32x32x16_bf16 v[52:67], v[206:209], v[222:225], v[52:67]
	global_load_dwordx4 v[92:95], v[152:153], off offset:1152
	ds_read_b128 v[226:229], v195 offset:36960
	ds_read_b128 v[206:209], v195 offset:41536
	v_mfma_f32_32x32x16_bf16 v[20:35], v[214:217], v[222:225], v[20:35]
	global_load_dwordx4 v[104:107], v[146:147], off offset:1152
	ds_read_b128 v[222:225], v195 offset:36928
	ds_read_b128 v[214:217], v194 offset:96
	s_waitcnt lgkmcnt(1)
	v_mfma_f32_32x32x16_bf16 v[52:67], v[210:213], v[222:225], v[52:67]
	s_waitcnt vmcnt(23)
	ds_write_b128 v167, v[96:99] offset:18432
	v_mfma_f32_32x32x16_bf16 v[36:51], v[210:213], v[206:209], v[36:51]
	s_waitcnt vmcnt(22)
	ds_write_b128 v167, v[100:103] offset:55296
	v_mfma_f32_32x32x16_bf16 v[20:35], v[202:205], v[222:225], v[20:35]
	s_waitcnt vmcnt(21)
	ds_write_b128 v190, v[108:111] offset:18432
	v_mfma_f32_32x32x16_bf16 v[4:19], v[202:205], v[206:209], v[4:19]
	s_waitcnt vmcnt(20)
	ds_write_b128 v190, v[112:115] offset:55296
	s_waitcnt lgkmcnt(4)
	v_mfma_f32_32x32x16_bf16 v[52:67], v[214:217], v[226:229], v[52:67]
	s_waitcnt vmcnt(19)
	ds_write_b128 v191, v[116:119] offset:18432
	v_mfma_f32_32x32x16_bf16 v[36:51], v[214:217], v[230:233], v[36:51]
	s_setprio 0
	s_waitcnt vmcnt(18)
	ds_write_b128 v191, v[120:123] offset:55296
	v_mfma_f32_32x32x16_bf16 v[20:35], v[218:221], v[226:229], v[20:35]
	s_waitcnt vmcnt(17)
	ds_write_b128 v192, v[124:127] offset:18432
	v_mfma_f32_32x32x16_bf16 v[4:19], v[218:221], v[230:233], v[4:19]
	s_waitcnt vmcnt(16)
	ds_write_b128 v192, v[128:131] offset:55296
	s_waitcnt lgkmcnt(0)
	s_barrier
; template <class Epi, class ColV>
; DI void gemm_tile(const bf16_t* __restrict__ A, int lda, const bf16_t* __restrict__ Bt, int ldb, int K, int m0, int n0, unsigned char* smem, Epi epi, ColV colv, const bf16_t* __restrict__ HYT = nullptr) {
;     ...
;     auto step = [&](int kt, u32x4 (&ldset)[8], const u32x4 (&stset)[8]) {
;         const int buf = kt & 1;
;         if (kt + 2 < nk) gload(ldset, kt + 2);
;         const bf16_t* Ab = As + (buf * 128 + 64 * wr + li) * LS + 8 * lh;
;         const bf16_t* Bb = Bs + (buf * 128 + 64 * wc + li) * LS + 8 * lh;
;         bf16x8 fa[2][2], fb[2][2], ga[2][2], gb[2][2];
; #pragma unroll
;         for (int k2 = 0; k2 < 2; ++k2) { fa[k2][0] = ld8(Ab + 16 * k2); fa[k2][1] = ld8(Ab + 32 * LS + 16 * k2); fb[k2][0] = ld8(Bb + 16 * k2); fb[k2][1] = ld8(Bb + 32 * LS + 16 * k2); }
;         __builtin_amdgcn_sched_barrier(0);
; #pragma unroll
;         for (int k2 = 0; k2 < 2; ++k2) {
;             acc[0][0] = MFMA(fa[k2][0], fb[k2][0], acc[0][0]); acc[0][1] = MFMA(fa[k2][0], fb[k2][1], acc[0][1]);
;             acc[1][0] = MFMA(fa[k2][1], fb[k2][0], acc[1][0]); acc[1][1] = MFMA(fa[k2][1], fb[k2][1], acc[1][1]);
;         }
; #pragma unroll
;         for (int k2 = 0; k2 < 2; ++k2) { const int ks = 2 + k2; ga[k2][0] = ld8(Ab + 16 * ks); ga[k2][1] = ld8(Ab + 32 * LS + 16 * ks); gb[k2][0] = ld8(Bb + 16 * ks); gb[k2][1] = ld8(Bb + 32 * LS + 16 * ks); }
; #pragma unroll
;         for (int k2 = 0; k2 < 2; ++k2) {
;             acc[0][0] = MFMA(ga[k2][0], gb[k2][0], acc[0][0]); acc[0][1] = MFMA(ga[k2][0], gb[k2][1], acc[0][1]);
;             acc[1][0] = MFMA(ga[k2][1], gb[k2][0], acc[1][0]); acc[1][1] = MFMA(ga[k2][1], gb[k2][1], acc[1][1]);
;         }
;         if (kt + 1 < nk) sstore(stset, buf ^ 1, kt + 1);
; #pragma unroll
;         for (int i = 0; i < 8; ++i) { __builtin_amdgcn_sched_group_barrier(0x008, 1, 0); __builtin_amdgcn_sched_group_barrier(0x100, 1, 0); }
; #pragma unroll
;         for (int i = 0; i < 8; ++i) { __builtin_amdgcn_sched_group_barrier(0x008, 1, 0); __builtin_amdgcn_sched_group_barrier(0x200, 1, 0); }
;         __builtin_amdgcn_sched_barrier(0);
;         __syncthreads();
;     };
;     ...
;         XCD_TILE_LOOP(NT / 128, INP / 128, tm, tn) gemm_tile((const bf16_t*)(p.ws + WS_H), 1024, (const bf16_t*)(p.ws + wbase(layer) + W_IN), 1024, 1024, tm * 128, tn * 128, smem, epi, nocol);
	s_setprio 1
	ds_read_b128 v[202:205], v196
	ds_read_b128 v[218:221], v197 offset:36864
	ds_read_b128 v[226:229], v197 offset:41472
	ds_read_b128 v[210:213], v196 offset:4608
	ds_read_b128 v[206:209], v196 offset:32
	ds_read_b128 v[230:233], v197 offset:41504
	ds_read_b128 v[214:217], v196 offset:4640
	ds_read_b128 v[222:225], v197 offset:36896
	s_waitcnt lgkmcnt(6)
	v_mfma_f32_32x32x16_bf16 v[52:67], v[202:205], v[218:221], v[52:67]
	global_load_dwordx4 v[96:99], v[164:165], off offset:1280
	s_waitcnt lgkmcnt(5)
	v_mfma_f32_32x32x16_bf16 v[36:51], v[202:205], v[226:229], v[36:51]
	global_load_dwordx4 v[100:103], v[162:163], off offset:1280
	s_waitcnt lgkmcnt(4)
	v_mfma_f32_32x32x16_bf16 v[4:19], v[210:213], v[226:229], v[4:19]
	global_load_dwordx4 v[108:111], v[160:161], off offset:1280
	s_waitcnt lgkmcnt(2)
	v_mfma_f32_32x32x16_bf16 v[36:51], v[206:209], v[230:233], v[36:51]
	global_load_dwordx4 v[112:115], v[158:159], off offset:1280
	s_waitcnt lgkmcnt(1)
	v_mfma_f32_32x32x16_bf16 v[4:19], v[214:217], v[230:233], v[4:19]
	global_load_dwordx4 v[116:119], v[156:157], off offset:1280
	ds_read_b128 v[230:233], v197 offset:41568
	ds_read_b128 v[202:205], v196 offset:4672
	v_mfma_f32_32x32x16_bf16 v[20:35], v[210:213], v[218:221], v[20:35]
	global_load_dwordx4 v[120:123], v[154:155], off offset:1280
	ds_read_b128 v[218:221], v196 offset:4704
	ds_read_b128 v[210:213], v196 offset:64
	s_waitcnt lgkmcnt(4)
	v_mfma_f32_32x32x16_bf16 v[52:67], v[206:209], v[222:225], v[52:67]
	global_load_dwordx4 v[124:127], v[152:153], off offset:1280
	ds_read_b128 v[226:229], v197 offset:36960
	ds_read_b128 v[206:209], v197 offset:41536
	v_mfma_f32_32x32x16_bf16 v[20:35], v[214:217], v[222:225], v[20:35]
	global_load_dwordx4 v[128:131], v[146:147], off offset:1280
	ds_read_b128 v[222:225], v197 offset:36928
	ds_read_b128 v[214:217], v196 offset:96
	s_waitcnt lgkmcnt(1)
	v_mfma_f32_32x32x16_bf16 v[52:67], v[210:213], v[222:225], v[52:67]
	s_waitcnt vmcnt(23)
	ds_write_b128 v167, v[132:135]
	v_mfma_f32_32x32x16_bf16 v[36:51], v[210:213], v[206:209], v[36:51]
	s_waitcnt vmcnt(22)
	ds_write_b128 v167, v[136:139] offset:36864
	v_mfma_f32_32x32x16_bf16 v[20:35], v[202:205], v[222:225], v[20:35]
	s_waitcnt vmcnt(21)
	ds_write_b128 v190, v[140:143]
	v_mfma_f32_32x32x16_bf16 v[4:19], v[202:205], v[206:209], v[4:19]
	s_waitcnt vmcnt(20)
	ds_write_b128 v190, v[198:201] offset:36864
	s_waitcnt lgkmcnt(4)
	v_mfma_f32_32x32x16_bf16 v[52:67], v[214:217], v[226:229], v[52:67]
	s_waitcnt vmcnt(19)
	ds_write_b128 v191, v[174:177]
	v_mfma_f32_32x32x16_bf16 v[36:51], v[214:217], v[230:233], v[36:51]
	s_setprio 0
	s_waitcnt vmcnt(18)
	ds_write_b128 v191, v[178:181] offset:36864
	v_mfma_f32_32x32x16_bf16 v[20:35], v[218:221], v[226:229], v[20:35]
	s_waitcnt vmcnt(17)
	ds_write_b128 v192, v[242:245]
	v_mfma_f32_32x32x16_bf16 v[4:19], v[218:221], v[230:233], v[4:19]
	s_waitcnt vmcnt(16)
	ds_write_b128 v192, v[246:249] offset:36864
	s_waitcnt lgkmcnt(0)
	s_barrier
	s_setprio 1
	ds_read_b128 v[202:205], v194
	ds_read_b128 v[218:221], v195 offset:36864
	ds_read_b128 v[226:229], v195 offset:41472
	ds_read_b128 v[210:213], v194 offset:4608
	ds_read_b128 v[206:209], v194 offset:32
	ds_read_b128 v[230:233], v195 offset:41504
	ds_read_b128 v[214:217], v194 offset:4640
	ds_read_b128 v[222:225], v195 offset:36896
	s_waitcnt lgkmcnt(6)
	v_mfma_f32_32x32x16_bf16 v[52:67], v[202:205], v[218:221], v[52:67]
	global_load_dwordx4 v[132:135], v[164:165], off offset:1408
	s_waitcnt lgkmcnt(5)
	v_mfma_f32_32x32x16_bf16 v[36:51], v[202:205], v[226:229], v[36:51]
	global_load_dwordx4 v[136:139], v[162:163], off offset:1408
	s_waitcnt lgkmcnt(4)
	v_mfma_f32_32x32x16_bf16 v[4:19], v[210:213], v[226:229], v[4:19]
	global_load_dwordx4 v[140:143], v[160:161], off offset:1408
	s_waitcnt lgkmcnt(2)
	v_mfma_f32_32x32x16_bf16 v[36:51], v[206:209], v[230:233], v[36:51]
	global_load_dwordx4 v[198:201], v[158:159], off offset:1408
	s_waitcnt lgkmcnt(1)
	v_mfma_f32_32x32x16_bf16 v[4:19], v[214:217], v[230:233], v[4:19]
	global_load_dwordx4 v[174:177], v[156:157], off offset:1408
	ds_read_b128 v[230:233], v195 offset:41568
	ds_read_b128 v[202:205], v194 offset:4672
	v_mfma_f32_32x32x16_bf16 v[20:35], v[210:213], v[218:221], v[20:35]
	global_load_dwordx4 v[178:181], v[154:155], off offset:1408
	ds_read_b128 v[218:221], v194 offset:4704
	ds_read_b128 v[210:213], v194 offset:64
	s_waitcnt lgkmcnt(4)
	v_mfma_f32_32x32x16_bf16 v[52:67], v[206:209], v[222:225], v[52:67]
	global_load_dwordx4 v[242:245], v[152:153], off offset:1408
	ds_read_b128 v[226:229], v195 offset:36960
	ds_read_b128 v[206:209], v195 offset:41536
	v_mfma_f32_32x32x16_bf16 v[20:35], v[214:217], v[222:225], v[20:35]
	global_load_dwordx4 v[246:249], v[146:147], off offset:1408
	ds_read_b128 v[222:225], v195 offset:36928
	ds_read_b128 v[214:217], v194 offset:96
	s_waitcnt lgkmcnt(1)
	v_mfma_f32_32x32x16_bf16 v[52:67], v[210:213], v[222:225], v[52:67]
	s_waitcnt vmcnt(23)
	ds_write_b128 v167, v[68:71] offset:18432
	v_mfma_f32_32x32x16_bf16 v[36:51], v[210:213], v[206:209], v[36:51]
	s_waitcnt vmcnt(22)
	ds_write_b128 v167, v[72:75] offset:55296
	v_mfma_f32_32x32x16_bf16 v[20:35], v[202:205], v[222:225], v[20:35]
	s_waitcnt vmcnt(21)
	ds_write_b128 v190, v[76:79] offset:18432
	v_mfma_f32_32x32x16_bf16 v[4:19], v[202:205], v[206:209], v[4:19]
	s_waitcnt vmcnt(20)
	ds_write_b128 v190, v[80:83] offset:55296
	s_waitcnt lgkmcnt(4)
	v_mfma_f32_32x32x16_bf16 v[52:67], v[214:217], v[226:229], v[52:67]
	s_waitcnt vmcnt(19)
	ds_write_b128 v191, v[84:87] offset:18432
	v_mfma_f32_32x32x16_bf16 v[36:51], v[214:217], v[230:233], v[36:51]
	s_setprio 0
	s_waitcnt vmcnt(18)
	ds_write_b128 v191, v[88:91] offset:55296
	v_mfma_f32_32x32x16_bf16 v[20:35], v[218:221], v[226:229], v[20:35]
	s_waitcnt vmcnt(17)
	ds_write_b128 v192, v[92:95] offset:18432
	v_mfma_f32_32x32x16_bf16 v[4:19], v[218:221], v[230:233], v[4:19]
	s_waitcnt vmcnt(16)
	ds_write_b128 v192, v[104:107] offset:55296
	s_waitcnt lgkmcnt(0)
	s_barrier
; template <class Epi, class ColV>
; DI void gemm_tile(const bf16_t* __restrict__ A, int lda, const bf16_t* __restrict__ Bt, int ldb, int K, int m0, int n0, unsigned char* smem, Epi epi, ColV colv, const bf16_t* __restrict__ HYT = nullptr) {
;     ...
;     auto step = [&](int kt, u32x4 (&ldset)[8], const u32x4 (&stset)[8]) {
;         const int buf = kt & 1;
;         if (kt + 2 < nk) gload(ldset, kt + 2);
;         const bf16_t* Ab = As + (buf * 128 + 64 * wr + li) * LS + 8 * lh;
;         const bf16_t* Bb = Bs + (buf * 128 + 64 * wc + li) * LS + 8 * lh;
;         bf16x8 fa[2][2], fb[2][2], ga[2][2], gb[2][2];
; #pragma unroll
;         for (int k2 = 0; k2 < 2; ++k2) { fa[k2][0] = ld8(Ab + 16 * k2); fa[k2][1] = ld8(Ab + 32 * LS + 16 * k2); fb[k2][0] = ld8(Bb + 16 * k2); fb[k2][1] = ld8(Bb + 32 * LS + 16 * k2); }
;         __builtin_amdgcn_sched_barrier(0);
; #pragma unroll
;         for (int k2 = 0; k2 < 2; ++k2) {
;             acc[0][0] = MFMA(fa[k2][0], fb[k2][0], acc[0][0]); acc[0][1] = MFMA(fa[k2][0], fb[k2][1], acc[0][1]);
;             acc[1][0] = MFMA(fa[k2][1], fb[k2][0], acc[1][0]); acc[1][1] = MFMA(fa[k2][1], fb[k2][1], acc[1][1]);
;         }
; #pragma unroll
;         for (int k2 = 0; k2 < 2; ++k2) { const int ks = 2 + k2; ga[k2][0] = ld8(Ab + 16 * ks); ga[k2][1] = ld8(Ab + 32 * LS + 16 * ks); gb[k2][0] = ld8(Bb + 16 * ks); gb[k2][1] = ld8(Bb + 32 * LS + 16 * ks); }
; #pragma unroll
;         for (int k2 = 0; k2 < 2; ++k2) {
;             acc[0][0] = MFMA(ga[k2][0], gb[k2][0], acc[0][0]); acc[0][1] = MFMA(ga[k2][0], gb[k2][1], acc[0][1]);
;             acc[1][0] = MFMA(ga[k2][1], gb[k2][0], acc[1][0]); acc[1][1] = MFMA(ga[k2][1], gb[k2][1], acc[1][1]);
;         }
;         if (kt + 1 < nk) sstore(stset, buf ^ 1, kt + 1);
; #pragma unroll
;         for (int i = 0; i < 8; ++i) { __builtin_amdgcn_sched_group_barrier(0x008, 1, 0); __builtin_amdgcn_sched_group_barrier(0x100, 1, 0); }
; #pragma unroll
;         for (int i = 0; i < 8; ++i) { __builtin_amdgcn_sched_group_barrier(0x008, 1, 0); __builtin_amdgcn_sched_group_barrier(0x200, 1, 0); }
;         __builtin_amdgcn_sched_barrier(0);
;         __syncthreads();
;     };
;     ...
;         XCD_TILE_LOOP(NT / 128, INP / 128, tm, tn) gemm_tile((const bf16_t*)(p.ws + WS_H), 1024, (const bf16_t*)(p.ws + wbase(layer) + W_IN), 1024, 1024, tm * 128, tn * 128, smem, epi, nocol);
	s_setprio 1
	ds_read_b128 v[202:205], v196
	ds_read_b128 v[218:221], v197 offset:36864
	ds_read_b128 v[226:229], v197 offset:41472
	ds_read_b128 v[210:213], v196 offset:4608
	ds_read_b128 v[206:209], v196 offset:32
	ds_read_b128 v[230:233], v197 offset:41504
	ds_read_b128 v[214:217], v196 offset:4640
	ds_read_b128 v[222:225], v197 offset:36896
	s_waitcnt lgkmcnt(6)
	v_mfma_f32_32x32x16_bf16 v[52:67], v[202:205], v[218:221], v[52:67]
	global_load_dwordx4 v[68:71], v[164:165], off offset:1536
	s_waitcnt lgkmcnt(5)
	v_mfma_f32_32x32x16_bf16 v[36:51], v[202:205], v[226:229], v[36:51]
	global_load_dwordx4 v[72:75], v[162:163], off offset:1536
	s_waitcnt lgkmcnt(4)
	v_mfma_f32_32x32x16_bf16 v[4:19], v[210:213], v[226:229], v[4:19]
	global_load_dwordx4 v[76:79], v[160:161], off offset:1536
	s_waitcnt lgkmcnt(2)
	v_mfma_f32_32x32x16_bf16 v[36:51], v[206:209], v[230:233], v[36:51]
	global_load_dwordx4 v[80:83], v[158:159], off offset:1536
	s_waitcnt lgkmcnt(1)
	v_mfma_f32_32x32x16_bf16 v[4:19], v[214:217], v[230:233], v[4:19]
	global_load_dwordx4 v[84:87], v[156:157], off offset:1536
	ds_read_b128 v[230:233], v197 offset:41568
	ds_read_b128 v[202:205], v196 offset:4672
	v_mfma_f32_32x32x16_bf16 v[20:35], v[210:213], v[218:221], v[20:35]
	global_load_dwordx4 v[88:91], v[154:155], off offset:1536
	ds_read_b128 v[218:221], v196 offset:4704
	ds_read_b128 v[210:213], v196 offset:64
	s_waitcnt lgkmcnt(4)
	v_mfma_f32_32x32x16_bf16 v[52:67], v[206:209], v[222:225], v[52:67]
	global_load_dwordx4 v[92:95], v[152:153], off offset:1536
	ds_read_b128 v[226:229], v197 offset:36960
	ds_read_b128 v[206:209], v197 offset:41536
	v_mfma_f32_32x32x16_bf16 v[20:35], v[214:217], v[222:225], v[20:35]
	global_load_dwordx4 v[104:107], v[146:147], off offset:1536
	ds_read_b128 v[222:225], v197 offset:36928
	ds_read_b128 v[214:217], v196 offset:96
	s_waitcnt lgkmcnt(1)
	v_mfma_f32_32x32x16_bf16 v[52:67], v[210:213], v[222:225], v[52:67]
	s_waitcnt vmcnt(23)
	ds_write_b128 v167, v[96:99]
	v_mfma_f32_32x32x16_bf16 v[36:51], v[210:213], v[206:209], v[36:51]
	s_waitcnt vmcnt(22)
	ds_write_b128 v167, v[100:103] offset:36864
	v_mfma_f32_32x32x16_bf16 v[20:35], v[202:205], v[222:225], v[20:35]
	s_waitcnt vmcnt(21)
	ds_write_b128 v190, v[108:111]
	v_mfma_f32_32x32x16_bf16 v[4:19], v[202:205], v[206:209], v[4:19]
	s_waitcnt vmcnt(20)
	ds_write_b128 v190, v[112:115] offset:36864
	s_waitcnt lgkmcnt(4)
	v_mfma_f32_32x32x16_bf16 v[52:67], v[214:217], v[226:229], v[52:67]
	s_waitcnt vmcnt(19)
	ds_write_b128 v191, v[116:119]
	v_mfma_f32_32x32x16_bf16 v[36:51], v[214:217], v[230:233], v[36:51]
	s_setprio 0
	s_waitcnt vmcnt(18)
	ds_write_b128 v191, v[120:123] offset:36864
	v_mfma_f32_32x32x16_bf16 v[20:35], v[218:221], v[226:229], v[20:35]
	s_waitcnt vmcnt(17)
	ds_write_b128 v192, v[124:127]
	v_mfma_f32_32x32x16_bf16 v[4:19], v[218:221], v[230:233], v[4:19]
	s_waitcnt vmcnt(16)
	ds_write_b128 v192, v[128:131] offset:36864
	s_waitcnt lgkmcnt(0)
	s_barrier
	s_setprio 1
	ds_read_b128 v[202:205], v194
	ds_read_b128 v[218:221], v195 offset:36864
	ds_read_b128 v[226:229], v195 offset:41472
	ds_read_b128 v[210:213], v194 offset:4608
	ds_read_b128 v[206:209], v194 offset:32
	ds_read_b128 v[230:233], v195 offset:41504
	ds_read_b128 v[214:217], v194 offset:4640
	ds_read_b128 v[222:225], v195 offset:36896
	s_waitcnt lgkmcnt(6)
	v_mfma_f32_32x32x16_bf16 v[52:67], v[202:205], v[218:221], v[52:67]
	global_load_dwordx4 v[96:99], v[164:165], off offset:1664
	s_waitcnt lgkmcnt(5)
	v_mfma_f32_32x32x16_bf16 v[36:51], v[202:205], v[226:229], v[36:51]
	global_load_dwordx4 v[100:103], v[162:163], off offset:1664
	s_waitcnt lgkmcnt(4)
	v_mfma_f32_32x32x16_bf16 v[4:19], v[210:213], v[226:229], v[4:19]
	global_load_dwordx4 v[108:111], v[160:161], off offset:1664
	s_waitcnt lgkmcnt(2)
	v_mfma_f32_32x32x16_bf16 v[36:51], v[206:209], v[230:233], v[36:51]
	global_load_dwordx4 v[112:115], v[158:159], off offset:1664
	s_waitcnt lgkmcnt(1)
	v_mfma_f32_32x32x16_bf16 v[4:19], v[214:217], v[230:233], v[4:19]
	global_load_dwordx4 v[116:119], v[156:157], off offset:1664
	ds_read_b128 v[230:233], v195 offset:41568
	ds_read_b128 v[202:205], v194 offset:4672
	v_mfma_f32_32x32x16_bf16 v[20:35], v[210:213], v[218:221], v[20:35]
	global_load_dwordx4 v[120:123], v[154:155], off offset:1664
	ds_read_b128 v[218:221], v194 offset:4704
	ds_read_b128 v[210:213], v194 offset:64
	s_waitcnt lgkmcnt(4)
	v_mfma_f32_32x32x16_bf16 v[52:67], v[206:209], v[222:225], v[52:67]
	global_load_dwordx4 v[124:127], v[152:153], off offset:1664
	ds_read_b128 v[226:229], v195 offset:36960
	ds_read_b128 v[206:209], v195 offset:41536
	v_mfma_f32_32x32x16_bf16 v[20:35], v[214:217], v[222:225], v[20:35]
	global_load_dwordx4 v[128:131], v[146:147], off offset:1664
	ds_read_b128 v[222:225], v195 offset:36928
	ds_read_b128 v[214:217], v194 offset:96
	s_waitcnt lgkmcnt(1)
	v_mfma_f32_32x32x16_bf16 v[52:67], v[210:213], v[222:225], v[52:67]
	s_waitcnt vmcnt(23)
	ds_write_b128 v167, v[132:135] offset:18432
	v_mfma_f32_32x32x16_bf16 v[36:51], v[210:213], v[206:209], v[36:51]
	s_waitcnt vmcnt(22)
	ds_write_b128 v167, v[136:139] offset:55296
	v_mfma_f32_32x32x16_bf16 v[20:35], v[202:205], v[222:225], v[20:35]
	s_waitcnt vmcnt(21)
	ds_write_b128 v190, v[140:143] offset:18432
	v_mfma_f32_32x32x16_bf16 v[4:19], v[202:205], v[206:209], v[4:19]
	s_waitcnt vmcnt(20)
	ds_write_b128 v190, v[198:201] offset:55296
	s_waitcnt lgkmcnt(4)
	v_mfma_f32_32x32x16_bf16 v[52:67], v[214:217], v[226:229], v[52:67]
	s_waitcnt vmcnt(19)
	ds_write_b128 v191, v[174:177] offset:18432
	v_mfma_f32_32x32x16_bf16 v[36:51], v[214:217], v[230:233], v[36:51]
	s_setprio 0
	s_waitcnt vmcnt(18)
	ds_write_b128 v191, v[178:181] offset:55296
	v_mfma_f32_32x32x16_bf16 v[20:35], v[218:221], v[226:229], v[20:35]
	s_waitcnt vmcnt(17)
	ds_write_b128 v192, v[242:245] offset:18432
	v_mfma_f32_32x32x16_bf16 v[4:19], v[218:221], v[230:233], v[4:19]
	s_waitcnt vmcnt(16)
	ds_write_b128 v192, v[246:249] offset:55296
	s_waitcnt lgkmcnt(0)
	s_barrier
; template <class Epi, class ColV>
; DI void gemm_tile(const bf16_t* __restrict__ A, int lda, const bf16_t* __restrict__ Bt, int ldb, int K, int m0, int n0, unsigned char* smem, Epi epi, ColV colv, const bf16_t* __restrict__ HYT = nullptr) {
;     ...
;     auto step = [&](int kt, u32x4 (&ldset)[8], const u32x4 (&stset)[8]) {
;         const int buf = kt & 1;
;         if (kt + 2 < nk) gload(ldset, kt + 2);
;         const bf16_t* Ab = As + (buf * 128 + 64 * wr + li) * LS + 8 * lh;
;         const bf16_t* Bb = Bs + (buf * 128 + 64 * wc + li) * LS + 8 * lh;
;         bf16x8 fa[2][2], fb[2][2], ga[2][2], gb[2][2];
; #pragma unroll
;         for (int k2 = 0; k2 < 2; ++k2) { fa[k2][0] = ld8(Ab + 16 * k2); fa[k2][1] = ld8(Ab + 32 * LS + 16 * k2); fb[k2][0] = ld8(Bb + 16 * k2); fb[k2][1] = ld8(Bb + 32 * LS + 16 * k2); }
;         __builtin_amdgcn_sched_barrier(0);
; #pragma unroll
;         for (int k2 = 0; k2 < 2; ++k2) {
;             acc[0][0] = MFMA(fa[k2][0], fb[k2][0], acc[0][0]); acc[0][1] = MFMA(fa[k2][0], fb[k2][1], acc[0][1]);
;             acc[1][0] = MFMA(fa[k2][1], fb[k2][0], acc[1][0]); acc[1][1] = MFMA(fa[k2][1], fb[k2][1], acc[1][1]);
;         }
; #pragma unroll
;         for (int k2 = 0; k2 < 2; ++k2) { const int ks = 2 + k2; ga[k2][0] = ld8(Ab + 16 * ks); ga[k2][1] = ld8(Ab + 32 * LS + 16 * ks); gb[k2][0] = ld8(Bb + 16 * ks); gb[k2][1] = ld8(Bb + 32 * LS + 16 * ks); }
; #pragma unroll
;         for (int k2 = 0; k2 < 2; ++k2) {
;             acc[0][0] = MFMA(ga[k2][0], gb[k2][0], acc[0][0]); acc[0][1] = MFMA(ga[k2][0], gb[k2][1], acc[0][1]);
;             acc[1][0] = MFMA(ga[k2][1], gb[k2][0], acc[1][0]); acc[1][1] = MFMA(ga[k2][1], gb[k2][1], acc[1][1]);
;         }
;         if (kt + 1 < nk) sstore(stset, buf ^ 1, kt + 1);
; #pragma unroll
;         for (int i = 0; i < 8; ++i) { __builtin_amdgcn_sched_group_barrier(0x008, 1, 0); __builtin_amdgcn_sched_group_barrier(0x100, 1, 0); }
; #pragma unroll
;         for (int i = 0; i < 8; ++i) { __builtin_amdgcn_sched_group_barrier(0x008, 1, 0); __builtin_amdgcn_sched_group_barrier(0x200, 1, 0); }
;         __builtin_amdgcn_sched_barrier(0);
;         __syncthreads();
;     };
;     ...
;         XCD_TILE_LOOP(NT / 128, INP / 128, tm, tn) gemm_tile((const bf16_t*)(p.ws + WS_H), 1024, (const bf16_t*)(p.ws + wbase(layer) + W_IN), 1024, 1024, tm * 128, tn * 128, smem, epi, nocol);
	s_setprio 1
	ds_read_b128 v[202:205], v196
	ds_read_b128 v[218:221], v197 offset:36864
	ds_read_b128 v[226:229], v197 offset:41472
	ds_read_b128 v[210:213], v196 offset:4608
	ds_read_b128 v[206:209], v196 offset:32
	ds_read_b128 v[230:233], v197 offset:41504
	ds_read_b128 v[214:217], v196 offset:4640
	ds_read_b128 v[222:225], v197 offset:36896
	s_waitcnt lgkmcnt(6)
	v_mfma_f32_32x32x16_bf16 v[52:67], v[202:205], v[218:221], v[52:67]
	global_load_dwordx4 v[132:135], v[164:165], off offset:1792
	s_waitcnt lgkmcnt(5)
	v_mfma_f32_32x32x16_bf16 v[36:51], v[202:205], v[226:229], v[36:51]
	global_load_dwordx4 v[136:139], v[162:163], off offset:1792
	s_waitcnt lgkmcnt(4)
	v_mfma_f32_32x32x16_bf16 v[4:19], v[210:213], v[226:229], v[4:19]
	global_load_dwordx4 v[140:143], v[160:161], off offset:1792
	s_waitcnt lgkmcnt(2)
	v_mfma_f32_32x32x16_bf16 v[36:51], v[206:209], v[230:233], v[36:51]
	global_load_dwordx4 v[198:201], v[158:159], off offset:1792
	s_waitcnt lgkmcnt(1)
	v_mfma_f32_32x32x16_bf16 v[4:19], v[214:217], v[230:233], v[4:19]
	global_load_dwordx4 v[174:177], v[156:157], off offset:1792
	ds_read_b128 v[230:233], v197 offset:41568
	ds_read_b128 v[202:205], v196 offset:4672
	v_mfma_f32_32x32x16_bf16 v[20:35], v[210:213], v[218:221], v[20:35]
	global_load_dwordx4 v[178:181], v[154:155], off offset:1792
	ds_read_b128 v[218:221], v196 offset:4704
	ds_read_b128 v[210:213], v196 offset:64
	s_waitcnt lgkmcnt(4)
	v_mfma_f32_32x32x16_bf16 v[52:67], v[206:209], v[222:225], v[52:67]
	global_load_dwordx4 v[242:245], v[152:153], off offset:1792
	ds_read_b128 v[226:229], v197 offset:36960
	ds_read_b128 v[206:209], v197 offset:41536
	v_mfma_f32_32x32x16_bf16 v[20:35], v[214:217], v[222:225], v[20:35]
	global_load_dwordx4 v[246:249], v[146:147], off offset:1792
	ds_read_b128 v[222:225], v197 offset:36928
	ds_read_b128 v[214:217], v196 offset:96
	s_waitcnt lgkmcnt(1)
	v_mfma_f32_32x32x16_bf16 v[52:67], v[210:213], v[222:225], v[52:67]
	s_waitcnt vmcnt(23)
	ds_write_b128 v167, v[68:71]
	v_mfma_f32_32x32x16_bf16 v[36:51], v[210:213], v[206:209], v[36:51]
	s_waitcnt vmcnt(22)
	ds_write_b128 v167, v[72:75] offset:36864
	v_mfma_f32_32x32x16_bf16 v[20:35], v[202:205], v[222:225], v[20:35]
	s_waitcnt vmcnt(21)
	ds_write_b128 v190, v[76:79]
	v_mfma_f32_32x32x16_bf16 v[4:19], v[202:205], v[206:209], v[4:19]
	s_waitcnt vmcnt(20)
	ds_write_b128 v190, v[80:83] offset:36864
	s_waitcnt lgkmcnt(4)
	v_mfma_f32_32x32x16_bf16 v[52:67], v[214:217], v[226:229], v[52:67]
	s_waitcnt vmcnt(19)
	ds_write_b128 v191, v[84:87]
	v_mfma_f32_32x32x16_bf16 v[36:51], v[214:217], v[230:233], v[36:51]
	s_setprio 0
	s_waitcnt vmcnt(18)
	ds_write_b128 v191, v[88:91] offset:36864
	v_mfma_f32_32x32x16_bf16 v[20:35], v[218:221], v[226:229], v[20:35]
	s_waitcnt vmcnt(17)
	ds_write_b128 v192, v[92:95]
	v_mfma_f32_32x32x16_bf16 v[4:19], v[218:221], v[230:233], v[4:19]
	s_waitcnt vmcnt(16)
	ds_write_b128 v192, v[104:107] offset:36864
	s_waitcnt lgkmcnt(0)
	s_barrier
	s_setprio 1
	ds_read_b128 v[202:205], v194
	ds_read_b128 v[218:221], v195 offset:36864
	ds_read_b128 v[226:229], v195 offset:41472
	ds_read_b128 v[210:213], v194 offset:4608
	ds_read_b128 v[206:209], v194 offset:32
	ds_read_b128 v[230:233], v195 offset:41504
	ds_read_b128 v[214:217], v194 offset:4640
	ds_read_b128 v[222:225], v195 offset:36896
	s_waitcnt lgkmcnt(6)
	v_mfma_f32_32x32x16_bf16 v[52:67], v[202:205], v[218:221], v[52:67]
	global_load_dwordx4 v[68:71], v[164:165], off offset:1920
	s_waitcnt lgkmcnt(5)
	v_mfma_f32_32x32x16_bf16 v[36:51], v[202:205], v[226:229], v[36:51]
	global_load_dwordx4 v[72:75], v[162:163], off offset:1920
	s_waitcnt lgkmcnt(4)
	v_mfma_f32_32x32x16_bf16 v[4:19], v[210:213], v[226:229], v[4:19]
	global_load_dwordx4 v[76:79], v[160:161], off offset:1920
	s_waitcnt lgkmcnt(2)
	v_mfma_f32_32x32x16_bf16 v[36:51], v[206:209], v[230:233], v[36:51]
	global_load_dwordx4 v[80:83], v[158:159], off offset:1920
	s_waitcnt lgkmcnt(1)
	v_mfma_f32_32x32x16_bf16 v[4:19], v[214:217], v[230:233], v[4:19]
	global_load_dwordx4 v[84:87], v[156:157], off offset:1920
	ds_read_b128 v[230:233], v195 offset:41568
	ds_read_b128 v[202:205], v194 offset:4672
	v_mfma_f32_32x32x16_bf16 v[20:35], v[210:213], v[218:221], v[20:35]
	global_load_dwordx4 v[88:91], v[154:155], off offset:1920
	ds_read_b128 v[218:221], v194 offset:4704
	ds_read_b128 v[210:213], v194 offset:64
	s_waitcnt lgkmcnt(4)
	v_mfma_f32_32x32x16_bf16 v[52:67], v[206:209], v[222:225], v[52:67]
	global_load_dwordx4 v[92:95], v[152:153], off offset:1920
	ds_read_b128 v[226:229], v195 offset:36960
	ds_read_b128 v[206:209], v195 offset:41536
	v_mfma_f32_32x32x16_bf16 v[20:35], v[214:217], v[222:225], v[20:35]
	global_load_dwordx4 v[104:107], v[146:147], off offset:1920
	ds_read_b128 v[222:225], v195 offset:36928
	ds_read_b128 v[214:217], v194 offset:96
	s_waitcnt lgkmcnt(1)
	v_mfma_f32_32x32x16_bf16 v[52:67], v[210:213], v[222:225], v[52:67]
	s_waitcnt vmcnt(23)
	ds_write_b128 v167, v[96:99] offset:18432
	v_mfma_f32_32x32x16_bf16 v[36:51], v[210:213], v[206:209], v[36:51]
	s_waitcnt vmcnt(22)
	ds_write_b128 v167, v[100:103] offset:55296
	v_mfma_f32_32x32x16_bf16 v[20:35], v[202:205], v[222:225], v[20:35]
	s_waitcnt vmcnt(21)
	ds_write_b128 v190, v[108:111] offset:18432
	v_mfma_f32_32x32x16_bf16 v[4:19], v[202:205], v[206:209], v[4:19]
	s_waitcnt vmcnt(20)
	ds_write_b128 v190, v[112:115] offset:55296
	s_waitcnt lgkmcnt(4)
	v_mfma_f32_32x32x16_bf16 v[52:67], v[214:217], v[226:229], v[52:67]
	s_waitcnt vmcnt(19)
	ds_write_b128 v191, v[116:119] offset:18432
	v_mfma_f32_32x32x16_bf16 v[36:51], v[214:217], v[230:233], v[36:51]
	s_setprio 0
	s_waitcnt vmcnt(18)
	ds_write_b128 v191, v[120:123] offset:55296
	v_mfma_f32_32x32x16_bf16 v[20:35], v[218:221], v[226:229], v[20:35]
	s_waitcnt vmcnt(17)
	ds_write_b128 v192, v[124:127] offset:18432
	v_mfma_f32_32x32x16_bf16 v[4:19], v[218:221], v[230:233], v[4:19]
	s_waitcnt vmcnt(16)
	ds_write_b128 v192, v[128:131] offset:55296
	s_waitcnt lgkmcnt(0)
	s_barrier
; template <class Epi, class ColV>
; DI void gemm_tile(const bf16_t* __restrict__ A, int lda, const bf16_t* __restrict__ Bt, int ldb, int K, int m0, int n0, unsigned char* smem, Epi epi, ColV colv, const bf16_t* __restrict__ HYT = nullptr) {
;     ...
;     auto step = [&](int kt, u32x4 (&ldset)[8], const u32x4 (&stset)[8]) {
;         const int buf = kt & 1;
;         if (kt + 2 < nk) gload(ldset, kt + 2);
;         const bf16_t* Ab = As + (buf * 128 + 64 * wr + li) * LS + 8 * lh;
;         const bf16_t* Bb = Bs + (buf * 128 + 64 * wc + li) * LS + 8 * lh;
;         bf16x8 fa[2][2], fb[2][2], ga[2][2], gb[2][2];
; #pragma unroll
;         for (int k2 = 0; k2 < 2; ++k2) { fa[k2][0] = ld8(Ab + 16 * k2); fa[k2][1] = ld8(Ab + 32 * LS + 16 * k2); fb[k2][0] = ld8(Bb + 16 * k2); fb[k2][1] = ld8(Bb + 32 * LS + 16 * k2); }
;         __builtin_amdgcn_sched_barrier(0);
; #pragma unroll
;         for (int k2 = 0; k2 < 2; ++k2) {
;             acc[0][0] = MFMA(fa[k2][0], fb[k2][0], acc[0][0]); acc[0][1] = MFMA(fa[k2][0], fb[k2][1], acc[0][1]);
;             acc[1][0] = MFMA(fa[k2][1], fb[k2][0], acc[1][0]); acc[1][1] = MFMA(fa[k2][1], fb[k2][1], acc[1][1]);
;         }
; #pragma unroll
;         for (int k2 = 0; k2 < 2; ++k2) { const int ks = 2 + k2; ga[k2][0] = ld8(Ab + 16 * ks); ga[k2][1] = ld8(Ab + 32 * LS + 16 * ks); gb[k2][0] = ld8(Bb + 16 * ks); gb[k2][1] = ld8(Bb + 32 * LS + 16 * ks); }
; #pragma unroll
;         for (int k2 = 0; k2 < 2; ++k2) {
;             acc[0][0] = MFMA(ga[k2][0], gb[k2][0], acc[0][0]); acc[0][1] = MFMA(ga[k2][0], gb[k2][1], acc[0][1]);
;             acc[1][0] = MFMA(ga[k2][1], gb[k2][0], acc[1][0]); acc[1][1] = MFMA(ga[k2][1], gb[k2][1], acc[1][1]);
;         }
;         if (kt + 1 < nk) sstore(stset, buf ^ 1, kt + 1);
; #pragma unroll
;         for (int i = 0; i < 8; ++i) { __builtin_amdgcn_sched_group_barrier(0x008, 1, 0); __builtin_amdgcn_sched_group_barrier(0x100, 1, 0); }
; #pragma unroll
;         for (int i = 0; i < 8; ++i) { __builtin_amdgcn_sched_group_barrier(0x008, 1, 0); __builtin_amdgcn_sched_group_barrier(0x200, 1, 0); }
;         __builtin_amdgcn_sched_barrier(0);
;         __syncthreads();
;     };
;     ...
;         XCD_TILE_LOOP(NT / 128, INP / 128, tm, tn) gemm_tile((const bf16_t*)(p.ws + WS_H), 1024, (const bf16_t*)(p.ws + wbase(layer) + W_IN), 1024, 1024, tm * 128, tn * 128, smem, epi, nocol);
	s_setprio 1
	ds_read_b128 v[202:205], v196
	ds_read_b128 v[218:221], v197 offset:36864
	ds_read_b128 v[226:229], v197 offset:41472
	ds_read_b128 v[210:213], v196 offset:4608
	ds_read_b128 v[206:209], v196 offset:32
	ds_read_b128 v[230:233], v197 offset:41504
	ds_read_b128 v[214:217], v196 offset:4640
	ds_read_b128 v[222:225], v197 offset:36896
	s_waitcnt lgkmcnt(6)
	v_mfma_f32_32x32x16_bf16 v[52:67], v[202:205], v[218:221], v[52:67]
	s_waitcnt lgkmcnt(5)
	v_mfma_f32_32x32x16_bf16 v[36:51], v[202:205], v[226:229], v[36:51]
	s_waitcnt lgkmcnt(4)
	v_mfma_f32_32x32x16_bf16 v[4:19], v[210:213], v[226:229], v[4:19]
	s_waitcnt lgkmcnt(2)
	v_mfma_f32_32x32x16_bf16 v[36:51], v[206:209], v[230:233], v[36:51]
	s_waitcnt lgkmcnt(1)
	v_mfma_f32_32x32x16_bf16 v[4:19], v[214:217], v[230:233], v[4:19]
	ds_read_b128 v[230:233], v197 offset:41568
	ds_read_b128 v[202:205], v196 offset:4672
	v_mfma_f32_32x32x16_bf16 v[20:35], v[210:213], v[218:221], v[20:35]
	ds_read_b128 v[218:221], v196 offset:4704
	ds_read_b128 v[210:213], v196 offset:64
	s_waitcnt lgkmcnt(4)
	v_mfma_f32_32x32x16_bf16 v[52:67], v[206:209], v[222:225], v[52:67]
	ds_read_b128 v[226:229], v197 offset:36960
	ds_read_b128 v[206:209], v197 offset:41536
	v_mfma_f32_32x32x16_bf16 v[20:35], v[214:217], v[222:225], v[20:35]
	ds_read_b128 v[222:225], v197 offset:36928
	ds_read_b128 v[214:217], v196 offset:96
	s_waitcnt lgkmcnt(1)
	v_mfma_f32_32x32x16_bf16 v[52:67], v[210:213], v[222:225], v[52:67]
	s_waitcnt vmcnt(15)
	ds_write_b128 v167, v[132:135]
	v_mfma_f32_32x32x16_bf16 v[36:51], v[210:213], v[206:209], v[36:51]
	s_waitcnt vmcnt(14)
	ds_write_b128 v167, v[136:139] offset:36864
	v_mfma_f32_32x32x16_bf16 v[20:35], v[202:205], v[222:225], v[20:35]
	s_waitcnt vmcnt(13)
	ds_write_b128 v190, v[140:143]
	v_mfma_f32_32x32x16_bf16 v[4:19], v[202:205], v[206:209], v[4:19]
	s_waitcnt vmcnt(12)
	ds_write_b128 v190, v[198:201] offset:36864
	s_waitcnt lgkmcnt(4)
	v_mfma_f32_32x32x16_bf16 v[52:67], v[214:217], v[226:229], v[52:67]
	s_waitcnt vmcnt(11)
	ds_write_b128 v191, v[174:177]
	v_mfma_f32_32x32x16_bf16 v[36:51], v[214:217], v[230:233], v[36:51]
	s_setprio 0
	s_waitcnt vmcnt(10)
	ds_write_b128 v191, v[178:181] offset:36864
	v_mfma_f32_32x32x16_bf16 v[20:35], v[218:221], v[226:229], v[20:35]
	s_waitcnt vmcnt(9)
	ds_write_b128 v192, v[242:245]
	v_mfma_f32_32x32x16_bf16 v[4:19], v[218:221], v[230:233], v[4:19]
	s_waitcnt vmcnt(8)
	ds_write_b128 v192, v[246:249] offset:36864
	s_waitcnt lgkmcnt(0)
	s_barrier
; #define MFMA(a, b, c) __builtin_amdgcn_mfma_f32_32x32x16_bf16((a), (b), (c), 0, 0, 0)
; template <class Epi, class ColV>
; DI void gemm_tile(const bf16_t* __restrict__ A, int lda, const bf16_t* __restrict__ Bt, int ldb, int K, int m0, int n0, unsigned char* smem, Epi epi, ColV colv, const bf16_t* __restrict__ HYT = nullptr) {
;     ...
;     auto step = [&](int kt, u32x4 (&ldset)[8], const u32x4 (&stset)[8]) {
;         const int buf = kt & 1;
;         if (kt + 2 < nk) gload(ldset, kt + 2);
;         const bf16_t* Ab = As + (buf * 128 + 64 * wr + li) * LS + 8 * lh;
;         const bf16_t* Bb = Bs + (buf * 128 + 64 * wc + li) * LS + 8 * lh;
;         bf16x8 fa[2][2], fb[2][2], ga[2][2], gb[2][2];
; #pragma unroll
;         for (int k2 = 0; k2 < 2; ++k2) { fa[k2][0] = ld8(Ab + 16 * k2); fa[k2][1] = ld8(Ab + 32 * LS + 16 * k2); fb[k2][0] = ld8(Bb + 16 * k2); fb[k2][1] = ld8(Bb + 32 * LS + 16 * k2); }
;         __builtin_amdgcn_sched_barrier(0);
; #pragma unroll
;         for (int k2 = 0; k2 < 2; ++k2) {
;             acc[0][0] = MFMA(fa[k2][0], fb[k2][0], acc[0][0]); acc[0][1] = MFMA(fa[k2][0], fb[k2][1], acc[0][1]);
;             acc[1][0] = MFMA(fa[k2][1], fb[k2][0], acc[1][0]); acc[1][1] = MFMA(fa[k2][1], fb[k2][1], acc[1][1]);
;         }
; #pragma unroll
;         for (int k2 = 0; k2 < 2; ++k2) { const int ks = 2 + k2; ga[k2][0] = ld8(Ab + 16 * ks); ga[k2][1] = ld8(Ab + 32 * LS + 16 * ks); gb[k2][0] = ld8(Bb + 16 * ks); gb[k2][1] = ld8(Bb + 32 * LS + 16 * ks); }
; #pragma unroll
;         for (int k2 = 0; k2 < 2; ++k2) {
;             acc[0][0] = MFMA(ga[k2][0], gb[k2][0], acc[0][0]); acc[0][1] = MFMA(ga[k2][0], gb[k2][1], acc[0][1]);
;             acc[1][0] = MFMA(ga[k2][1], gb[k2][0], acc[1][0]); acc[1][1] = MFMA(ga[k2][1], gb[k2][1], acc[1][1]);
;         }
;         if (kt + 1 < nk) sstore(stset, buf ^ 1, kt + 1);
; #pragma unroll
;         for (int i = 0; i < 8; ++i) { __builtin_amdgcn_sched_group_barrier(0x008, 1, 0); __builtin_amdgcn_sched_group_barrier(0x100, 1, 0); }
; #pragma unroll
;         for (int i = 0; i < 8; ++i) { __builtin_amdgcn_sched_group_barrier(0x008, 1, 0); __builtin_amdgcn_sched_group_barrier(0x200, 1, 0); }
;         __builtin_amdgcn_sched_barrier(0);
;         __syncthreads();
	s_setprio 1
	ds_read_b128 v[202:205], v194
	ds_read_b128 v[218:221], v195 offset:36864
	ds_read_b128 v[226:229], v195 offset:41472
	ds_read_b128 v[210:213], v194 offset:4608
	ds_read_b128 v[206:209], v194 offset:32
	ds_read_b128 v[230:233], v195 offset:41504
	ds_read_b128 v[214:217], v194 offset:4640
	ds_read_b128 v[222:225], v195 offset:36896
	s_waitcnt lgkmcnt(6)
	v_mfma_f32_32x32x16_bf16 v[52:67], v[202:205], v[218:221], v[52:67]
	s_waitcnt lgkmcnt(5)
	v_mfma_f32_32x32x16_bf16 v[36:51], v[202:205], v[226:229], v[36:51]
	s_waitcnt lgkmcnt(4)
	v_mfma_f32_32x32x16_bf16 v[4:19], v[210:213], v[226:229], v[4:19]
	s_waitcnt lgkmcnt(2)
	v_mfma_f32_32x32x16_bf16 v[36:51], v[206:209], v[230:233], v[36:51]
	s_waitcnt lgkmcnt(1)
	v_mfma_f32_32x32x16_bf16 v[4:19], v[214:217], v[230:233], v[4:19]
	ds_read_b128 v[230:233], v195 offset:41568
	ds_read_b128 v[202:205], v194 offset:4672
	v_mfma_f32_32x32x16_bf16 v[20:35], v[210:213], v[218:221], v[20:35]
	ds_read_b128 v[218:221], v194 offset:4704
	ds_read_b128 v[210:213], v194 offset:64
	s_waitcnt lgkmcnt(4)
	v_mfma_f32_32x32x16_bf16 v[52:67], v[206:209], v[222:225], v[52:67]
	ds_read_b128 v[226:229], v195 offset:36960
	ds_read_b128 v[206:209], v195 offset:41536
	v_mfma_f32_32x32x16_bf16 v[20:35], v[214:217], v[222:225], v[20:35]
	ds_read_b128 v[222:225], v195 offset:36928
	ds_read_b128 v[214:217], v194 offset:96
	s_waitcnt lgkmcnt(1)
	v_mfma_f32_32x32x16_bf16 v[52:67], v[210:213], v[222:225], v[52:67]
	s_waitcnt vmcnt(7)
	ds_write_b128 v167, v[68:71] offset:18432
	v_mfma_f32_32x32x16_bf16 v[36:51], v[210:213], v[206:209], v[36:51]
	s_waitcnt vmcnt(6)
	ds_write_b128 v167, v[72:75] offset:55296
	v_mfma_f32_32x32x16_bf16 v[20:35], v[202:205], v[222:225], v[20:35]
	s_waitcnt vmcnt(5)
	ds_write_b128 v190, v[76:79] offset:18432
	v_mfma_f32_32x32x16_bf16 v[4:19], v[202:205], v[206:209], v[4:19]
	s_waitcnt vmcnt(4)
	ds_write_b128 v190, v[80:83] offset:55296
	s_waitcnt lgkmcnt(4)
	v_mfma_f32_32x32x16_bf16 v[52:67], v[214:217], v[226:229], v[52:67]
	s_waitcnt vmcnt(3)
	ds_write_b128 v191, v[84:87] offset:18432
	v_mfma_f32_32x32x16_bf16 v[36:51], v[214:217], v[230:233], v[36:51]
	s_setprio 0
	s_waitcnt vmcnt(2)
	ds_write_b128 v191, v[88:91] offset:55296
	v_mfma_f32_32x32x16_bf16 v[20:35], v[218:221], v[226:229], v[20:35]
	s_waitcnt vmcnt(1)
	ds_write_b128 v192, v[92:95] offset:18432
	v_mfma_f32_32x32x16_bf16 v[4:19], v[218:221], v[230:233], v[4:19]
	s_waitcnt vmcnt(0)
	ds_write_b128 v192, v[104:107] offset:55296
	s_waitcnt lgkmcnt(0)
	s_barrier
	s_setprio 1
	ds_read_b128 v[202:205], v196
	ds_read_b128 v[218:221], v197 offset:36864
	ds_read_b128 v[226:229], v197 offset:41472
	ds_read_b128 v[210:213], v196 offset:4608
	ds_read_b128 v[206:209], v196 offset:32
	ds_read_b128 v[230:233], v197 offset:41504
	ds_read_b128 v[214:217], v196 offset:4640
	ds_read_b128 v[222:225], v197 offset:36896
	s_waitcnt lgkmcnt(6)
	v_mfma_f32_32x32x16_bf16 v[52:67], v[202:205], v[218:221], v[52:67]
	s_waitcnt lgkmcnt(5)
	v_mfma_f32_32x32x16_bf16 v[36:51], v[202:205], v[226:229], v[36:51]
	s_waitcnt lgkmcnt(4)
	v_mfma_f32_32x32x16_bf16 v[4:19], v[210:213], v[226:229], v[4:19]
	s_waitcnt lgkmcnt(2)
	v_mfma_f32_32x32x16_bf16 v[36:51], v[206:209], v[230:233], v[36:51]
	s_waitcnt lgkmcnt(1)
	v_mfma_f32_32x32x16_bf16 v[4:19], v[214:217], v[230:233], v[4:19]
	ds_read_b128 v[230:233], v197 offset:41568
	ds_read_b128 v[202:205], v196 offset:4672
	v_mfma_f32_32x32x16_bf16 v[20:35], v[210:213], v[218:221], v[20:35]
	ds_read_b128 v[218:221], v196 offset:4704
	ds_read_b128 v[210:213], v196 offset:64
	s_waitcnt lgkmcnt(4)
	v_mfma_f32_32x32x16_bf16 v[52:67], v[206:209], v[222:225], v[52:67]
	ds_read_b128 v[226:229], v197 offset:36960
	ds_read_b128 v[206:209], v197 offset:41536
	v_mfma_f32_32x32x16_bf16 v[20:35], v[214:217], v[222:225], v[20:35]
	ds_read_b128 v[222:225], v197 offset:36928
	ds_read_b128 v[214:217], v196 offset:96
	s_waitcnt lgkmcnt(1)
	v_mfma_f32_32x32x16_bf16 v[52:67], v[210:213], v[222:225], v[52:67]
	v_mfma_f32_32x32x16_bf16 v[36:51], v[210:213], v[206:209], v[36:51]
	v_mfma_f32_32x32x16_bf16 v[20:35], v[202:205], v[222:225], v[20:35]
	v_mfma_f32_32x32x16_bf16 v[4:19], v[202:205], v[206:209], v[4:19]
	s_waitcnt lgkmcnt(0)
	v_mfma_f32_32x32x16_bf16 v[52:67], v[214:217], v[226:229], v[52:67]
	v_mfma_f32_32x32x16_bf16 v[36:51], v[214:217], v[230:233], v[36:51]
	s_setprio 0
	v_mfma_f32_32x32x16_bf16 v[20:35], v[218:221], v[226:229], v[20:35]
	v_mfma_f32_32x32x16_bf16 v[4:19], v[218:221], v[230:233], v[4:19]
	s_waitcnt lgkmcnt(0)
	s_barrier
	s_setprio 1
	s_nop 7
	s_nop 3
	s_branch .LBB0_1555
